# static s_setprio 1 for waves 4-7 around each GEMM K-loop (on top of flip removal)
# baseline (speedup 1.0000x reference)
.LBB0_137:
	s_ashr_i32 s49, s48, 31
	s_lshl_b64 s[22:23], s[48:49], 20
	s_add_u32 s52, s26, s22
	s_addc_u32 s53, s27, s23
	s_and_b64 s[0:1], s[0:1], exec
	s_cselect_b32 s22, s53, s7
	s_cselect_b32 s23, s52, s6
	s_add_u32 s0, s12, 0x80080
	s_addc_u32 s1, s13, 0
	s_add_u32 s38, s6, 0x100
	v_mov_b32_e32 v2, 0
	s_addc_u32 s39, s7, 0
	s_mov_b32 s49, -2
	v_mov_b32_e32 v3, v2
	v_mov_b32_e32 v4, v2
	v_mov_b32_e32 v5, v2
	v_mov_b32_e32 v6, v2
	v_mov_b32_e32 v7, v2
	v_mov_b32_e32 v8, v2
	v_mov_b32_e32 v9, v2
	v_mov_b32_e32 v14, v2
	v_mov_b32_e32 v15, v2
	v_mov_b32_e32 v16, v2
	v_mov_b32_e32 v17, v2
	v_mov_b32_e32 v22, v2
	v_mov_b32_e32 v23, v2
	v_mov_b32_e32 v24, v2
	v_mov_b32_e32 v25, v2
	v_mov_b32_e32 v30, v2
	v_mov_b32_e32 v31, v2
	v_mov_b32_e32 v32, v2
	v_mov_b32_e32 v33, v2
	v_mov_b32_e32 v38, v2
	v_mov_b32_e32 v39, v2
	v_mov_b32_e32 v40, v2
	v_mov_b32_e32 v41, v2
	v_mov_b32_e32 v46, v2
	v_mov_b32_e32 v47, v2
	v_mov_b32_e32 v48, v2
	v_mov_b32_e32 v49, v2
	v_mov_b32_e32 v54, v2
	v_mov_b32_e32 v55, v2
	v_mov_b32_e32 v56, v2
	v_mov_b32_e32 v57, v2
	v_mov_b32_e32 v10, v2
	v_mov_b32_e32 v11, v2
	v_mov_b32_e32 v12, v2
	v_mov_b32_e32 v13, v2
	v_mov_b32_e32 v18, v2
	v_mov_b32_e32 v19, v2
	v_mov_b32_e32 v20, v2
	v_mov_b32_e32 v21, v2
	v_mov_b32_e32 v26, v2
	v_mov_b32_e32 v27, v2
	v_mov_b32_e32 v28, v2
	v_mov_b32_e32 v29, v2
	v_mov_b32_e32 v34, v2
	v_mov_b32_e32 v35, v2
	v_mov_b32_e32 v36, v2
	v_mov_b32_e32 v37, v2
	v_mov_b32_e32 v42, v2
	v_mov_b32_e32 v43, v2
	v_mov_b32_e32 v44, v2
	v_mov_b32_e32 v45, v2
	v_mov_b32_e32 v50, v2
	v_mov_b32_e32 v51, v2
	v_mov_b32_e32 v52, v2
	v_mov_b32_e32 v53, v2
	v_mov_b32_e32 v58, v2
	v_mov_b32_e32 v59, v2
	v_mov_b32_e32 v60, v2
	v_mov_b32_e32 v61, v2
	v_mov_b32_e32 v62, v2
	v_mov_b32_e32 v63, v2
	v_mov_b32_e32 v64, v2
	v_mov_b32_e32 v65, v2
	v_mov_b32_e32 v66, v2
	v_mov_b32_e32 v67, v2
	v_mov_b32_e32 v68, v2
	v_mov_b32_e32 v69, v2
	v_mov_b32_e32 v70, v2
	v_mov_b32_e32 v71, v2
	v_mov_b32_e32 v72, v2
	v_mov_b32_e32 v73, v2
	v_mov_b32_e32 v78, v2
	v_mov_b32_e32 v79, v2
	v_mov_b32_e32 v80, v2
	v_mov_b32_e32 v81, v2
	v_mov_b32_e32 v86, v2
	v_mov_b32_e32 v87, v2
	v_mov_b32_e32 v88, v2
	v_mov_b32_e32 v89, v2
	v_mov_b32_e32 v94, v2
	v_mov_b32_e32 v95, v2
	v_mov_b32_e32 v96, v2
	v_mov_b32_e32 v97, v2
	v_mov_b32_e32 v102, v2
	v_mov_b32_e32 v103, v2
	v_mov_b32_e32 v104, v2
	v_mov_b32_e32 v105, v2
	v_mov_b32_e32 v110, v2
	v_mov_b32_e32 v111, v2
	v_mov_b32_e32 v112, v2
	v_mov_b32_e32 v113, v2
	v_mov_b32_e32 v118, v2
	v_mov_b32_e32 v119, v2
	v_mov_b32_e32 v120, v2
	v_mov_b32_e32 v121, v2
	v_mov_b32_e32 v74, v2
	v_mov_b32_e32 v75, v2
	v_mov_b32_e32 v76, v2
	v_mov_b32_e32 v77, v2
	v_mov_b32_e32 v82, v2
	v_mov_b32_e32 v83, v2
	v_mov_b32_e32 v84, v2
	v_mov_b32_e32 v85, v2
	v_mov_b32_e32 v90, v2
	v_mov_b32_e32 v91, v2
	v_mov_b32_e32 v92, v2
	v_mov_b32_e32 v93, v2
	v_mov_b32_e32 v98, v2
	v_mov_b32_e32 v99, v2
	v_mov_b32_e32 v100, v2
	v_mov_b32_e32 v101, v2
	v_mov_b32_e32 v106, v2
	v_mov_b32_e32 v107, v2
	v_mov_b32_e32 v108, v2
	v_mov_b32_e32 v109, v2
	v_mov_b32_e32 v114, v2
	v_mov_b32_e32 v115, v2
	v_mov_b32_e32 v116, v2
	v_mov_b32_e32 v117, v2
	v_mov_b32_e32 v122, v2
	v_mov_b32_e32 v123, v2
	v_mov_b32_e32 v124, v2
	v_mov_b32_e32 v125, v2
	v_mov_b32_e32 v126, v2
	v_mov_b32_e32 v127, v2
	v_mov_b32_e32 v128, v2
	v_mov_b32_e32 v129, v2
	v_add_u32_e32 v224, 0x10000, v149
	v_add_u32_e32 v225, 0x14000, v149
	v_add_u32_e32 v226, 0x18000, v149
	v_add_u32_e32 v227, 0x1c000, v149
	v_readfirstlane_b32 s32, v148
	s_nop 3
	s_cmp_ge_u32 s32, 0x100
	s_cbranch_scc0 .Lprio_skip_0
	s_setprio 1
.Lprio_skip_0:
.LBB0_138:
	s_add_u32 s6, s0, 0xfff80080
	s_addc_u32 s7, s1, -1
	s_add_i32 s76, 0, 0x10000
	ds_read_b128 v[130:133], v224
	ds_read_b128 v[134:137], v224 offset:1024
	ds_read_b128 v[138:141], v224 offset:2048
	ds_read_b128 v[142:145], v224 offset:3072
	s_cmp_eq_u32 s49, 28
	s_cselect_b32 s13, s51, s7
	s_cselect_b32 s12, s50, s6
	s_cselect_b32 s7, s22, s39
	s_cselect_b32 s6, s23, s38
	s_add_i32 m0, s31, 0xc000
	ds_read_b128 v[152:155], v174
	ds_read_b128 v[166:169], v174 offset:1024
	ds_read_b128 v[170:173], v174 offset:2048
	ds_read_b128 v[176:179], v174 offset:3072
	ds_read_b128 v[180:183], v174 offset:4096
	ds_read_b128 v[184:187], v174 offset:5120
	ds_read_b128 v[188:191], v174 offset:6144
	global_load_lds_dwordx4 v162, s[0:1]
	s_add_i32 m0, s31, 0xe000
	ds_read_b128 v[192:195], v174 offset:7168
	global_load_lds_dwordx4 v164, s[0:1]
	s_waitcnt lgkmcnt(8)
	s_barrier
	s_waitcnt lgkmcnt(7)
	v_mfma_f32_16x16x32_bf16 v[126:129], v[130:133], v[152:155], v[126:129]
	v_mfma_f32_16x16x32_bf16 v[122:125], v[138:141], v[152:155], v[122:125]
	s_waitcnt lgkmcnt(5)
	v_mfma_f32_16x16x32_bf16 v[114:117], v[130:133], v[170:173], v[114:117]
	v_mfma_f32_16x16x32_bf16 v[106:109], v[138:141], v[170:173], v[106:109]
	s_waitcnt lgkmcnt(3)
	v_mfma_f32_16x16x32_bf16 v[98:101], v[130:133], v[180:183], v[98:101]
	v_mfma_f32_16x16x32_bf16 v[90:93], v[138:141], v[180:183], v[90:93]
	s_waitcnt lgkmcnt(1)
	v_mfma_f32_16x16x32_bf16 v[82:85], v[130:133], v[188:191], v[82:85]
	v_mfma_f32_16x16x32_bf16 v[74:77], v[138:141], v[188:191], v[74:77]
	v_mfma_f32_16x16x32_bf16 v[126:129], v[134:137], v[166:169], v[126:129]
	v_mfma_f32_16x16x32_bf16 v[122:125], v[142:145], v[166:169], v[122:125]
	v_mfma_f32_16x16x32_bf16 v[114:117], v[134:137], v[176:179], v[114:117]
	v_mfma_f32_16x16x32_bf16 v[106:109], v[142:145], v[176:179], v[106:109]
	v_mfma_f32_16x16x32_bf16 v[98:101], v[134:137], v[184:187], v[98:101]
	v_mfma_f32_16x16x32_bf16 v[90:93], v[142:145], v[184:187], v[90:93]
	s_waitcnt lgkmcnt(0)
	v_mfma_f32_16x16x32_bf16 v[82:85], v[134:137], v[192:195], v[82:85]
	v_mfma_f32_16x16x32_bf16 v[74:77], v[142:145], v[192:195], v[74:77]
	s_barrier
	s_add_i32 s78, 0, 0x14000
	s_add_i32 s76, s76, s30
	s_mov_b32 m0, s76
	ds_read_b128 v[196:199], v225
	ds_read_b128 v[200:203], v225 offset:1024
	ds_read_b128 v[204:207], v225 offset:2048
	global_load_lds_dwordx4 v158, s[6:7]
	s_add_i32 m0, s76, 0x2000
	ds_read_b128 v[216:219], v225 offset:3072
	global_load_lds_dwordx4 v146, s[6:7]
	s_barrier
	s_waitcnt lgkmcnt(3)
	v_mfma_f32_16x16x32_bf16 v[118:121], v[196:199], v[152:155], v[118:121]
	s_waitcnt lgkmcnt(1)
	v_mfma_f32_16x16x32_bf16 v[110:113], v[204:207], v[152:155], v[110:113]
	v_mfma_f32_16x16x32_bf16 v[102:105], v[196:199], v[170:173], v[102:105]
	v_mfma_f32_16x16x32_bf16 v[94:97], v[204:207], v[170:173], v[94:97]
	v_mfma_f32_16x16x32_bf16 v[86:89], v[196:199], v[180:183], v[86:89]
	v_mfma_f32_16x16x32_bf16 v[78:81], v[204:207], v[180:183], v[78:81]
	v_mfma_f32_16x16x32_bf16 v[70:73], v[196:199], v[188:191], v[70:73]
	v_mfma_f32_16x16x32_bf16 v[66:69], v[204:207], v[188:191], v[66:69]
	v_mfma_f32_16x16x32_bf16 v[118:121], v[200:203], v[166:169], v[118:121]
	s_waitcnt lgkmcnt(0)
	v_mfma_f32_16x16x32_bf16 v[110:113], v[216:219], v[166:169], v[110:113]
	v_mfma_f32_16x16x32_bf16 v[102:105], v[200:203], v[176:179], v[102:105]
	v_mfma_f32_16x16x32_bf16 v[94:97], v[216:219], v[176:179], v[94:97]
	v_mfma_f32_16x16x32_bf16 v[86:89], v[200:203], v[184:187], v[86:89]
	v_mfma_f32_16x16x32_bf16 v[78:81], v[216:219], v[184:187], v[78:81]
	v_mfma_f32_16x16x32_bf16 v[70:73], v[200:203], v[192:195], v[70:73]
	v_mfma_f32_16x16x32_bf16 v[66:69], v[216:219], v[192:195], v[66:69]
	s_mov_b32 m0, s31
	s_add_u32 s98, s12, 0x80
	s_addc_u32 s99, s13, 0
	s_barrier
	ds_read_b128 v[152:155], v174 offset:16384
	ds_read_b128 v[166:169], v174 offset:17408
	ds_read_b128 v[170:173], v174 offset:18432
	ds_read_b128 v[176:179], v174 offset:19456
	ds_read_b128 v[180:183], v174 offset:20480
	ds_read_b128 v[184:187], v174 offset:21504
	ds_read_b128 v[188:191], v174 offset:22528
	global_load_lds_dwordx4 v160, s[12:13]
	s_mov_b32 m0, s40
	ds_read_b128 v[192:195], v174 offset:23552
	global_load_lds_dwordx4 v156, s[12:13]
	s_barrier
	s_waitcnt lgkmcnt(7)
	v_mfma_f32_16x16x32_bf16 v[62:65], v[130:133], v[152:155], v[62:65]
	v_mfma_f32_16x16x32_bf16 v[58:61], v[138:141], v[152:155], v[58:61]
	s_waitcnt lgkmcnt(5)
	v_mfma_f32_16x16x32_bf16 v[50:53], v[130:133], v[170:173], v[50:53]
	v_mfma_f32_16x16x32_bf16 v[42:45], v[138:141], v[170:173], v[42:45]
	s_waitcnt lgkmcnt(3)
	v_mfma_f32_16x16x32_bf16 v[34:37], v[130:133], v[180:183], v[34:37]
	v_mfma_f32_16x16x32_bf16 v[26:29], v[138:141], v[180:183], v[26:29]
	s_waitcnt lgkmcnt(1)
	v_mfma_f32_16x16x32_bf16 v[18:21], v[130:133], v[188:191], v[18:21]
	v_mfma_f32_16x16x32_bf16 v[10:13], v[138:141], v[188:191], v[10:13]
	v_mfma_f32_16x16x32_bf16 v[62:65], v[134:137], v[166:169], v[62:65]
	v_mfma_f32_16x16x32_bf16 v[58:61], v[142:145], v[166:169], v[58:61]
	v_mfma_f32_16x16x32_bf16 v[50:53], v[134:137], v[176:179], v[50:53]
	v_mfma_f32_16x16x32_bf16 v[42:45], v[142:145], v[176:179], v[42:45]
	v_mfma_f32_16x16x32_bf16 v[34:37], v[134:137], v[184:187], v[34:37]
	v_mfma_f32_16x16x32_bf16 v[26:29], v[142:145], v[184:187], v[26:29]
	s_waitcnt lgkmcnt(0)
	v_mfma_f32_16x16x32_bf16 v[18:21], v[134:137], v[192:195], v[18:21]
	v_mfma_f32_16x16x32_bf16 v[10:13], v[142:145], v[192:195], v[10:13]
	s_barrier
	s_add_i32 s78, s78, s30
	s_mov_b32 m0, s78
	s_add_u32 s76, s6, 0x80000
	s_addc_u32 s77, s7, 0
	global_load_lds_dwordx4 v158, s[76:77]
	s_add_i32 m0, s78, 0x2000
	s_nop 0
	global_load_lds_dwordx4 v146, s[76:77]
	s_waitcnt vmcnt(6)
	s_barrier
	v_mfma_f32_16x16x32_bf16 v[54:57], v[196:199], v[152:155], v[54:57]
	v_mfma_f32_16x16x32_bf16 v[46:49], v[204:207], v[152:155], v[46:49]
	v_mfma_f32_16x16x32_bf16 v[38:41], v[196:199], v[170:173], v[38:41]
	v_mfma_f32_16x16x32_bf16 v[30:33], v[204:207], v[170:173], v[30:33]
	v_mfma_f32_16x16x32_bf16 v[22:25], v[196:199], v[180:183], v[22:25]
	v_mfma_f32_16x16x32_bf16 v[14:17], v[204:207], v[180:183], v[14:17]
	v_mfma_f32_16x16x32_bf16 v[6:9], v[196:199], v[188:191], v[6:9]
	v_mfma_f32_16x16x32_bf16 v[2:5], v[204:207], v[188:191], v[2:5]
	v_mfma_f32_16x16x32_bf16 v[54:57], v[200:203], v[166:169], v[54:57]
	v_mfma_f32_16x16x32_bf16 v[46:49], v[216:219], v[166:169], v[46:49]
	v_mfma_f32_16x16x32_bf16 v[38:41], v[200:203], v[176:179], v[38:41]
	v_mfma_f32_16x16x32_bf16 v[30:33], v[216:219], v[176:179], v[30:33]
	v_mfma_f32_16x16x32_bf16 v[22:25], v[200:203], v[184:187], v[22:25]
	v_mfma_f32_16x16x32_bf16 v[14:17], v[216:219], v[184:187], v[14:17]
	v_mfma_f32_16x16x32_bf16 v[6:9], v[200:203], v[192:195], v[6:9]
	v_mfma_f32_16x16x32_bf16 v[2:5], v[216:219], v[192:195], v[2:5]
	s_add_i32 s76, 0, 0x18000
	s_barrier
	ds_read_b128 v[130:133], v226
	ds_read_b128 v[134:137], v226 offset:1024
	ds_read_b128 v[138:141], v226 offset:2048
	ds_read_b128 v[142:145], v226 offset:3072
	s_add_u32 s12, s12, 0x80000
	s_addc_u32 s13, s13, 0
	s_mov_b32 m0, s41
	ds_read_b128 v[152:155], v174 offset:32768
	ds_read_b128 v[166:169], v174 offset:33792
	ds_read_b128 v[170:173], v174 offset:34816
	ds_read_b128 v[176:179], v174 offset:35840
	ds_read_b128 v[180:183], v174 offset:36864
	ds_read_b128 v[184:187], v174 offset:37888
	ds_read_b128 v[188:191], v174 offset:38912
	global_load_lds_dwordx4 v160, s[12:13]
	s_mov_b32 m0, s60
	ds_read_b128 v[192:195], v174 offset:39936
	global_load_lds_dwordx4 v156, s[12:13]
	s_waitcnt lgkmcnt(8)
	s_barrier
	s_waitcnt lgkmcnt(7)
	v_mfma_f32_16x16x32_bf16 v[126:129], v[130:133], v[152:155], v[126:129]
	v_mfma_f32_16x16x32_bf16 v[122:125], v[138:141], v[152:155], v[122:125]
	s_waitcnt lgkmcnt(5)
	v_mfma_f32_16x16x32_bf16 v[114:117], v[130:133], v[170:173], v[114:117]
	v_mfma_f32_16x16x32_bf16 v[106:109], v[138:141], v[170:173], v[106:109]
	s_waitcnt lgkmcnt(3)
	v_mfma_f32_16x16x32_bf16 v[98:101], v[130:133], v[180:183], v[98:101]
	v_mfma_f32_16x16x32_bf16 v[90:93], v[138:141], v[180:183], v[90:93]
	s_waitcnt lgkmcnt(1)
	v_mfma_f32_16x16x32_bf16 v[82:85], v[130:133], v[188:191], v[82:85]
	v_mfma_f32_16x16x32_bf16 v[74:77], v[138:141], v[188:191], v[74:77]
	v_mfma_f32_16x16x32_bf16 v[126:129], v[134:137], v[166:169], v[126:129]
	v_mfma_f32_16x16x32_bf16 v[122:125], v[142:145], v[166:169], v[122:125]
	v_mfma_f32_16x16x32_bf16 v[114:117], v[134:137], v[176:179], v[114:117]
	v_mfma_f32_16x16x32_bf16 v[106:109], v[142:145], v[176:179], v[106:109]
	v_mfma_f32_16x16x32_bf16 v[98:101], v[134:137], v[184:187], v[98:101]
	v_mfma_f32_16x16x32_bf16 v[90:93], v[142:145], v[184:187], v[90:93]
	s_waitcnt lgkmcnt(0)
	v_mfma_f32_16x16x32_bf16 v[82:85], v[134:137], v[192:195], v[82:85]
	v_mfma_f32_16x16x32_bf16 v[74:77], v[142:145], v[192:195], v[74:77]
	s_barrier
	s_add_i32 s12, 0, 0x1c000
	s_add_i32 s13, s76, s30
	s_add_u32 s100, s6, 0x80
	s_addc_u32 s101, s7, 0
	s_mov_b32 m0, s13
	ds_read_b128 v[196:199], v227
	ds_read_b128 v[200:203], v227 offset:1024
	ds_read_b128 v[204:207], v227 offset:2048
	global_load_lds_dwordx4 v158, s[100:101]
	s_add_i32 m0, s13, 0x2000
	ds_read_b128 v[216:219], v227 offset:3072
	global_load_lds_dwordx4 v146, s[100:101]
	s_barrier
	s_waitcnt lgkmcnt(3)
	v_mfma_f32_16x16x32_bf16 v[118:121], v[196:199], v[152:155], v[118:121]
	s_waitcnt lgkmcnt(1)
	v_mfma_f32_16x16x32_bf16 v[110:113], v[204:207], v[152:155], v[110:113]
	v_mfma_f32_16x16x32_bf16 v[102:105], v[196:199], v[170:173], v[102:105]
	v_mfma_f32_16x16x32_bf16 v[94:97], v[204:207], v[170:173], v[94:97]
	v_mfma_f32_16x16x32_bf16 v[86:89], v[196:199], v[180:183], v[86:89]
	v_mfma_f32_16x16x32_bf16 v[78:81], v[204:207], v[180:183], v[78:81]
	v_mfma_f32_16x16x32_bf16 v[70:73], v[196:199], v[188:191], v[70:73]
	v_mfma_f32_16x16x32_bf16 v[66:69], v[204:207], v[188:191], v[66:69]
	v_mfma_f32_16x16x32_bf16 v[118:121], v[200:203], v[166:169], v[118:121]
	s_waitcnt lgkmcnt(0)
	v_mfma_f32_16x16x32_bf16 v[110:113], v[216:219], v[166:169], v[110:113]
	v_mfma_f32_16x16x32_bf16 v[102:105], v[200:203], v[176:179], v[102:105]
	v_mfma_f32_16x16x32_bf16 v[94:97], v[216:219], v[176:179], v[94:97]
	v_mfma_f32_16x16x32_bf16 v[86:89], v[200:203], v[184:187], v[86:89]
	v_mfma_f32_16x16x32_bf16 v[78:81], v[216:219], v[184:187], v[78:81]
	v_mfma_f32_16x16x32_bf16 v[70:73], v[200:203], v[192:195], v[70:73]
	v_mfma_f32_16x16x32_bf16 v[66:69], v[216:219], v[192:195], v[66:69]
	s_mov_b32 m0, s64
	s_barrier
	ds_read_b128 v[152:155], v174 offset:49152
	ds_read_b128 v[166:169], v174 offset:50176
	ds_read_b128 v[170:173], v174 offset:51200
	ds_read_b128 v[176:179], v174 offset:52224
	ds_read_b128 v[180:183], v174 offset:53248
	ds_read_b128 v[184:187], v174 offset:54272
	ds_read_b128 v[188:191], v174 offset:55296
	global_load_lds_dwordx4 v160, s[98:99]
	s_mov_b32 m0, s65
	ds_read_b128 v[192:195], v174 offset:56320
	global_load_lds_dwordx4 v156, s[98:99]
	s_barrier
	s_waitcnt lgkmcnt(7)
	v_mfma_f32_16x16x32_bf16 v[62:65], v[130:133], v[152:155], v[62:65]
	v_mfma_f32_16x16x32_bf16 v[58:61], v[138:141], v[152:155], v[58:61]
	s_waitcnt lgkmcnt(5)
	v_mfma_f32_16x16x32_bf16 v[50:53], v[130:133], v[170:173], v[50:53]
	v_mfma_f32_16x16x32_bf16 v[42:45], v[138:141], v[170:173], v[42:45]
	s_waitcnt lgkmcnt(3)
	v_mfma_f32_16x16x32_bf16 v[34:37], v[130:133], v[180:183], v[34:37]
	v_mfma_f32_16x16x32_bf16 v[26:29], v[138:141], v[180:183], v[26:29]
	s_waitcnt lgkmcnt(1)
	v_mfma_f32_16x16x32_bf16 v[18:21], v[130:133], v[188:191], v[18:21]
	v_mfma_f32_16x16x32_bf16 v[10:13], v[138:141], v[188:191], v[10:13]
	v_mfma_f32_16x16x32_bf16 v[62:65], v[134:137], v[166:169], v[62:65]
	v_mfma_f32_16x16x32_bf16 v[58:61], v[142:145], v[166:169], v[58:61]
	v_mfma_f32_16x16x32_bf16 v[50:53], v[134:137], v[176:179], v[50:53]
	v_mfma_f32_16x16x32_bf16 v[42:45], v[142:145], v[176:179], v[42:45]
	v_mfma_f32_16x16x32_bf16 v[34:37], v[134:137], v[184:187], v[34:37]
	v_mfma_f32_16x16x32_bf16 v[26:29], v[142:145], v[184:187], v[26:29]
	s_waitcnt lgkmcnt(0)
	v_mfma_f32_16x16x32_bf16 v[18:21], v[134:137], v[192:195], v[18:21]
	v_mfma_f32_16x16x32_bf16 v[10:13], v[142:145], v[192:195], v[10:13]
	s_barrier
	s_add_i32 s12, s12, s30
	s_mov_b32 m0, s12
	s_add_u32 s6, s6, 0x80080
	s_addc_u32 s7, s7, 0
	global_load_lds_dwordx4 v158, s[6:7]
	s_add_i32 m0, s12, 0x2000
	s_nop 0
	global_load_lds_dwordx4 v146, s[6:7]
	s_waitcnt vmcnt(6)
	s_barrier
	v_mfma_f32_16x16x32_bf16 v[54:57], v[196:199], v[152:155], v[54:57]
	v_mfma_f32_16x16x32_bf16 v[46:49], v[204:207], v[152:155], v[46:49]
	v_mfma_f32_16x16x32_bf16 v[38:41], v[196:199], v[170:173], v[38:41]
	v_mfma_f32_16x16x32_bf16 v[30:33], v[204:207], v[170:173], v[30:33]
	v_mfma_f32_16x16x32_bf16 v[22:25], v[196:199], v[180:183], v[22:25]
	v_mfma_f32_16x16x32_bf16 v[14:17], v[204:207], v[180:183], v[14:17]
	v_mfma_f32_16x16x32_bf16 v[6:9], v[196:199], v[188:191], v[6:9]
	v_mfma_f32_16x16x32_bf16 v[2:5], v[204:207], v[188:191], v[2:5]
	v_mfma_f32_16x16x32_bf16 v[54:57], v[200:203], v[166:169], v[54:57]
	v_mfma_f32_16x16x32_bf16 v[46:49], v[216:219], v[166:169], v[46:49]
	v_mfma_f32_16x16x32_bf16 v[38:41], v[200:203], v[176:179], v[38:41]
	v_mfma_f32_16x16x32_bf16 v[30:33], v[216:219], v[176:179], v[30:33]
	v_mfma_f32_16x16x32_bf16 v[22:25], v[200:203], v[184:187], v[22:25]
	v_mfma_f32_16x16x32_bf16 v[14:17], v[216:219], v[184:187], v[14:17]
	v_mfma_f32_16x16x32_bf16 v[6:9], v[200:203], v[192:195], v[6:9]
	v_mfma_f32_16x16x32_bf16 v[2:5], v[216:219], v[192:195], v[2:5]
	s_add_i32 s49, s49, 2
	s_add_u32 s0, s0, 0x100
	s_addc_u32 s1, s1, 0
	s_add_u32 s38, s38, 0x100
	s_addc_u32 s39, s39, 0
	s_cmp_gt_u32 s49, 29
	s_barrier
	s_cbranch_scc0 .LBB0_138
	s_setprio 0
	v_mov_b32_e32 v0, v148
	s_cmp_gt_i32 s69, 15
	v_and_b32_e32 v176, 15, v0
	v_bfe_u32 v175, v0, 4, 2
	s_mov_b64 s[0:1], -1
	s_cbranch_scc0 .LBB0_157
	s_cmp_gt_u32 s69, 23
	s_cbranch_scc0 .LBB0_154
	s_cmp_gt_u32 s69, 31
	s_cbranch_scc0 .LBB0_151
	s_cmp_gt_u32 s69, 39
	s_cbranch_scc0 .LBB0_148
	v_mul_f32_e32 v0, 0xbfb8aa3b, v126
	v_exp_f32_e32 v131, v0
	s_lshr_b32 s0, s75, 3
	s_mulk_i32 s0, 0x880
	s_lshl_b32 s1, s75, 8
	v_add_f32_e32 v131, 1.0, v131
	v_rcp_f32_e32 v132, v131
	v_mul_f32_e32 v131, 0xbfb8aa3b, v122
	v_mul_f32_e32 v133, 0xbfb8aa3b, v127
	v_mul_f32_e32 v134, 0xbfb8aa3b, v123
	v_mul_f32_e32 v135, 0xbfb8aa3b, v128
	v_mul_f32_e32 v136, 0xbfb8aa3b, v124
	v_mul_f32_e32 v137, 0xbfb8aa3b, v129
	v_mul_f32_e32 v138, 0xbfb8aa3b, v125
	v_mul_f32_e32 v139, 0xbfb8aa3b, v118
	v_mul_f32_e32 v140, 0xbfb8aa3b, v110
	v_mul_f32_e32 v141, 0xbfb8aa3b, v119
	v_mul_f32_e32 v142, 0xbfb8aa3b, v111
	v_mul_f32_e32 v143, 0xbfb8aa3b, v120
	v_mul_f32_e32 v152, 0xbfb8aa3b, v112
	v_mul_f32_e32 v153, 0xbfb8aa3b, v121
	v_mul_f32_e32 v154, 0xbfb8aa3b, v113
	v_mul_f32_e32 v155, 0xbfb8aa3b, v114
	v_mul_f32_e32 v177, 0xbfb8aa3b, v106
	v_mul_f32_e32 v178, 0xbfb8aa3b, v115
	v_mul_f32_e32 v179, 0xbfb8aa3b, v107
	v_mul_f32_e32 v180, 0xbfb8aa3b, v116
	v_mul_f32_e32 v181, 0xbfb8aa3b, v108
	v_mul_f32_e32 v182, 0xbfb8aa3b, v117
	v_mul_f32_e32 v183, 0xbfb8aa3b, v109
	v_mul_f32_e32 v184, 0xbfb8aa3b, v102
	v_mul_f32_e32 v185, 0xbfb8aa3b, v94
	v_mul_f32_e32 v186, 0xbfb8aa3b, v103
	v_mul_f32_e32 v187, 0xbfb8aa3b, v95
	v_mul_f32_e32 v188, 0xbfb8aa3b, v104
	v_mul_f32_e32 v189, 0xbfb8aa3b, v96
	v_mul_f32_e32 v190, 0xbfb8aa3b, v105
	v_mul_f32_e32 v191, 0xbfb8aa3b, v97
	v_mul_f32_e32 v192, 0xbfb8aa3b, v98
	v_mul_f32_e32 v193, 0xbfb8aa3b, v90
	v_mul_f32_e32 v194, 0xbfb8aa3b, v99
	v_mul_f32_e32 v195, 0xbfb8aa3b, v91
	v_mul_f32_e32 v196, 0xbfb8aa3b, v100
	v_mul_f32_e32 v197, 0xbfb8aa3b, v92
	v_mul_f32_e32 v198, 0xbfb8aa3b, v101
	v_mul_f32_e32 v199, 0xbfb8aa3b, v93
	v_mul_f32_e32 v200, 0xbfb8aa3b, v86
	v_mul_f32_e32 v201, 0xbfb8aa3b, v78
	v_mul_f32_e32 v202, 0xbfb8aa3b, v87
	v_mul_f32_e32 v203, 0xbfb8aa3b, v79
	v_mul_f32_e32 v204, 0xbfb8aa3b, v88
	v_mul_f32_e32 v205, 0xbfb8aa3b, v80
	v_mul_f32_e32 v206, 0xbfb8aa3b, v89
	v_mul_f32_e32 v207, 0xbfb8aa3b, v81
	v_mul_f32_e32 v208, 0xbfb8aa3b, v82
	v_mul_f32_e32 v209, 0xbfb8aa3b, v74
	v_mul_f32_e32 v215, 0xbfb8aa3b, v83
	v_mul_f32_e32 v216, 0xbfb8aa3b, v75
	v_mul_f32_e32 v217, 0xbfb8aa3b, v84
	v_mul_f32_e32 v218, 0xbfb8aa3b, v76
	v_mul_f32_e32 v219, 0xbfb8aa3b, v85
	v_mul_f32_e32 v220, 0xbfb8aa3b, v77
	v_mul_f32_e32 v221, 0xbfb8aa3b, v70
	v_mul_f32_e32 v222, 0xbfb8aa3b, v66
	v_mul_f32_e32 v223, 0xbfb8aa3b, v71
	v_mul_f32_e32 v224, 0xbfb8aa3b, v67
	v_mul_f32_e32 v225, 0xbfb8aa3b, v72
	v_mul_f32_e32 v226, 0xbfb8aa3b, v68
	v_mul_f32_e32 v227, 0xbfb8aa3b, v73
	v_mul_f32_e32 v228, 0xbfb8aa3b, v69
	v_mul_f32_e32 v229, 0xbfb8aa3b, v62
	v_mul_f32_e32 v230, 0xbfb8aa3b, v58
	v_mul_f32_e32 v231, 0xbfb8aa3b, v63
	v_mul_f32_e32 v232, 0xbfb8aa3b, v59
	v_mul_f32_e32 v233, 0xbfb8aa3b, v64
	v_mul_f32_e32 v234, 0xbfb8aa3b, v60
	v_mul_f32_e32 v235, 0xbfb8aa3b, v65
	v_mul_f32_e32 v236, 0xbfb8aa3b, v61
	v_mul_f32_e32 v237, 0xbfb8aa3b, v54
	v_mul_f32_e32 v238, 0xbfb8aa3b, v46
	v_mul_f32_e32 v239, 0xbfb8aa3b, v55
	s_and_b32 s1, s1, 0x700
	s_add_i32 s0, s0, s66
	v_exp_f32_e32 v173, v131
	v_exp_f32_e32 v133, v133
	v_exp_f32_e32 v172, v134
	v_exp_f32_e32 v171, v135
	v_exp_f32_e32 v170, v136
	v_exp_f32_e32 v169, v137
	v_exp_f32_e32 v131, v138
	v_exp_f32_e32 v168, v139
	v_exp_f32_e32 v167, v140
	v_exp_f32_e32 v166, v141
	v_exp_f32_e32 v145, v142
	v_exp_f32_e32 v144, v143
	v_exp_f32_e32 v143, v152
	v_exp_f32_e32 v142, v153
	v_exp_f32_e32 v141, v154
	v_exp_f32_e32 v140, v155
	v_exp_f32_e32 v139, v177
	v_exp_f32_e32 v138, v178
	v_exp_f32_e32 v213, v179
	v_exp_f32_e32 v155, v180
	v_exp_f32_e32 v154, v181
	v_exp_f32_e32 v153, v182
	v_exp_f32_e32 v152, v183
	v_exp_f32_e32 v212, v184
	v_exp_f32_e32 v211, v185
	v_exp_f32_e32 v252, v186
	v_exp_f32_e32 v251, v187
	v_exp_f32_e32 v250, v188
	v_exp_f32_e32 v249, v189
	v_exp_f32_e32 v248, v190
	v_exp_f32_e32 v247, v191
	v_exp_f32_e32 v246, v192
	v_exp_f32_e32 v245, v193
	v_exp_f32_e32 v244, v194
	v_exp_f32_e32 v243, v195
	v_exp_f32_e32 v242, v196
	v_exp_f32_e32 v241, v197
	v_exp_f32_e32 v184, v198
	v_exp_f32_e32 v177, v199
	v_exp_f32_e32 v198, v200
	v_exp_f32_e32 v199, v201
	v_exp_f32_e32 v197, v202
	v_exp_f32_e32 v196, v203
	v_exp_f32_e32 v195, v204
	v_exp_f32_e32 v194, v205
	v_exp_f32_e32 v193, v206
	v_exp_f32_e32 v192, v207
	v_exp_f32_e32 v191, v208
	v_exp_f32_e32 v190, v209
	v_exp_f32_e32 v189, v215
	v_exp_f32_e32 v188, v216
	v_exp_f32_e32 v187, v217
	v_exp_f32_e32 v186, v218
	v_exp_f32_e32 v185, v219
	v_exp_f32_e32 v201, v220
	v_exp_f32_e32 v200, v221
	v_exp_f32_e32 v221, v222
	v_exp_f32_e32 v220, v223
	v_exp_f32_e32 v219, v224
	v_exp_f32_e32 v218, v225
	v_exp_f32_e32 v217, v226
	v_exp_f32_e32 v216, v227
	v_exp_f32_e32 v215, v228
	v_exp_f32_e32 v209, v229
	v_exp_f32_e32 v208, v230
	v_exp_f32_e32 v207, v231
	v_exp_f32_e32 v206, v232
	v_exp_f32_e32 v205, v233
	v_exp_f32_e32 v204, v234
	v_exp_f32_e32 v203, v235
	v_exp_f32_e32 v202, v236
	v_exp_f32_e32 v223, v237
	v_exp_f32_e32 v222, v238
	v_exp_f32_e32 v238, v239
	s_add_i32 s0, s0, s1
	s_lshl_b32 s1, s69, 8
	v_lshl_or_b32 v130, v175, 3, s1
	s_cmp_gt_u32 s69, 47
	v_or_b32_e32 v240, s0, v176
	v_or_b32_e32 v130, s61, v130
	s_mov_b64 s[0:1], -1
	v_mul_f32_e32 v237, 0xbfb8aa3b, v47
	v_mul_f32_e32 v236, 0xbfb8aa3b, v56
	v_mul_f32_e32 v235, 0xbfb8aa3b, v48
	v_mul_f32_e32 v234, 0xbfb8aa3b, v57
	v_mul_f32_e32 v233, 0xbfb8aa3b, v49
	v_mul_f32_e32 v232, 0xbfb8aa3b, v50
	v_mul_f32_e32 v231, 0xbfb8aa3b, v42
	v_mul_f32_e32 v230, 0xbfb8aa3b, v51
	v_mul_f32_e32 v229, 0xbfb8aa3b, v43
	v_mul_f32_e32 v228, 0xbfb8aa3b, v18
	s_cbranch_scc0 .LBB0_145
	v_add_f32_e32 v178, 1.0, v171
	v_rcp_f32_e32 v179, v178
	v_add_f32_e32 v178, 1.0, v170
	v_add_f32_e32 v134, 1.0, v173
	v_add_f32_e32 v135, 1.0, v133
	v_add_f32_e32 v137, 1.0, v172
	v_rcp_f32_e32 v181, v178
	v_add_f32_e32 v178, 1.0, v169
	v_rcp_f32_e32 v134, v134
	v_rcp_f32_e32 v135, v135
	v_rcp_f32_e32 v137, v137
	v_rcp_f32_e32 v180, v178
	v_add_f32_e32 v178, 1.0, v131
	v_rcp_f32_e32 v182, v178
	v_mov_b32_e32 v0, v240
	v_mov_b32_e32 v136, v130
	v_cvt_pk_bf16_f32 v178, v132, v135
	v_cvt_pk_bf16_f32 v179, v179, v180
	v_cvt_pk_bf16_f32 v180, v134, v137
	v_mov_b64_e32 v[134:135], s[8:9]
	v_ashrrev_i32_e32 v137, 31, v136
	v_cvt_pk_bf16_f32 v181, v181, v182
	v_mad_i64_i32 v[182:183], s[0:1], v0, s47, v[134:135]
	v_lshlrev_b64 v[136:137], 1, v[136:137]
	v_lshl_add_u64 v[182:183], v[182:183], 0, v[136:137]
	global_store_dwordx4 v[182:183], v[178:181], off
	s_nop 1
	v_add_f32_e32 v179, 1.0, v167
	v_add_f32_e32 v178, 1.0, v168
	v_rcp_f32_e32 v180, v179
	v_add_f32_e32 v179, 1.0, v166
	v_add_f32_e32 v181, 1.0, v145
	v_add_f32_e32 v239, 1.0, v144
	v_add_f32_e32 v224, 1.0, v143
	v_add_f32_e32 v225, 1.0, v142
	v_add_f32_e32 v226, 1.0, v141
	v_rcp_f32_e32 v178, v178
	v_rcp_f32_e32 v179, v179
	v_rcp_f32_e32 v181, v181
	v_rcp_f32_e32 v239, v239
	v_rcp_f32_e32 v224, v224
	v_rcp_f32_e32 v225, v225
	v_rcp_f32_e32 v226, v226
	v_cvt_pk_bf16_f32 v178, v178, v179
	v_cvt_pk_bf16_f32 v180, v180, v181
	v_cvt_pk_bf16_f32 v179, v239, v225
	v_cvt_pk_bf16_f32 v181, v224, v226
	global_store_dwordx4 v[182:183], v[178:181], off offset:256
	s_nop 1
	v_add_f32_e32 v179, 1.0, v139
	v_add_f32_e32 v178, 1.0, v140
	v_rcp_f32_e32 v180, v179
	v_add_f32_e32 v179, 1.0, v138
	v_add_f32_e32 v183, 1.0, v155
	v_add_f32_e32 v225, 1.0, v153
	v_rcp_f32_e32 v178, v178
	v_rcp_f32_e32 v179, v179
	v_add_f32_e32 v181, 1.0, v213
	v_rcp_f32_e32 v183, v183
	v_add_f32_e32 v224, 1.0, v154
	v_rcp_f32_e32 v225, v225
	v_add_f32_e32 v226, 1.0, v152
	v_rcp_f32_e32 v181, v181
	v_rcp_f32_e32 v224, v224
	v_rcp_f32_e32 v226, v226
	v_add_u32_e32 v182, 16, v0
	v_cvt_pk_bf16_f32 v178, v178, v179
	v_cvt_pk_bf16_f32 v179, v183, v225
	v_mad_i64_i32 v[182:183], s[0:1], v182, s47, v[134:135]
	v_cvt_pk_bf16_f32 v180, v180, v181
	v_cvt_pk_bf16_f32 v181, v224, v226
	v_lshl_add_u64 v[182:183], v[182:183], 0, v[136:137]
	global_store_dwordx4 v[182:183], v[178:181], off
	s_nop 1
	v_add_f32_e32 v179, 1.0, v211
	v_add_f32_e32 v178, 1.0, v212
	v_rcp_f32_e32 v180, v179
	v_add_f32_e32 v179, 1.0, v252
	v_add_f32_e32 v181, 1.0, v251
	v_add_f32_e32 v224, 1.0, v250
	v_add_f32_e32 v225, 1.0, v249
	v_add_f32_e32 v226, 1.0, v248
	v_add_f32_e32 v239, 1.0, v247
	v_rcp_f32_e32 v178, v178
	v_rcp_f32_e32 v179, v179
	v_rcp_f32_e32 v181, v181
	v_rcp_f32_e32 v224, v224
	v_rcp_f32_e32 v225, v225
	v_rcp_f32_e32 v226, v226
	v_rcp_f32_e32 v239, v239
	v_cvt_pk_bf16_f32 v178, v178, v179
	v_cvt_pk_bf16_f32 v180, v180, v181
	v_cvt_pk_bf16_f32 v179, v224, v226
	v_cvt_pk_bf16_f32 v181, v225, v239
	global_store_dwordx4 v[182:183], v[178:181], off offset:256
	s_nop 1
	v_add_f32_e32 v179, 1.0, v245
	v_add_f32_e32 v178, 1.0, v246
	v_rcp_f32_e32 v180, v179
	v_add_f32_e32 v179, 1.0, v244
	v_add_f32_e32 v183, 1.0, v242
	v_add_f32_e32 v225, 1.0, v184
	v_rcp_f32_e32 v178, v178
	v_rcp_f32_e32 v179, v179
	v_add_f32_e32 v181, 1.0, v243
	v_rcp_f32_e32 v183, v183
	v_add_f32_e32 v224, 1.0, v241
	v_rcp_f32_e32 v225, v225
	v_add_f32_e32 v226, 1.0, v177
	v_rcp_f32_e32 v181, v181
	v_rcp_f32_e32 v224, v224
	v_rcp_f32_e32 v226, v226
	v_add_u32_e32 v182, 32, v0
	v_cvt_pk_bf16_f32 v178, v178, v179
	v_cvt_pk_bf16_f32 v179, v183, v225
	v_mad_i64_i32 v[182:183], s[0:1], v182, s47, v[134:135]
	v_cvt_pk_bf16_f32 v180, v180, v181
	v_cvt_pk_bf16_f32 v181, v224, v226
	v_lshl_add_u64 v[182:183], v[182:183], 0, v[136:137]
	global_store_dwordx4 v[182:183], v[178:181], off
	s_nop 1
	v_add_f32_e32 v179, 1.0, v199
	v_add_f32_e32 v178, 1.0, v198
	v_rcp_f32_e32 v180, v179
	v_add_f32_e32 v179, 1.0, v197
	v_add_f32_e32 v181, 1.0, v196
	v_add_f32_e32 v224, 1.0, v195
	v_add_f32_e32 v225, 1.0, v194
	v_add_f32_e32 v226, 1.0, v193
	v_add_f32_e32 v239, 1.0, v192
	v_rcp_f32_e32 v178, v178
	v_rcp_f32_e32 v179, v179
	v_rcp_f32_e32 v181, v181
	v_rcp_f32_e32 v224, v224
	v_rcp_f32_e32 v225, v225
	v_rcp_f32_e32 v226, v226
	v_rcp_f32_e32 v239, v239
	v_cvt_pk_bf16_f32 v178, v178, v179
	v_cvt_pk_bf16_f32 v180, v180, v181
	v_cvt_pk_bf16_f32 v179, v224, v226
	v_cvt_pk_bf16_f32 v181, v225, v239
	global_store_dwordx4 v[182:183], v[178:181], off offset:256
	s_nop 1
	v_add_f32_e32 v179, 1.0, v190
	v_add_f32_e32 v178, 1.0, v191
	v_rcp_f32_e32 v180, v179
	v_add_f32_e32 v179, 1.0, v189
	v_add_f32_e32 v183, 1.0, v187
	v_add_f32_e32 v225, 1.0, v185
	v_rcp_f32_e32 v178, v178
	v_rcp_f32_e32 v179, v179
	v_add_f32_e32 v181, 1.0, v188
	v_rcp_f32_e32 v183, v183
	v_add_f32_e32 v224, 1.0, v186
	v_rcp_f32_e32 v225, v225
	v_add_f32_e32 v226, 1.0, v201
	v_rcp_f32_e32 v181, v181
	v_rcp_f32_e32 v224, v224
	v_rcp_f32_e32 v226, v226
	v_add_u32_e32 v182, 48, v0
	v_cvt_pk_bf16_f32 v178, v178, v179
	v_cvt_pk_bf16_f32 v179, v183, v225
	v_mad_i64_i32 v[182:183], s[0:1], v182, s47, v[134:135]
	v_cvt_pk_bf16_f32 v180, v180, v181
	v_cvt_pk_bf16_f32 v181, v224, v226
	v_lshl_add_u64 v[182:183], v[182:183], 0, v[136:137]
	global_store_dwordx4 v[182:183], v[178:181], off
	s_nop 1
	v_add_f32_e32 v179, 1.0, v221
	v_add_f32_e32 v178, 1.0, v200
	v_rcp_f32_e32 v180, v179
	v_add_f32_e32 v179, 1.0, v220
	v_add_f32_e32 v181, 1.0, v219
	v_add_f32_e32 v224, 1.0, v218
	v_add_f32_e32 v225, 1.0, v217
	v_add_f32_e32 v226, 1.0, v216
	v_add_f32_e32 v239, 1.0, v215
	v_rcp_f32_e32 v178, v178
	v_rcp_f32_e32 v179, v179
	v_rcp_f32_e32 v181, v181
	v_rcp_f32_e32 v224, v224
	v_rcp_f32_e32 v225, v225
	v_rcp_f32_e32 v226, v226
	v_rcp_f32_e32 v239, v239
	v_cvt_pk_bf16_f32 v178, v178, v179
	v_cvt_pk_bf16_f32 v180, v180, v181
	v_cvt_pk_bf16_f32 v179, v224, v226
	v_cvt_pk_bf16_f32 v181, v225, v239
	global_store_dwordx4 v[182:183], v[178:181], off offset:256
	s_nop 1
	v_add_f32_e32 v179, 1.0, v208
	v_add_f32_e32 v178, 1.0, v209
	v_rcp_f32_e32 v180, v179
	v_add_f32_e32 v179, 1.0, v207
	v_add_f32_e32 v183, 1.0, v205
	v_add_f32_e32 v225, 1.0, v203
	v_rcp_f32_e32 v178, v178
	v_rcp_f32_e32 v179, v179
	v_add_f32_e32 v181, 1.0, v206
	v_rcp_f32_e32 v183, v183
	v_add_f32_e32 v224, 1.0, v204
	v_rcp_f32_e32 v225, v225
	v_add_f32_e32 v226, 1.0, v202
	v_rcp_f32_e32 v181, v181
	v_rcp_f32_e32 v224, v224
	v_rcp_f32_e32 v226, v226
	v_add_u32_e32 v182, 0x80, v0
	v_cvt_pk_bf16_f32 v178, v178, v179
	v_cvt_pk_bf16_f32 v179, v183, v225
	v_mad_i64_i32 v[182:183], s[0:1], v182, s47, v[134:135]
	v_cvt_pk_bf16_f32 v180, v180, v181
	v_cvt_pk_bf16_f32 v181, v224, v226
	v_lshl_add_u64 v[182:183], v[182:183], 0, v[136:137]
	global_store_dwordx4 v[182:183], v[178:181], off
	s_nop 1
	v_add_f32_e32 v179, 1.0, v222
	v_rcp_f32_e32 v180, v179
	v_exp_f32_e32 v179, v237
	v_exp_f32_e32 v224, v236
	v_exp_f32_e32 v226, v234
	v_exp_f32_e32 v239, v233
	v_add_f32_e32 v179, 1.0, v179
	v_rcp_f32_e32 v225, v179
	v_exp_f32_e32 v179, v235
	v_add_f32_e32 v178, 1.0, v223
	v_add_f32_e32 v181, 1.0, v238
	v_add_f32_e32 v224, 1.0, v224
	v_add_f32_e32 v179, 1.0, v179
	v_rcp_f32_e32 v227, v179
	v_add_f32_e32 v179, 1.0, v226
	v_add_f32_e32 v226, 1.0, v239
	v_rcp_f32_e32 v178, v178
	v_rcp_f32_e32 v181, v181
	v_rcp_f32_e32 v224, v224
	v_rcp_f32_e32 v179, v179
	v_rcp_f32_e32 v226, v226
	v_cvt_pk_bf16_f32 v178, v178, v181
	v_cvt_pk_bf16_f32 v180, v180, v225
	v_cvt_pk_bf16_f32 v179, v224, v179
	v_cvt_pk_bf16_f32 v181, v227, v226
	global_store_dwordx4 v[182:183], v[178:181], off offset:256
	s_nop 1
	v_exp_f32_e32 v179, v231
	v_mul_f32_e32 v183, 0xbfb8aa3b, v52
	v_mul_f32_e32 v225, 0xbfb8aa3b, v53
	v_exp_f32_e32 v183, v183
	v_add_f32_e32 v179, 1.0, v179
	v_rcp_f32_e32 v181, v179
	v_exp_f32_e32 v179, v229
	v_exp_f32_e32 v225, v225
	v_mul_f32_e32 v226, 0xbfb8aa3b, v45
	v_exp_f32_e32 v178, v232
	v_add_f32_e32 v179, 1.0, v179
	v_rcp_f32_e32 v224, v179
	v_mul_f32_e32 v179, 0xbfb8aa3b, v44
	v_exp_f32_e32 v179, v179
	v_exp_f32_e32 v180, v230
	v_exp_f32_e32 v226, v226
	v_add_f32_e32 v183, 1.0, v183
	v_add_f32_e32 v179, 1.0, v179
	v_rcp_f32_e32 v227, v179
	v_add_f32_e32 v179, 1.0, v225
	v_add_f32_e32 v178, 1.0, v178
	v_add_f32_e32 v180, 1.0, v180
	v_rcp_f32_e32 v183, v183
	v_rcp_f32_e32 v179, v179
	v_add_f32_e32 v225, 1.0, v226
	v_rcp_f32_e32 v178, v178
	v_rcp_f32_e32 v180, v180
	v_rcp_f32_e32 v225, v225
	v_add_u32_e32 v182, 0x90, v0
	v_cvt_pk_bf16_f32 v179, v183, v179
	v_mad_i64_i32 v[182:183], s[0:1], v182, s47, v[134:135]
	v_cvt_pk_bf16_f32 v178, v178, v180
	v_cvt_pk_bf16_f32 v180, v181, v224
	v_cvt_pk_bf16_f32 v181, v227, v225
	v_lshl_add_u64 v[182:183], v[182:183], 0, v[136:137]
	global_store_dwordx4 v[182:183], v[178:181], off
	s_nop 1
	v_mul_f32_e32 v179, 0xbfb8aa3b, v30
	v_exp_f32_e32 v179, v179
	v_mul_f32_e32 v178, 0xbfb8aa3b, v38
	v_mul_f32_e32 v180, 0xbfb8aa3b, v39
	v_mul_f32_e32 v224, 0xbfb8aa3b, v40
	v_add_f32_e32 v179, 1.0, v179
	v_rcp_f32_e32 v181, v179
	v_mul_f32_e32 v179, 0xbfb8aa3b, v31
	v_exp_f32_e32 v179, v179
	v_mul_f32_e32 v226, 0xbfb8aa3b, v41
	v_mul_f32_e32 v227, 0xbfb8aa3b, v33
	v_exp_f32_e32 v178, v178
	v_add_f32_e32 v179, 1.0, v179
	v_rcp_f32_e32 v225, v179
	v_mul_f32_e32 v179, 0xbfb8aa3b, v32
	v_exp_f32_e32 v179, v179
	v_exp_f32_e32 v180, v180
	v_exp_f32_e32 v224, v224
	v_exp_f32_e32 v226, v226
	v_exp_f32_e32 v227, v227
	v_add_f32_e32 v179, 1.0, v179
	v_add_f32_e32 v178, 1.0, v178
	v_add_f32_e32 v180, 1.0, v180
	v_add_f32_e32 v224, 1.0, v224
	v_rcp_f32_e32 v239, v179
	v_add_f32_e32 v179, 1.0, v226
	v_add_f32_e32 v226, 1.0, v227
	v_rcp_f32_e32 v178, v178
	v_rcp_f32_e32 v180, v180
	v_rcp_f32_e32 v224, v224
	v_rcp_f32_e32 v179, v179
	v_rcp_f32_e32 v226, v226
	v_cvt_pk_bf16_f32 v178, v178, v180
	v_cvt_pk_bf16_f32 v180, v181, v225
	v_cvt_pk_bf16_f32 v179, v224, v179
	v_cvt_pk_bf16_f32 v181, v239, v226
	global_store_dwordx4 v[182:183], v[178:181], off offset:256
	s_nop 1
	v_mul_f32_e32 v179, 0xbfb8aa3b, v26
	v_exp_f32_e32 v179, v179
	v_mul_f32_e32 v183, 0xbfb8aa3b, v36
	v_mul_f32_e32 v225, 0xbfb8aa3b, v37
	v_mul_f32_e32 v178, 0xbfb8aa3b, v34
	v_add_f32_e32 v179, 1.0, v179
	v_rcp_f32_e32 v181, v179
	v_mul_f32_e32 v179, 0xbfb8aa3b, v27
	v_exp_f32_e32 v179, v179
	v_mul_f32_e32 v180, 0xbfb8aa3b, v35
	v_exp_f32_e32 v183, v183
	v_exp_f32_e32 v225, v225
	v_add_f32_e32 v179, 1.0, v179
	v_rcp_f32_e32 v224, v179
	v_mul_f32_e32 v179, 0xbfb8aa3b, v28
	v_exp_f32_e32 v179, v179
	v_mul_f32_e32 v226, 0xbfb8aa3b, v29
	v_exp_f32_e32 v178, v178
	v_exp_f32_e32 v180, v180
	v_exp_f32_e32 v226, v226
	v_add_f32_e32 v179, 1.0, v179
	v_add_f32_e32 v183, 1.0, v183
	v_rcp_f32_e32 v227, v179
	v_add_f32_e32 v179, 1.0, v225
	v_add_f32_e32 v178, 1.0, v178
	v_add_f32_e32 v180, 1.0, v180
	v_rcp_f32_e32 v183, v183
	v_rcp_f32_e32 v179, v179
	v_add_f32_e32 v225, 1.0, v226
	v_rcp_f32_e32 v178, v178
	v_rcp_f32_e32 v180, v180
	v_rcp_f32_e32 v225, v225
	v_add_u32_e32 v182, 0xa0, v0
	v_cvt_pk_bf16_f32 v179, v183, v179
	v_mad_i64_i32 v[182:183], s[0:1], v182, s47, v[134:135]
	v_cvt_pk_bf16_f32 v178, v178, v180
	v_cvt_pk_bf16_f32 v180, v181, v224
	v_cvt_pk_bf16_f32 v181, v227, v225
	v_lshl_add_u64 v[182:183], v[182:183], 0, v[136:137]
	global_store_dwordx4 v[182:183], v[178:181], off
	s_nop 1
	v_mul_f32_e32 v179, 0xbfb8aa3b, v14
	v_exp_f32_e32 v179, v179
	v_mul_f32_e32 v178, 0xbfb8aa3b, v22
	v_mul_f32_e32 v180, 0xbfb8aa3b, v23
	v_mul_f32_e32 v224, 0xbfb8aa3b, v24
	v_add_f32_e32 v179, 1.0, v179
	v_rcp_f32_e32 v181, v179
	v_mul_f32_e32 v179, 0xbfb8aa3b, v15
	v_exp_f32_e32 v179, v179
	v_mul_f32_e32 v226, 0xbfb8aa3b, v25
	v_mul_f32_e32 v227, 0xbfb8aa3b, v17
	v_exp_f32_e32 v178, v178
	v_add_f32_e32 v179, 1.0, v179
	v_rcp_f32_e32 v225, v179
	v_mul_f32_e32 v179, 0xbfb8aa3b, v16
	v_exp_f32_e32 v179, v179
	v_exp_f32_e32 v180, v180
	v_exp_f32_e32 v224, v224
	v_exp_f32_e32 v226, v226
	v_exp_f32_e32 v227, v227
	v_add_f32_e32 v179, 1.0, v179
	v_add_f32_e32 v178, 1.0, v178
	v_add_f32_e32 v180, 1.0, v180
	v_add_f32_e32 v224, 1.0, v224
	v_rcp_f32_e32 v239, v179
	v_add_f32_e32 v179, 1.0, v226
	v_add_f32_e32 v226, 1.0, v227
	v_rcp_f32_e32 v178, v178
	v_rcp_f32_e32 v180, v180
	v_rcp_f32_e32 v224, v224
	v_rcp_f32_e32 v179, v179
	v_rcp_f32_e32 v226, v226
	v_cvt_pk_bf16_f32 v178, v178, v180
	v_cvt_pk_bf16_f32 v180, v181, v225
	v_cvt_pk_bf16_f32 v179, v224, v179
	v_cvt_pk_bf16_f32 v181, v239, v226
	global_store_dwordx4 v[182:183], v[178:181], off offset:256
	s_nop 1
	v_mul_f32_e32 v179, 0xbfb8aa3b, v10
	v_exp_f32_e32 v179, v179
	v_mul_f32_e32 v180, 0xbfb8aa3b, v19
	v_mul_f32_e32 v181, 0xbfb8aa3b, v11
	v_exp_f32_e32 v180, v180
	v_exp_f32_e32 v181, v181
	v_add_f32_e32 v179, 1.0, v179
	v_rcp_f32_e32 v182, v179
	v_add_f32_e32 v179, 1.0, v180
	v_add_f32_e32 v180, 1.0, v181
	v_mul_f32_e32 v181, 0xbfb8aa3b, v20
	v_mul_f32_e32 v183, 0xbfb8aa3b, v12
	v_mul_f32_e32 v224, 0xbfb8aa3b, v21
	v_mul_f32_e32 v225, 0xbfb8aa3b, v13
	v_exp_f32_e32 v178, v228
	v_exp_f32_e32 v181, v181
	v_exp_f32_e32 v183, v183
	v_exp_f32_e32 v224, v224
	v_exp_f32_e32 v225, v225
	v_add_f32_e32 v178, 1.0, v178
	v_add_f32_e32 v181, 1.0, v181
	v_add_f32_e32 v183, 1.0, v183
	v_add_f32_e32 v224, 1.0, v224
	v_add_f32_e32 v225, 1.0, v225
	v_rcp_f32_e32 v178, v178
	v_rcp_f32_e32 v179, v179
	v_rcp_f32_e32 v180, v180
	v_rcp_f32_e32 v181, v181
	v_rcp_f32_e32 v183, v183
	v_rcp_f32_e32 v224, v224
	v_rcp_f32_e32 v225, v225
	v_add_u32_e32 v0, 0xb0, v0
	v_mad_i64_i32 v[134:135], s[0:1], v0, s47, v[134:135]
	v_cvt_pk_bf16_f32 v178, v178, v179
	v_cvt_pk_bf16_f32 v179, v181, v224
	v_cvt_pk_bf16_f32 v180, v182, v180
	v_cvt_pk_bf16_f32 v181, v183, v225
	v_lshl_add_u64 v[182:183], v[134:135], 0, v[136:137]
	global_store_dwordx4 v[182:183], v[178:181], off
	v_mul_f32_e32 v134, 0xbfb8aa3b, v2
	v_exp_f32_e32 v134, v134
	v_mul_f32_e32 v135, 0xbfb8aa3b, v7
	v_mul_f32_e32 v136, 0xbfb8aa3b, v3
	v_exp_f32_e32 v135, v135
	v_exp_f32_e32 v136, v136
	v_add_f32_e32 v134, 1.0, v134
	v_rcp_f32_e32 v137, v134
	v_add_f32_e32 v134, 1.0, v135
	v_add_f32_e32 v135, 1.0, v136
	v_mul_f32_e32 v136, 0xbfb8aa3b, v8
	v_mul_f32_e32 v178, 0xbfb8aa3b, v4
	v_exp_f32_e32 v136, v136
	v_exp_f32_e32 v178, v178
	v_mul_f32_e32 v0, 0xbfb8aa3b, v6
	v_rcp_f32_e32 v179, v135
	v_add_f32_e32 v135, 1.0, v136
	v_add_f32_e32 v136, 1.0, v178
	v_mul_f32_e32 v178, 0xbfb8aa3b, v9
	v_mul_f32_e32 v180, 0xbfb8aa3b, v5
	v_exp_f32_e32 v0, v0
	v_exp_f32_e32 v178, v178
	v_exp_f32_e32 v180, v180
	v_rcp_f32_e32 v181, v136
	v_add_f32_e32 v0, 1.0, v0
	v_add_f32_e32 v136, 1.0, v178
	v_add_f32_e32 v178, 1.0, v180
	v_rcp_f32_e32 v0, v0
	v_rcp_f32_e32 v134, v134
	v_rcp_f32_e32 v135, v135
	v_rcp_f32_e32 v136, v136
	v_rcp_f32_e32 v178, v178
	v_cvt_pk_bf16_f32 v134, v0, v134
	v_cvt_pk_bf16_f32 v135, v135, v136
	v_cvt_pk_bf16_f32 v136, v137, v179
	v_cvt_pk_bf16_f32 v137, v181, v178
	global_store_dwordx4 v[182:183], v[134:137], off offset:256
	s_mov_b64 s[0:1], 0

.LBB0_726:
	s_xor_b64 s[6:7], s[26:27], -1
	s_add_i32 vcc_lo, s14, 32
	s_lshl_b64 s[12:13], s[14:15], 7
	s_mov_b64 s[22:23], 0x1f00
	v_mov_b64_e32 v[130:131], v[158:159]
	v_mov_b64_e32 v[132:133], v[156:157]
	s_mov_b64 s[26:27], s[8:9]
	s_mov_b64 s[30:31], s[0:1]
	v_add_u32_e32 v224, 0x10000, v149
	v_add_u32_e32 v225, 0x14000, v149
	v_add_u32_e32 v226, 0x18000, v149
	v_add_u32_e32 v227, 0x1c000, v149
	v_readfirstlane_b32 s32, v148
	s_nop 3
	s_cmp_ge_u32 s32, 0x100
	s_cbranch_scc0 .Lprio_skip_1
	s_setprio 1
.Lprio_skip_1:
.LBB0_727:
	s_add_i32 s14, s14, 2
	s_add_u32 s40, s30, s12
	s_addc_u32 s41, s31, s13
	s_add_u32 s84, s26, s12
	s_addc_u32 s85, s27, s13
	s_add_i32 s86, 0, 0x10000
	ds_read_b128 v[134:137], v224
	ds_read_b128 v[152:155], v224 offset:1024
	ds_read_b128 v[162:165], v224 offset:2048
	ds_read_b128 v[166:169], v224 offset:3072
	s_cmp_eq_u32 s12, s22
	s_cselect_b32 s61, s51, s41
	s_cselect_b32 s60, s50, s40
	s_cselect_b32 s41, s49, s85
	s_cselect_b32 s40, s80, s84
	v_lshl_add_u64 v[202:203], v[132:133], 0, s[12:13]
	s_add_i32 m0, s66, 0xc000
	ds_read_b128 v[170:173], v160
	ds_read_b128 v[174:177], v160 offset:1024
	ds_read_b128 v[178:181], v160 offset:2048
	ds_read_b128 v[182:185], v160 offset:3072
	ds_read_b128 v[186:189], v160 offset:4096
	ds_read_b128 v[190:193], v160 offset:5120
	ds_read_b128 v[194:197], v160 offset:6144
	ds_read_b128 v[198:201], v160 offset:7168
	global_load_lds_dwordx4 v[202:203], off
	v_lshl_add_u64 v[202:203], v[130:131], 0, s[12:13]
	s_add_i32 m0, s66, 0xe000
	s_nop 0
	global_load_lds_dwordx4 v[202:203], off
	s_waitcnt lgkmcnt(8)
	s_barrier
	s_waitcnt lgkmcnt(7)
	v_mfma_f32_16x16x32_bf16 v[126:129], v[134:137], v[170:173], v[126:129]
	v_mfma_f32_16x16x32_bf16 v[122:125], v[162:165], v[170:173], v[122:125]
	s_waitcnt lgkmcnt(5)
	v_mfma_f32_16x16x32_bf16 v[110:113], v[134:137], v[178:181], v[110:113]
	v_mfma_f32_16x16x32_bf16 v[106:109], v[162:165], v[178:181], v[106:109]
	s_waitcnt lgkmcnt(3)
	v_mfma_f32_16x16x32_bf16 v[94:97], v[134:137], v[186:189], v[94:97]
	v_mfma_f32_16x16x32_bf16 v[90:93], v[162:165], v[186:189], v[90:93]
	s_waitcnt lgkmcnt(1)
	v_mfma_f32_16x16x32_bf16 v[78:81], v[134:137], v[194:197], v[78:81]
	v_mfma_f32_16x16x32_bf16 v[74:77], v[162:165], v[194:197], v[74:77]
	v_mfma_f32_16x16x32_bf16 v[126:129], v[152:155], v[174:177], v[126:129]
	v_mfma_f32_16x16x32_bf16 v[122:125], v[166:169], v[174:177], v[122:125]
	v_mfma_f32_16x16x32_bf16 v[110:113], v[152:155], v[182:185], v[110:113]
	v_mfma_f32_16x16x32_bf16 v[106:109], v[166:169], v[182:185], v[106:109]
	v_mfma_f32_16x16x32_bf16 v[94:97], v[152:155], v[190:193], v[94:97]
	v_mfma_f32_16x16x32_bf16 v[90:93], v[166:169], v[190:193], v[90:93]
	s_waitcnt lgkmcnt(0)
	v_mfma_f32_16x16x32_bf16 v[78:81], v[152:155], v[198:201], v[78:81]
	v_mfma_f32_16x16x32_bf16 v[74:77], v[166:169], v[198:201], v[74:77]
	s_barrier
	s_add_i32 s87, 0, 0x14000
	s_add_i32 s84, s86, s65
	s_mov_b32 m0, s84
	ds_read_b128 v[202:205], v225
	ds_read_b128 v[206:209], v225 offset:1024
	ds_read_b128 v[216:219], v225 offset:2048
	global_load_lds_dwordx4 v0, s[40:41]
	s_add_i32 m0, s84, 0x2000
	ds_read_b128 v[220:223], v225 offset:3072
	global_load_lds_dwordx4 v138, s[40:41]
	s_barrier
	s_waitcnt lgkmcnt(3)
	v_mfma_f32_16x16x32_bf16 v[118:121], v[202:205], v[170:173], v[118:121]
	s_waitcnt lgkmcnt(1)
	v_mfma_f32_16x16x32_bf16 v[114:117], v[216:219], v[170:173], v[114:117]
	v_mfma_f32_16x16x32_bf16 v[102:105], v[202:205], v[178:181], v[102:105]
	v_mfma_f32_16x16x32_bf16 v[98:101], v[216:219], v[178:181], v[98:101]
	v_mfma_f32_16x16x32_bf16 v[86:89], v[202:205], v[186:189], v[86:89]
	v_mfma_f32_16x16x32_bf16 v[82:85], v[216:219], v[186:189], v[82:85]
	v_mfma_f32_16x16x32_bf16 v[70:73], v[202:205], v[194:197], v[70:73]
	v_mfma_f32_16x16x32_bf16 v[66:69], v[216:219], v[194:197], v[66:69]
	v_mfma_f32_16x16x32_bf16 v[118:121], v[206:209], v[174:177], v[118:121]
	s_waitcnt lgkmcnt(0)
	v_mfma_f32_16x16x32_bf16 v[114:117], v[220:223], v[174:177], v[114:117]
	v_mfma_f32_16x16x32_bf16 v[102:105], v[206:209], v[182:185], v[102:105]
	v_mfma_f32_16x16x32_bf16 v[98:101], v[220:223], v[182:185], v[98:101]
	v_mfma_f32_16x16x32_bf16 v[86:89], v[206:209], v[190:193], v[86:89]
	v_mfma_f32_16x16x32_bf16 v[82:85], v[220:223], v[190:193], v[82:85]
	v_mfma_f32_16x16x32_bf16 v[70:73], v[206:209], v[198:201], v[70:73]
	v_mfma_f32_16x16x32_bf16 v[66:69], v[220:223], v[198:201], v[66:69]
	s_mov_b32 m0, s66
	s_add_u32 s98, s60, 0x80
	s_addc_u32 s99, s61, 0
	s_barrier
	ds_read_b128 v[170:173], v160 offset:16384
	ds_read_b128 v[174:177], v160 offset:17408
	ds_read_b128 v[178:181], v160 offset:18432
	ds_read_b128 v[182:185], v160 offset:19456
	ds_read_b128 v[186:189], v160 offset:20480
	ds_read_b128 v[190:193], v160 offset:21504
	ds_read_b128 v[194:197], v160 offset:22528
	global_load_lds_dwordx4 v142, s[60:61]
	s_mov_b32 m0, s67
	ds_read_b128 v[198:201], v160 offset:23552
	global_load_lds_dwordx4 v140, s[60:61]
	s_barrier
	s_waitcnt lgkmcnt(7)
	v_mfma_f32_16x16x32_bf16 v[62:65], v[134:137], v[170:173], v[62:65]
	v_mfma_f32_16x16x32_bf16 v[58:61], v[162:165], v[170:173], v[58:61]
	s_waitcnt lgkmcnt(5)
	v_mfma_f32_16x16x32_bf16 v[46:49], v[134:137], v[178:181], v[46:49]
	v_mfma_f32_16x16x32_bf16 v[42:45], v[162:165], v[178:181], v[42:45]
	s_waitcnt lgkmcnt(3)
	v_mfma_f32_16x16x32_bf16 v[30:33], v[134:137], v[186:189], v[30:33]
	v_mfma_f32_16x16x32_bf16 v[26:29], v[162:165], v[186:189], v[26:29]
	s_waitcnt lgkmcnt(1)
	v_mfma_f32_16x16x32_bf16 v[14:17], v[134:137], v[194:197], v[14:17]
	v_mfma_f32_16x16x32_bf16 v[10:13], v[162:165], v[194:197], v[10:13]
	v_mfma_f32_16x16x32_bf16 v[62:65], v[152:155], v[174:177], v[62:65]
	v_mfma_f32_16x16x32_bf16 v[58:61], v[166:169], v[174:177], v[58:61]
	v_mfma_f32_16x16x32_bf16 v[46:49], v[152:155], v[182:185], v[46:49]
	v_mfma_f32_16x16x32_bf16 v[42:45], v[166:169], v[182:185], v[42:45]
	v_mfma_f32_16x16x32_bf16 v[30:33], v[152:155], v[190:193], v[30:33]
	v_mfma_f32_16x16x32_bf16 v[26:29], v[166:169], v[190:193], v[26:29]
	s_waitcnt lgkmcnt(0)
	v_mfma_f32_16x16x32_bf16 v[14:17], v[152:155], v[198:201], v[14:17]
	v_mfma_f32_16x16x32_bf16 v[10:13], v[166:169], v[198:201], v[10:13]
	s_barrier
	s_add_i32 s86, s87, s65
	s_mov_b32 m0, s86
	s_add_u32 s84, s40, 0x100000
	s_addc_u32 s85, s41, 0
	global_load_lds_dwordx4 v0, s[84:85]
	s_add_i32 m0, s86, 0x2000
	s_nop 0
	global_load_lds_dwordx4 v138, s[84:85]
	s_waitcnt vmcnt(6)
	s_barrier
	v_mfma_f32_16x16x32_bf16 v[54:57], v[202:205], v[170:173], v[54:57]
	v_mfma_f32_16x16x32_bf16 v[50:53], v[216:219], v[170:173], v[50:53]
	v_mfma_f32_16x16x32_bf16 v[38:41], v[202:205], v[178:181], v[38:41]
	v_mfma_f32_16x16x32_bf16 v[34:37], v[216:219], v[178:181], v[34:37]
	v_mfma_f32_16x16x32_bf16 v[22:25], v[202:205], v[186:189], v[22:25]
	v_mfma_f32_16x16x32_bf16 v[18:21], v[216:219], v[186:189], v[18:21]
	v_mfma_f32_16x16x32_bf16 v[6:9], v[202:205], v[194:197], v[6:9]
	v_mfma_f32_16x16x32_bf16 v[2:5], v[216:219], v[194:197], v[2:5]
	v_mfma_f32_16x16x32_bf16 v[54:57], v[206:209], v[174:177], v[54:57]
	v_mfma_f32_16x16x32_bf16 v[50:53], v[220:223], v[174:177], v[50:53]
	v_mfma_f32_16x16x32_bf16 v[38:41], v[206:209], v[182:185], v[38:41]
	v_mfma_f32_16x16x32_bf16 v[34:37], v[220:223], v[182:185], v[34:37]
	v_mfma_f32_16x16x32_bf16 v[22:25], v[206:209], v[190:193], v[22:25]
	v_mfma_f32_16x16x32_bf16 v[18:21], v[220:223], v[190:193], v[18:21]
	v_mfma_f32_16x16x32_bf16 v[6:9], v[206:209], v[198:201], v[6:9]
	v_mfma_f32_16x16x32_bf16 v[2:5], v[220:223], v[198:201], v[2:5]
	s_add_i32 s84, 0, 0x18000
	s_barrier
	ds_read_b128 v[134:137], v226
	ds_read_b128 v[152:155], v226 offset:1024
	ds_read_b128 v[162:165], v226 offset:2048
	ds_read_b128 v[166:169], v226 offset:3072
	s_add_u32 s60, s60, 0x100000
	s_addc_u32 s61, s61, 0
	s_mov_b32 m0, s68
	ds_read_b128 v[170:173], v160 offset:32768
	ds_read_b128 v[174:177], v160 offset:33792
	ds_read_b128 v[178:181], v160 offset:34816
	ds_read_b128 v[182:185], v160 offset:35840
	ds_read_b128 v[186:189], v160 offset:36864
	ds_read_b128 v[190:193], v160 offset:37888
	ds_read_b128 v[194:197], v160 offset:38912
	global_load_lds_dwordx4 v142, s[60:61]
	s_mov_b32 m0, s69
	ds_read_b128 v[198:201], v160 offset:39936
	global_load_lds_dwordx4 v140, s[60:61]
	s_waitcnt lgkmcnt(8)
	s_barrier
	s_waitcnt lgkmcnt(7)
	v_mfma_f32_16x16x32_bf16 v[126:129], v[134:137], v[170:173], v[126:129]
	v_mfma_f32_16x16x32_bf16 v[122:125], v[162:165], v[170:173], v[122:125]
	s_waitcnt lgkmcnt(5)
	v_mfma_f32_16x16x32_bf16 v[110:113], v[134:137], v[178:181], v[110:113]
	v_mfma_f32_16x16x32_bf16 v[106:109], v[162:165], v[178:181], v[106:109]
	s_waitcnt lgkmcnt(3)
	v_mfma_f32_16x16x32_bf16 v[94:97], v[134:137], v[186:189], v[94:97]
	v_mfma_f32_16x16x32_bf16 v[90:93], v[162:165], v[186:189], v[90:93]
	s_waitcnt lgkmcnt(1)
	v_mfma_f32_16x16x32_bf16 v[78:81], v[134:137], v[194:197], v[78:81]
	v_mfma_f32_16x16x32_bf16 v[74:77], v[162:165], v[194:197], v[74:77]
	v_mfma_f32_16x16x32_bf16 v[126:129], v[152:155], v[174:177], v[126:129]
	v_mfma_f32_16x16x32_bf16 v[122:125], v[166:169], v[174:177], v[122:125]
	v_mfma_f32_16x16x32_bf16 v[110:113], v[152:155], v[182:185], v[110:113]
	v_mfma_f32_16x16x32_bf16 v[106:109], v[166:169], v[182:185], v[106:109]
	v_mfma_f32_16x16x32_bf16 v[94:97], v[152:155], v[190:193], v[94:97]
	v_mfma_f32_16x16x32_bf16 v[90:93], v[166:169], v[190:193], v[90:93]
	s_waitcnt lgkmcnt(0)
	v_mfma_f32_16x16x32_bf16 v[78:81], v[152:155], v[198:201], v[78:81]
	v_mfma_f32_16x16x32_bf16 v[74:77], v[166:169], v[198:201], v[74:77]
	s_barrier
	s_add_i32 s60, 0, 0x1c000
	s_add_i32 s61, s84, s65
	s_add_u32 s100, s40, 0x80
	s_addc_u32 s101, s41, 0
	s_mov_b32 m0, s61
	ds_read_b128 v[202:205], v227
	ds_read_b128 v[206:209], v227 offset:1024
	ds_read_b128 v[216:219], v227 offset:2048
	global_load_lds_dwordx4 v0, s[100:101]
	s_add_i32 m0, s61, 0x2000
	ds_read_b128 v[220:223], v227 offset:3072
	global_load_lds_dwordx4 v138, s[100:101]
	s_barrier
	s_waitcnt lgkmcnt(3)
	v_mfma_f32_16x16x32_bf16 v[118:121], v[202:205], v[170:173], v[118:121]
	s_waitcnt lgkmcnt(1)
	v_mfma_f32_16x16x32_bf16 v[114:117], v[216:219], v[170:173], v[114:117]
	v_mfma_f32_16x16x32_bf16 v[102:105], v[202:205], v[178:181], v[102:105]
	v_mfma_f32_16x16x32_bf16 v[98:101], v[216:219], v[178:181], v[98:101]
	v_mfma_f32_16x16x32_bf16 v[86:89], v[202:205], v[186:189], v[86:89]
	v_mfma_f32_16x16x32_bf16 v[82:85], v[216:219], v[186:189], v[82:85]
	v_mfma_f32_16x16x32_bf16 v[70:73], v[202:205], v[194:197], v[70:73]
	v_mfma_f32_16x16x32_bf16 v[66:69], v[216:219], v[194:197], v[66:69]
	v_mfma_f32_16x16x32_bf16 v[118:121], v[206:209], v[174:177], v[118:121]
	s_waitcnt lgkmcnt(0)
	v_mfma_f32_16x16x32_bf16 v[114:117], v[220:223], v[174:177], v[114:117]
	v_mfma_f32_16x16x32_bf16 v[102:105], v[206:209], v[182:185], v[102:105]
	v_mfma_f32_16x16x32_bf16 v[98:101], v[220:223], v[182:185], v[98:101]
	v_mfma_f32_16x16x32_bf16 v[86:89], v[206:209], v[190:193], v[86:89]
	v_mfma_f32_16x16x32_bf16 v[82:85], v[220:223], v[190:193], v[82:85]
	v_mfma_f32_16x16x32_bf16 v[70:73], v[206:209], v[198:201], v[70:73]
	v_mfma_f32_16x16x32_bf16 v[66:69], v[220:223], v[198:201], v[66:69]
	s_mov_b32 m0, s76
	s_barrier
	ds_read_b128 v[170:173], v160 offset:49152
	ds_read_b128 v[174:177], v160 offset:50176
	ds_read_b128 v[178:181], v160 offset:51200
	ds_read_b128 v[182:185], v160 offset:52224
	ds_read_b128 v[186:189], v160 offset:53248
	ds_read_b128 v[190:193], v160 offset:54272
	ds_read_b128 v[194:197], v160 offset:55296
	global_load_lds_dwordx4 v142, s[98:99]
	s_mov_b32 m0, s77
	ds_read_b128 v[198:201], v160 offset:56320
	global_load_lds_dwordx4 v140, s[98:99]
	s_barrier
	s_waitcnt lgkmcnt(7)
	v_mfma_f32_16x16x32_bf16 v[62:65], v[134:137], v[170:173], v[62:65]
	v_mfma_f32_16x16x32_bf16 v[58:61], v[162:165], v[170:173], v[58:61]
	s_waitcnt lgkmcnt(5)
	v_mfma_f32_16x16x32_bf16 v[46:49], v[134:137], v[178:181], v[46:49]
	v_mfma_f32_16x16x32_bf16 v[42:45], v[162:165], v[178:181], v[42:45]
	s_waitcnt lgkmcnt(3)
	v_mfma_f32_16x16x32_bf16 v[30:33], v[134:137], v[186:189], v[30:33]
	v_mfma_f32_16x16x32_bf16 v[26:29], v[162:165], v[186:189], v[26:29]
	s_waitcnt lgkmcnt(1)
	v_mfma_f32_16x16x32_bf16 v[14:17], v[134:137], v[194:197], v[14:17]
	v_mfma_f32_16x16x32_bf16 v[10:13], v[162:165], v[194:197], v[10:13]
	v_mfma_f32_16x16x32_bf16 v[62:65], v[152:155], v[174:177], v[62:65]
	v_mfma_f32_16x16x32_bf16 v[58:61], v[166:169], v[174:177], v[58:61]
	v_mfma_f32_16x16x32_bf16 v[46:49], v[152:155], v[182:185], v[46:49]
	v_mfma_f32_16x16x32_bf16 v[42:45], v[166:169], v[182:185], v[42:45]
	v_mfma_f32_16x16x32_bf16 v[30:33], v[152:155], v[190:193], v[30:33]
	v_mfma_f32_16x16x32_bf16 v[26:29], v[166:169], v[190:193], v[26:29]
	s_waitcnt lgkmcnt(0)
	v_mfma_f32_16x16x32_bf16 v[14:17], v[152:155], v[198:201], v[14:17]
	v_mfma_f32_16x16x32_bf16 v[10:13], v[166:169], v[198:201], v[10:13]
	s_barrier
	s_add_i32 s60, s60, s65
	s_mov_b32 m0, s60
	s_add_u32 s40, s40, 0x100080
	s_addc_u32 s41, s41, 0
	global_load_lds_dwordx4 v0, s[40:41]
	s_add_i32 m0, s60, 0x2000
	s_nop 0
	global_load_lds_dwordx4 v138, s[40:41]
	s_waitcnt vmcnt(6)
	s_barrier
	v_mfma_f32_16x16x32_bf16 v[54:57], v[202:205], v[170:173], v[54:57]
	v_mfma_f32_16x16x32_bf16 v[50:53], v[216:219], v[170:173], v[50:53]
	v_mfma_f32_16x16x32_bf16 v[38:41], v[202:205], v[178:181], v[38:41]
	v_mfma_f32_16x16x32_bf16 v[34:37], v[216:219], v[178:181], v[34:37]
	v_mfma_f32_16x16x32_bf16 v[22:25], v[202:205], v[186:189], v[22:25]
	v_mfma_f32_16x16x32_bf16 v[18:21], v[216:219], v[186:189], v[18:21]
	v_mfma_f32_16x16x32_bf16 v[6:9], v[202:205], v[194:197], v[6:9]
	v_mfma_f32_16x16x32_bf16 v[2:5], v[216:219], v[194:197], v[2:5]
	v_mfma_f32_16x16x32_bf16 v[54:57], v[206:209], v[174:177], v[54:57]
	v_mfma_f32_16x16x32_bf16 v[50:53], v[220:223], v[174:177], v[50:53]
	v_mfma_f32_16x16x32_bf16 v[38:41], v[206:209], v[182:185], v[38:41]
	v_mfma_f32_16x16x32_bf16 v[34:37], v[220:223], v[182:185], v[34:37]
	v_mfma_f32_16x16x32_bf16 v[22:25], v[206:209], v[190:193], v[22:25]
	v_mfma_f32_16x16x32_bf16 v[18:21], v[220:223], v[190:193], v[18:21]
	v_mfma_f32_16x16x32_bf16 v[6:9], v[206:209], v[198:201], v[6:9]
	v_mfma_f32_16x16x32_bf16 v[2:5], v[220:223], v[198:201], v[2:5]
	s_add_u32 s30, s30, 0x100
	s_addc_u32 s31, s31, 0
	s_add_u32 s26, s26, 0x100
	s_addc_u32 s27, s27, 0
	s_add_u32 s22, s22, 0xffffff00
	s_addc_u32 s23, s23, -1
	v_lshl_add_u64 v[132:133], v[132:133], 0, s[18:19]
	s_cmp_ge_u32 s14, vcc_lo
	v_lshl_add_u64 v[130:131], v[130:131], 0, s[18:19]
	s_barrier
	s_cbranch_scc0 .LBB0_727
	s_setprio 0
	s_mov_b32 s14, 32
	s_mov_b64 s[26:27], 0
	s_andn2_b64 vcc, exec, s[6:7]
	s_mov_b64 s[6:7], -1
	s_cbranch_vccnz .LBB0_724
	v_mov_b32_e32 v130, v148
	v_mov_b64_e32 v[134:135], s[38:39]
	v_and_or_b32 v132, v130, 15, s82
	v_lshrrev_b32_e32 v130, 1, v130
	v_and_or_b32 v130, v130, 24, s75
	v_or_b32_e32 v130, s81, v130
	s_mov_b32 s14, s48
	v_ashrrev_i32_e32 v131, 31, v130
	v_mad_i64_i32 v[136:137], s[0:1], v132, s47, v[134:135]
	v_lshlrev_b64 v[130:131], 1, v[130:131]
	v_lshl_add_u64 v[136:137], v[136:137], 0, v[130:131]
	v_add_co_u32_e32 v152, vcc, s72, v136
	v_ashrrev_i32_e32 v133, 31, v132
	s_nop 0
	v_addc_co_u32_e32 v153, vcc, 0, v137, vcc
	global_load_dwordx4 v[152:155], v[152:153], off
	v_lshlrev_b64 v[156:157], 12, v[132:133]
	v_lshl_add_u64 v[156:157], s[28:29], 0, v[156:157]
	v_lshl_add_u64 v[156:157], v[156:157], 0, v[130:131]
	v_lshl_add_u64 v[136:137], v[136:137], 0, s[34:35]
	s_mov_b32 s22, s79
	s_mov_b64 s[6:7], s[52:53]
	s_mov_b64 s[12:13], s[50:51]
	s_waitcnt vmcnt(0)
	v_lshlrev_b32_e32 v158, 16, v152
	v_and_b32_e32 v159, 0xffff0000, v152
	v_lshlrev_b32_e32 v152, 16, v153
	v_and_b32_e32 v153, 0xffff0000, v153
	v_lshlrev_b32_e32 v162, 16, v154
	v_and_b32_e32 v163, 0xffff0000, v154
	v_lshlrev_b32_e32 v154, 16, v155
	v_and_b32_e32 v155, 0xffff0000, v155
	v_pk_mul_f32 v[128:129], v[128:129], v[152:153]
	v_pk_mul_f32 v[126:127], v[126:127], v[158:159]
	v_pk_mul_f32 v[152:153], v[124:125], v[154:155]
	v_pk_mul_f32 v[124:125], v[122:123], v[162:163]
	v_cvt_pk_bf16_f32 v122, v126, v127
	v_cvt_pk_bf16_f32 v123, v128, v129
	v_cvt_pk_bf16_f32 v124, v124, v125
	v_cvt_pk_bf16_f32 v125, v152, v153
	global_store_dwordx4 v[156:157], v[122:125], off
	global_load_dwordx4 v[122:125], v[136:137], off offset:256
	v_add_u32_e32 v126, 16, v132
	v_mad_i64_i32 v[128:129], s[0:1], v126, s47, v[134:135]
	v_lshl_add_u64 v[128:129], v[128:129], 0, v[130:131]
	v_add_co_u32_e32 v136, vcc, s72, v128
	v_ashrrev_i32_e32 v127, 31, v126
	s_nop 0
	v_addc_co_u32_e32 v137, vcc, 0, v129, vcc
	s_waitcnt vmcnt(0)
	v_lshlrev_b32_e32 v152, 16, v122
	v_and_b32_e32 v153, 0xffff0000, v122
	v_lshlrev_b32_e32 v122, 16, v123
	v_and_b32_e32 v123, 0xffff0000, v123
	v_lshlrev_b32_e32 v154, 16, v124
	v_and_b32_e32 v155, 0xffff0000, v124
	v_lshlrev_b32_e32 v124, 16, v125
	v_and_b32_e32 v125, 0xffff0000, v125
	v_pk_mul_f32 v[120:121], v[120:121], v[122:123]
	v_pk_mul_f32 v[118:119], v[118:119], v[152:153]
	v_pk_mul_f32 v[122:123], v[116:117], v[124:125]
	v_pk_mul_f32 v[116:117], v[114:115], v[154:155]
	v_cvt_pk_bf16_f32 v114, v118, v119
	v_cvt_pk_bf16_f32 v115, v120, v121
	v_cvt_pk_bf16_f32 v116, v116, v117
	v_cvt_pk_bf16_f32 v117, v122, v123
	global_store_dwordx4 v[156:157], v[114:117], off offset:256
	global_load_dwordx4 v[114:117], v[136:137], off
	v_lshlrev_b64 v[118:119], 12, v[126:127]
	v_lshl_add_u64 v[118:119], s[28:29], 0, v[118:119]
	v_lshl_add_u64 v[118:119], v[118:119], 0, v[130:131]
	v_lshl_add_u64 v[120:121], v[128:129], 0, s[34:35]
	s_waitcnt vmcnt(0)
	v_lshlrev_b32_e32 v122, 16, v114
	v_and_b32_e32 v123, 0xffff0000, v114
	v_lshlrev_b32_e32 v114, 16, v115
	v_and_b32_e32 v115, 0xffff0000, v115
	v_lshlrev_b32_e32 v124, 16, v116
	v_and_b32_e32 v125, 0xffff0000, v116
	v_lshlrev_b32_e32 v116, 16, v117
	v_and_b32_e32 v117, 0xffff0000, v117
	v_pk_mul_f32 v[112:113], v[112:113], v[114:115]
	v_pk_mul_f32 v[110:111], v[110:111], v[122:123]
	v_pk_mul_f32 v[114:115], v[108:109], v[116:117]
	v_pk_mul_f32 v[108:109], v[106:107], v[124:125]
	v_cvt_pk_bf16_f32 v106, v110, v111
	v_cvt_pk_bf16_f32 v107, v112, v113
	v_cvt_pk_bf16_f32 v108, v108, v109
	v_cvt_pk_bf16_f32 v109, v114, v115
	global_store_dwordx4 v[118:119], v[106:109], off
	global_load_dwordx4 v[106:109], v[120:121], off offset:256
	v_add_u32_e32 v110, 32, v132
	v_mad_i64_i32 v[112:113], s[0:1], v110, s47, v[134:135]
	v_lshl_add_u64 v[112:113], v[112:113], 0, v[130:131]
	v_add_co_u32_e32 v114, vcc, s72, v112
	v_ashrrev_i32_e32 v111, 31, v110
	s_nop 0
	v_addc_co_u32_e32 v115, vcc, 0, v113, vcc
	s_waitcnt vmcnt(0)
	v_lshlrev_b32_e32 v116, 16, v106
	v_and_b32_e32 v117, 0xffff0000, v106
	v_lshlrev_b32_e32 v106, 16, v107
	v_and_b32_e32 v107, 0xffff0000, v107
	v_lshlrev_b32_e32 v120, 16, v108
	v_and_b32_e32 v121, 0xffff0000, v108
	v_lshlrev_b32_e32 v108, 16, v109
	v_and_b32_e32 v109, 0xffff0000, v109
	v_pk_mul_f32 v[104:105], v[104:105], v[106:107]
	v_pk_mul_f32 v[102:103], v[102:103], v[116:117]
	v_pk_mul_f32 v[106:107], v[100:101], v[108:109]
	v_pk_mul_f32 v[100:101], v[98:99], v[120:121]
	v_cvt_pk_bf16_f32 v98, v102, v103
	v_cvt_pk_bf16_f32 v99, v104, v105
	v_cvt_pk_bf16_f32 v100, v100, v101
	v_cvt_pk_bf16_f32 v101, v106, v107
	global_store_dwordx4 v[118:119], v[98:101], off offset:256
	global_load_dwordx4 v[98:101], v[114:115], off
	v_lshlrev_b64 v[102:103], 12, v[110:111]
	v_lshl_add_u64 v[102:103], s[28:29], 0, v[102:103]
	v_lshl_add_u64 v[102:103], v[102:103], 0, v[130:131]
	v_lshl_add_u64 v[104:105], v[112:113], 0, s[34:35]
	s_waitcnt vmcnt(0)
	v_lshlrev_b32_e32 v106, 16, v98
	v_and_b32_e32 v107, 0xffff0000, v98
	v_lshlrev_b32_e32 v98, 16, v99
	v_and_b32_e32 v99, 0xffff0000, v99
	v_lshlrev_b32_e32 v108, 16, v100
	v_and_b32_e32 v109, 0xffff0000, v100
	v_lshlrev_b32_e32 v100, 16, v101
	v_and_b32_e32 v101, 0xffff0000, v101
	v_pk_mul_f32 v[96:97], v[96:97], v[98:99]
	v_pk_mul_f32 v[94:95], v[94:95], v[106:107]
	v_pk_mul_f32 v[98:99], v[92:93], v[100:101]
	v_pk_mul_f32 v[92:93], v[90:91], v[108:109]
	v_cvt_pk_bf16_f32 v90, v94, v95
	v_cvt_pk_bf16_f32 v91, v96, v97
	v_cvt_pk_bf16_f32 v92, v92, v93
	v_cvt_pk_bf16_f32 v93, v98, v99
	global_store_dwordx4 v[102:103], v[90:93], off
	global_load_dwordx4 v[90:93], v[104:105], off offset:256
	v_add_u32_e32 v94, 48, v132
	v_mad_i64_i32 v[96:97], s[0:1], v94, s47, v[134:135]
	v_lshl_add_u64 v[96:97], v[96:97], 0, v[130:131]
	v_add_co_u32_e32 v98, vcc, s72, v96
	v_ashrrev_i32_e32 v95, 31, v94
	s_nop 0
	v_addc_co_u32_e32 v99, vcc, 0, v97, vcc
	s_waitcnt vmcnt(0)
	v_lshlrev_b32_e32 v100, 16, v90
	v_and_b32_e32 v101, 0xffff0000, v90
	v_lshlrev_b32_e32 v90, 16, v91
	v_and_b32_e32 v91, 0xffff0000, v91
	v_lshlrev_b32_e32 v104, 16, v92
	v_and_b32_e32 v105, 0xffff0000, v92
	v_lshlrev_b32_e32 v92, 16, v93
	v_and_b32_e32 v93, 0xffff0000, v93
	v_pk_mul_f32 v[88:89], v[88:89], v[90:91]
	v_pk_mul_f32 v[86:87], v[86:87], v[100:101]
	v_pk_mul_f32 v[90:91], v[84:85], v[92:93]
	v_pk_mul_f32 v[84:85], v[82:83], v[104:105]
	v_cvt_pk_bf16_f32 v82, v86, v87
	v_cvt_pk_bf16_f32 v83, v88, v89
	v_cvt_pk_bf16_f32 v84, v84, v85
	v_cvt_pk_bf16_f32 v85, v90, v91
	global_store_dwordx4 v[102:103], v[82:85], off offset:256
	global_load_dwordx4 v[82:85], v[98:99], off
	v_lshlrev_b64 v[86:87], 12, v[94:95]
	v_lshl_add_u64 v[86:87], s[28:29], 0, v[86:87]
	v_lshl_add_u64 v[86:87], v[86:87], 0, v[130:131]
	v_lshl_add_u64 v[88:89], v[96:97], 0, s[34:35]
	s_waitcnt vmcnt(0)
	v_lshlrev_b32_e32 v90, 16, v82
	v_and_b32_e32 v91, 0xffff0000, v82
	v_lshlrev_b32_e32 v82, 16, v83
	v_and_b32_e32 v83, 0xffff0000, v83
	v_lshlrev_b32_e32 v92, 16, v84
	v_and_b32_e32 v93, 0xffff0000, v84
	v_lshlrev_b32_e32 v84, 16, v85
	v_and_b32_e32 v85, 0xffff0000, v85
	v_pk_mul_f32 v[80:81], v[80:81], v[82:83]
	v_pk_mul_f32 v[78:79], v[78:79], v[90:91]
	v_pk_mul_f32 v[82:83], v[76:77], v[84:85]
	v_pk_mul_f32 v[76:77], v[74:75], v[92:93]
	v_cvt_pk_bf16_f32 v74, v78, v79
	v_cvt_pk_bf16_f32 v75, v80, v81
	v_cvt_pk_bf16_f32 v76, v76, v77
	v_cvt_pk_bf16_f32 v77, v82, v83
	global_store_dwordx4 v[86:87], v[74:77], off
	global_load_dwordx4 v[74:77], v[88:89], off offset:256
	v_add_u32_e32 v78, 0x80, v132
	v_mad_i64_i32 v[80:81], s[0:1], v78, s47, v[134:135]
	v_lshl_add_u64 v[80:81], v[80:81], 0, v[130:131]
	v_add_co_u32_e32 v82, vcc, s72, v80
	v_ashrrev_i32_e32 v79, 31, v78
	s_nop 0
	v_addc_co_u32_e32 v83, vcc, 0, v81, vcc
	s_waitcnt vmcnt(0)
	v_lshlrev_b32_e32 v84, 16, v74
	v_and_b32_e32 v85, 0xffff0000, v74
	v_lshlrev_b32_e32 v74, 16, v75
	v_and_b32_e32 v75, 0xffff0000, v75
	v_lshlrev_b32_e32 v88, 16, v76
	v_and_b32_e32 v89, 0xffff0000, v76
	v_lshlrev_b32_e32 v76, 16, v77
	v_and_b32_e32 v77, 0xffff0000, v77
	v_pk_mul_f32 v[72:73], v[72:73], v[74:75]
	v_pk_mul_f32 v[70:71], v[70:71], v[84:85]
	v_pk_mul_f32 v[74:75], v[68:69], v[76:77]
	v_pk_mul_f32 v[68:69], v[66:67], v[88:89]
	v_cvt_pk_bf16_f32 v66, v70, v71
	v_cvt_pk_bf16_f32 v67, v72, v73
	v_cvt_pk_bf16_f32 v68, v68, v69
	v_cvt_pk_bf16_f32 v69, v74, v75
	global_store_dwordx4 v[86:87], v[66:69], off offset:256
	global_load_dwordx4 v[66:69], v[82:83], off
	v_lshlrev_b64 v[70:71], 12, v[78:79]
	v_lshl_add_u64 v[70:71], s[28:29], 0, v[70:71]
	v_lshl_add_u64 v[70:71], v[70:71], 0, v[130:131]
	v_lshl_add_u64 v[72:73], v[80:81], 0, s[34:35]
	s_waitcnt vmcnt(0)
	v_lshlrev_b32_e32 v74, 16, v66
	v_and_b32_e32 v75, 0xffff0000, v66
	v_lshlrev_b32_e32 v66, 16, v67
	v_and_b32_e32 v67, 0xffff0000, v67
	v_lshlrev_b32_e32 v76, 16, v68
	v_and_b32_e32 v77, 0xffff0000, v68
	v_lshlrev_b32_e32 v68, 16, v69
	v_and_b32_e32 v69, 0xffff0000, v69
	v_pk_mul_f32 v[64:65], v[64:65], v[66:67]
	v_pk_mul_f32 v[62:63], v[62:63], v[74:75]
	v_pk_mul_f32 v[66:67], v[60:61], v[68:69]
	v_pk_mul_f32 v[60:61], v[58:59], v[76:77]
	v_cvt_pk_bf16_f32 v58, v62, v63
	v_cvt_pk_bf16_f32 v59, v64, v65
	v_cvt_pk_bf16_f32 v60, v60, v61
	v_cvt_pk_bf16_f32 v61, v66, v67
	global_store_dwordx4 v[70:71], v[58:61], off
	global_load_dwordx4 v[58:61], v[72:73], off offset:256
	v_add_u32_e32 v62, 0x90, v132
	v_mad_i64_i32 v[64:65], s[0:1], v62, s47, v[134:135]
	v_lshl_add_u64 v[64:65], v[64:65], 0, v[130:131]
	v_add_co_u32_e32 v66, vcc, s72, v64
	v_ashrrev_i32_e32 v63, 31, v62
	s_nop 0
	v_addc_co_u32_e32 v67, vcc, 0, v65, vcc
	s_waitcnt vmcnt(0)
	v_lshlrev_b32_e32 v68, 16, v58
	v_and_b32_e32 v69, 0xffff0000, v58
	v_lshlrev_b32_e32 v58, 16, v59
	v_and_b32_e32 v59, 0xffff0000, v59
	v_lshlrev_b32_e32 v72, 16, v60
	v_and_b32_e32 v73, 0xffff0000, v60
	v_lshlrev_b32_e32 v60, 16, v61
	v_and_b32_e32 v61, 0xffff0000, v61
	v_pk_mul_f32 v[56:57], v[56:57], v[58:59]
	v_pk_mul_f32 v[54:55], v[54:55], v[68:69]
	v_pk_mul_f32 v[58:59], v[52:53], v[60:61]
	v_pk_mul_f32 v[52:53], v[50:51], v[72:73]
	v_cvt_pk_bf16_f32 v50, v54, v55
	v_cvt_pk_bf16_f32 v51, v56, v57
	v_cvt_pk_bf16_f32 v52, v52, v53
	v_cvt_pk_bf16_f32 v53, v58, v59
	global_store_dwordx4 v[70:71], v[50:53], off offset:256
	global_load_dwordx4 v[50:53], v[66:67], off
	v_lshlrev_b64 v[54:55], 12, v[62:63]
	v_lshl_add_u64 v[54:55], s[28:29], 0, v[54:55]
	v_lshl_add_u64 v[54:55], v[54:55], 0, v[130:131]
	v_lshl_add_u64 v[56:57], v[64:65], 0, s[34:35]
	s_waitcnt vmcnt(0)
	v_lshlrev_b32_e32 v58, 16, v50
	v_and_b32_e32 v59, 0xffff0000, v50
	v_lshlrev_b32_e32 v50, 16, v51
	v_and_b32_e32 v51, 0xffff0000, v51
	v_lshlrev_b32_e32 v60, 16, v52
	v_and_b32_e32 v61, 0xffff0000, v52
	v_lshlrev_b32_e32 v52, 16, v53
	v_and_b32_e32 v53, 0xffff0000, v53
	v_pk_mul_f32 v[48:49], v[48:49], v[50:51]
	v_pk_mul_f32 v[46:47], v[46:47], v[58:59]
	v_pk_mul_f32 v[50:51], v[44:45], v[52:53]
	v_pk_mul_f32 v[44:45], v[42:43], v[60:61]
	v_cvt_pk_bf16_f32 v42, v46, v47
	v_cvt_pk_bf16_f32 v43, v48, v49
	v_cvt_pk_bf16_f32 v44, v44, v45
	v_cvt_pk_bf16_f32 v45, v50, v51
	global_store_dwordx4 v[54:55], v[42:45], off
	global_load_dwordx4 v[42:45], v[56:57], off offset:256
	v_add_u32_e32 v46, 0xa0, v132
	v_mad_i64_i32 v[48:49], s[0:1], v46, s47, v[134:135]
	v_lshl_add_u64 v[48:49], v[48:49], 0, v[130:131]
	v_add_co_u32_e32 v50, vcc, s72, v48
	v_ashrrev_i32_e32 v47, 31, v46
	s_nop 0
	v_addc_co_u32_e32 v51, vcc, 0, v49, vcc
	s_waitcnt vmcnt(0)
	v_lshlrev_b32_e32 v52, 16, v42
	v_and_b32_e32 v53, 0xffff0000, v42
	v_lshlrev_b32_e32 v42, 16, v43
	v_and_b32_e32 v43, 0xffff0000, v43
	v_lshlrev_b32_e32 v56, 16, v44
	v_and_b32_e32 v57, 0xffff0000, v44
	v_lshlrev_b32_e32 v44, 16, v45
	v_and_b32_e32 v45, 0xffff0000, v45
	v_pk_mul_f32 v[40:41], v[40:41], v[42:43]
	v_pk_mul_f32 v[38:39], v[38:39], v[52:53]
	v_pk_mul_f32 v[42:43], v[36:37], v[44:45]
	v_pk_mul_f32 v[36:37], v[34:35], v[56:57]
	v_cvt_pk_bf16_f32 v34, v38, v39
	v_cvt_pk_bf16_f32 v35, v40, v41
	v_cvt_pk_bf16_f32 v36, v36, v37
	v_cvt_pk_bf16_f32 v37, v42, v43
	global_store_dwordx4 v[54:55], v[34:37], off offset:256
	global_load_dwordx4 v[34:37], v[50:51], off
	v_lshlrev_b64 v[38:39], 12, v[46:47]
	v_lshl_add_u64 v[38:39], s[28:29], 0, v[38:39]
	v_lshl_add_u64 v[38:39], v[38:39], 0, v[130:131]
	v_lshl_add_u64 v[40:41], v[48:49], 0, s[34:35]
	s_waitcnt vmcnt(0)
	v_lshlrev_b32_e32 v42, 16, v34
	v_and_b32_e32 v43, 0xffff0000, v34
	v_lshlrev_b32_e32 v34, 16, v35
	v_and_b32_e32 v35, 0xffff0000, v35
	v_lshlrev_b32_e32 v44, 16, v36
	v_and_b32_e32 v45, 0xffff0000, v36
	v_lshlrev_b32_e32 v36, 16, v37
	v_and_b32_e32 v37, 0xffff0000, v37
	v_pk_mul_f32 v[32:33], v[32:33], v[34:35]
	v_pk_mul_f32 v[30:31], v[30:31], v[42:43]
	v_pk_mul_f32 v[34:35], v[28:29], v[36:37]
	v_pk_mul_f32 v[28:29], v[26:27], v[44:45]
	v_cvt_pk_bf16_f32 v26, v30, v31
	v_cvt_pk_bf16_f32 v27, v32, v33
	v_cvt_pk_bf16_f32 v28, v28, v29
	v_cvt_pk_bf16_f32 v29, v34, v35
	global_store_dwordx4 v[38:39], v[26:29], off
	global_load_dwordx4 v[26:29], v[40:41], off offset:256
	v_add_u32_e32 v30, 0xb0, v132
	v_mad_i64_i32 v[32:33], s[0:1], v30, s47, v[134:135]
	v_lshl_add_u64 v[32:33], v[32:33], 0, v[130:131]
	v_add_co_u32_e32 v34, vcc, s72, v32
	v_ashrrev_i32_e32 v31, 31, v30
	s_nop 0
	v_addc_co_u32_e32 v35, vcc, 0, v33, vcc
	s_and_b64 vcc, exec, s[36:37]
	s_waitcnt vmcnt(0)
	v_lshlrev_b32_e32 v36, 16, v26
	v_and_b32_e32 v37, 0xffff0000, v26
	v_lshlrev_b32_e32 v26, 16, v27
	v_and_b32_e32 v27, 0xffff0000, v27
	v_lshlrev_b32_e32 v40, 16, v28
	v_and_b32_e32 v41, 0xffff0000, v28
	v_lshlrev_b32_e32 v28, 16, v29
	v_and_b32_e32 v29, 0xffff0000, v29
	v_pk_mul_f32 v[24:25], v[24:25], v[26:27]
	v_pk_mul_f32 v[22:23], v[22:23], v[36:37]
	v_pk_mul_f32 v[26:27], v[20:21], v[28:29]
	v_pk_mul_f32 v[20:21], v[18:19], v[40:41]
	v_cvt_pk_bf16_f32 v18, v22, v23
	v_cvt_pk_bf16_f32 v19, v24, v25
	v_cvt_pk_bf16_f32 v20, v20, v21
	v_cvt_pk_bf16_f32 v21, v26, v27
	global_store_dwordx4 v[38:39], v[18:21], off offset:256
	global_load_dwordx4 v[18:21], v[34:35], off
	v_lshlrev_b64 v[22:23], 12, v[30:31]
	v_lshl_add_u64 v[22:23], s[28:29], 0, v[22:23]
	v_lshl_add_u64 v[22:23], v[22:23], 0, v[130:131]
	v_lshl_add_u64 v[24:25], v[32:33], 0, s[34:35]
	s_waitcnt vmcnt(0)
	v_lshlrev_b32_e32 v26, 16, v18
	v_and_b32_e32 v27, 0xffff0000, v18
	v_lshlrev_b32_e32 v18, 16, v19
	v_and_b32_e32 v19, 0xffff0000, v19
	v_lshlrev_b32_e32 v28, 16, v20
	v_and_b32_e32 v29, 0xffff0000, v20
	v_lshlrev_b32_e32 v20, 16, v21
	v_and_b32_e32 v21, 0xffff0000, v21
	v_pk_mul_f32 v[16:17], v[16:17], v[18:19]
	v_pk_mul_f32 v[14:15], v[14:15], v[26:27]
	v_pk_mul_f32 v[18:19], v[12:13], v[20:21]
	v_pk_mul_f32 v[12:13], v[10:11], v[28:29]
	v_cvt_pk_bf16_f32 v10, v14, v15
	v_cvt_pk_bf16_f32 v11, v16, v17
	v_cvt_pk_bf16_f32 v12, v12, v13
	v_cvt_pk_bf16_f32 v13, v18, v19
	global_store_dwordx4 v[22:23], v[10:13], off
	global_load_dwordx4 v[10:13], v[24:25], off offset:256
	s_waitcnt vmcnt(0)
	v_lshlrev_b32_e32 v14, 16, v10
	v_and_b32_e32 v15, 0xffff0000, v10
	v_lshlrev_b32_e32 v10, 16, v11
	v_and_b32_e32 v11, 0xffff0000, v11
	v_lshlrev_b32_e32 v16, 16, v12
	v_and_b32_e32 v17, 0xffff0000, v12
	v_lshlrev_b32_e32 v12, 16, v13
	v_and_b32_e32 v13, 0xffff0000, v13
	v_pk_mul_f32 v[8:9], v[8:9], v[10:11]
	v_pk_mul_f32 v[6:7], v[6:7], v[14:15]
	v_pk_mul_f32 v[10:11], v[4:5], v[12:13]
	v_pk_mul_f32 v[4:5], v[2:3], v[16:17]
	v_cvt_pk_bf16_f32 v2, v6, v7
	v_cvt_pk_bf16_f32 v3, v8, v9
	v_cvt_pk_bf16_f32 v4, v4, v5
	v_cvt_pk_bf16_f32 v5, v10, v11
	global_store_dwordx4 v[22:23], v[2:5], off offset:256
	s_cbranch_vccz .LBB0_715
	s_waitcnt vmcnt(0)
	s_cmpk_gt_u32 s97, 0xff
	s_cbranch_scc1 .LBB0_732
	s_barrier

.LBB0_806:
	s_add_u32 s79, s26, 0x100
	s_addc_u32 s80, s27, 0
	s_ashr_i32 s9, s8, 31
	s_lshl_b64 s[12:13], s[8:9], 20
	s_add_u32 s12, s38, s12
	s_addc_u32 s13, s39, s13
	s_and_b64 s[30:31], s[44:45], exec
	s_cselect_b32 s9, s13, s27
	s_cselect_b32 s44, s12, s26
	s_add_u32 s26, s6, 0x80080
	s_addc_u32 s27, s7, 0
	v_lshl_add_u64 v[140:141], s[26:27], 0, v[136:137]
	v_lshl_add_u64 v[142:143], s[26:27], 0, v[138:139]
	s_mov_b32 s45, -2
	s_mov_b64 s[26:27], 0
	v_add_u32_e32 v224, 0x10000, v144
	v_add_u32_e32 v225, 0x14000, v144
	v_add_u32_e32 v226, 0x18000, v144
	v_add_u32_e32 v227, 0x1c000, v144
	v_readfirstlane_b32 s32, v148
	s_nop 3
	s_cmp_ge_u32 s32, 0x100
	s_cbranch_scc0 .Lprio_skip_2
	s_setprio 1
.Lprio_skip_2:
.LBB0_807:
	s_add_u32 s30, s6, s26
	s_addc_u32 s31, s7, s27
	s_add_u32 s30, s30, 0x100
	s_addc_u32 s31, s31, 0
	s_add_u32 s81, s79, s26
	s_addc_u32 s82, s80, s27
	s_add_i32 s83, 0, 0x10000
	ds_read_b128 v[152:155], v224
	ds_read_b128 v[156:159], v224 offset:1024
	ds_read_b128 v[160:163], v224 offset:2048
	ds_read_b128 v[164:167], v224 offset:3072
	s_cmpk_eq_i32 s26, 0xf00
	s_cselect_b32 s41, s23, s31
	s_cselect_b32 s40, s22, s30
	s_cselect_b32 s31, s9, s82
	s_cselect_b32 s30, s44, s81
	v_lshl_add_u64 v[146:147], v[140:141], 0, s[26:27]
	s_add_i32 m0, s61, 0xc000
	ds_read_b128 v[168:171], v145
	ds_read_b128 v[172:175], v145 offset:1024
	ds_read_b128 v[176:179], v145 offset:2048
	ds_read_b128 v[180:183], v145 offset:3072
	ds_read_b128 v[184:187], v145 offset:4096
	ds_read_b128 v[188:191], v145 offset:5120
	ds_read_b128 v[192:195], v145 offset:6144
	ds_read_b128 v[196:199], v145 offset:7168
	global_load_lds_dwordx4 v[146:147], off
	v_lshl_add_u64 v[146:147], v[142:143], 0, s[26:27]
	s_add_i32 m0, s61, 0xe000
	s_nop 0
	global_load_lds_dwordx4 v[146:147], off
	s_waitcnt lgkmcnt(8)
	s_barrier
	s_waitcnt lgkmcnt(7)
	v_mfma_f32_16x16x32_bf16 v[126:129], v[152:155], v[168:171], v[126:129]
	v_mfma_f32_16x16x32_bf16 v[122:125], v[160:163], v[168:171], v[122:125]
	s_waitcnt lgkmcnt(5)
	v_mfma_f32_16x16x32_bf16 v[110:113], v[152:155], v[176:179], v[110:113]
	v_mfma_f32_16x16x32_bf16 v[106:109], v[160:163], v[176:179], v[106:109]
	s_waitcnt lgkmcnt(3)
	v_mfma_f32_16x16x32_bf16 v[94:97], v[152:155], v[184:187], v[94:97]
	v_mfma_f32_16x16x32_bf16 v[90:93], v[160:163], v[184:187], v[90:93]
	s_waitcnt lgkmcnt(1)
	v_mfma_f32_16x16x32_bf16 v[78:81], v[152:155], v[192:195], v[78:81]
	v_mfma_f32_16x16x32_bf16 v[74:77], v[160:163], v[192:195], v[74:77]
	v_mfma_f32_16x16x32_bf16 v[126:129], v[156:159], v[172:175], v[126:129]
	v_mfma_f32_16x16x32_bf16 v[122:125], v[164:167], v[172:175], v[122:125]
	v_mfma_f32_16x16x32_bf16 v[110:113], v[156:159], v[180:183], v[110:113]
	v_mfma_f32_16x16x32_bf16 v[106:109], v[164:167], v[180:183], v[106:109]
	v_mfma_f32_16x16x32_bf16 v[94:97], v[156:159], v[188:191], v[94:97]
	v_mfma_f32_16x16x32_bf16 v[90:93], v[164:167], v[188:191], v[90:93]
	s_waitcnt lgkmcnt(0)
	v_mfma_f32_16x16x32_bf16 v[78:81], v[156:159], v[196:199], v[78:81]
	v_mfma_f32_16x16x32_bf16 v[74:77], v[164:167], v[196:199], v[74:77]
	s_barrier
	s_add_i32 s81, 0, 0x14000
	s_add_i32 s82, s83, s60
	ds_read_b128 v[200:203], v225
	ds_read_b128 v[204:207], v225 offset:1024
	ds_read_b128 v[216:219], v225 offset:2048
	ds_read_b128 v[220:223], v225 offset:3072
	s_mov_b32 m0, s82
	s_nop 0
	global_load_lds_dwordx4 v0, s[30:31]
	s_add_i32 m0, s82, 0x2000
	s_nop 0
	global_load_lds_dwordx4 v134, s[30:31]
	s_barrier
	s_waitcnt lgkmcnt(3)
	v_mfma_f32_16x16x32_bf16 v[118:121], v[200:203], v[168:171], v[118:121]
	s_waitcnt lgkmcnt(1)
	v_mfma_f32_16x16x32_bf16 v[114:117], v[216:219], v[168:171], v[114:117]
	v_mfma_f32_16x16x32_bf16 v[102:105], v[200:203], v[176:179], v[102:105]
	v_mfma_f32_16x16x32_bf16 v[98:101], v[216:219], v[176:179], v[98:101]
	v_mfma_f32_16x16x32_bf16 v[86:89], v[200:203], v[184:187], v[86:89]
	v_mfma_f32_16x16x32_bf16 v[82:85], v[216:219], v[184:187], v[82:85]
	v_mfma_f32_16x16x32_bf16 v[70:73], v[200:203], v[192:195], v[70:73]
	v_mfma_f32_16x16x32_bf16 v[66:69], v[216:219], v[192:195], v[66:69]
	v_mfma_f32_16x16x32_bf16 v[118:121], v[204:207], v[172:175], v[118:121]
	s_waitcnt lgkmcnt(0)
	v_mfma_f32_16x16x32_bf16 v[114:117], v[220:223], v[172:175], v[114:117]
	v_mfma_f32_16x16x32_bf16 v[102:105], v[204:207], v[180:183], v[102:105]
	v_mfma_f32_16x16x32_bf16 v[98:101], v[220:223], v[180:183], v[98:101]
	v_mfma_f32_16x16x32_bf16 v[86:89], v[204:207], v[188:191], v[86:89]
	v_mfma_f32_16x16x32_bf16 v[82:85], v[220:223], v[188:191], v[82:85]
	v_mfma_f32_16x16x32_bf16 v[70:73], v[204:207], v[196:199], v[70:73]
	v_mfma_f32_16x16x32_bf16 v[66:69], v[220:223], v[196:199], v[66:69]
	s_mov_b32 m0, s61
	s_add_u32 s98, s40, 0x80
	s_addc_u32 s99, s41, 0
	s_barrier
	ds_read_b128 v[168:171], v145 offset:16384
	ds_read_b128 v[172:175], v145 offset:17408
	ds_read_b128 v[176:179], v145 offset:18432
	ds_read_b128 v[180:183], v145 offset:19456
	ds_read_b128 v[184:187], v145 offset:20480
	ds_read_b128 v[188:191], v145 offset:21504
	ds_read_b128 v[192:195], v145 offset:22528
	global_load_lds_dwordx4 v0, s[40:41]
	s_mov_b32 m0, s64
	ds_read_b128 v[196:199], v145 offset:23552
	global_load_lds_dwordx4 v134, s[40:41]
	s_barrier
	s_waitcnt lgkmcnt(7)
	v_mfma_f32_16x16x32_bf16 v[62:65], v[152:155], v[168:171], v[62:65]
	v_mfma_f32_16x16x32_bf16 v[58:61], v[160:163], v[168:171], v[58:61]
	s_waitcnt lgkmcnt(5)
	v_mfma_f32_16x16x32_bf16 v[46:49], v[152:155], v[176:179], v[46:49]
	v_mfma_f32_16x16x32_bf16 v[42:45], v[160:163], v[176:179], v[42:45]
	s_waitcnt lgkmcnt(3)
	v_mfma_f32_16x16x32_bf16 v[30:33], v[152:155], v[184:187], v[30:33]
	v_mfma_f32_16x16x32_bf16 v[26:29], v[160:163], v[184:187], v[26:29]
	s_waitcnt lgkmcnt(1)
	v_mfma_f32_16x16x32_bf16 v[14:17], v[152:155], v[192:195], v[14:17]
	v_mfma_f32_16x16x32_bf16 v[10:13], v[160:163], v[192:195], v[10:13]
	v_mfma_f32_16x16x32_bf16 v[62:65], v[156:159], v[172:175], v[62:65]
	v_mfma_f32_16x16x32_bf16 v[58:61], v[164:167], v[172:175], v[58:61]
	v_mfma_f32_16x16x32_bf16 v[46:49], v[156:159], v[180:183], v[46:49]
	v_mfma_f32_16x16x32_bf16 v[42:45], v[164:167], v[180:183], v[42:45]
	v_mfma_f32_16x16x32_bf16 v[30:33], v[156:159], v[188:191], v[30:33]
	v_mfma_f32_16x16x32_bf16 v[26:29], v[164:167], v[188:191], v[26:29]
	s_waitcnt lgkmcnt(0)
	v_mfma_f32_16x16x32_bf16 v[14:17], v[156:159], v[196:199], v[14:17]
	v_mfma_f32_16x16x32_bf16 v[10:13], v[164:167], v[196:199], v[10:13]
	s_barrier
	s_add_i32 s81, s81, s60
	s_mov_b32 m0, s81
	s_add_u32 s82, s30, 0x80000
	s_addc_u32 s83, s31, 0
	global_load_lds_dwordx4 v0, s[82:83]
	s_add_i32 m0, s81, 0x2000
	s_nop 0
	global_load_lds_dwordx4 v134, s[82:83]
	s_waitcnt vmcnt(6)
	s_barrier
	v_mfma_f32_16x16x32_bf16 v[54:57], v[200:203], v[168:171], v[54:57]
	v_mfma_f32_16x16x32_bf16 v[50:53], v[216:219], v[168:171], v[50:53]
	v_mfma_f32_16x16x32_bf16 v[38:41], v[200:203], v[176:179], v[38:41]
	v_mfma_f32_16x16x32_bf16 v[34:37], v[216:219], v[176:179], v[34:37]
	v_mfma_f32_16x16x32_bf16 v[22:25], v[200:203], v[184:187], v[22:25]
	v_mfma_f32_16x16x32_bf16 v[18:21], v[216:219], v[184:187], v[18:21]
	v_mfma_f32_16x16x32_bf16 v[6:9], v[200:203], v[192:195], v[6:9]
	v_mfma_f32_16x16x32_bf16 v[2:5], v[216:219], v[192:195], v[2:5]
	v_mfma_f32_16x16x32_bf16 v[54:57], v[204:207], v[172:175], v[54:57]
	v_mfma_f32_16x16x32_bf16 v[50:53], v[220:223], v[172:175], v[50:53]
	v_mfma_f32_16x16x32_bf16 v[38:41], v[204:207], v[180:183], v[38:41]
	v_mfma_f32_16x16x32_bf16 v[34:37], v[220:223], v[180:183], v[34:37]
	v_mfma_f32_16x16x32_bf16 v[22:25], v[204:207], v[188:191], v[22:25]
	v_mfma_f32_16x16x32_bf16 v[18:21], v[220:223], v[188:191], v[18:21]
	v_mfma_f32_16x16x32_bf16 v[6:9], v[204:207], v[196:199], v[6:9]
	v_mfma_f32_16x16x32_bf16 v[2:5], v[220:223], v[196:199], v[2:5]
	s_add_i32 s81, 0, 0x18000
	s_barrier
	ds_read_b128 v[152:155], v226
	ds_read_b128 v[156:159], v226 offset:1024
	ds_read_b128 v[160:163], v226 offset:2048
	ds_read_b128 v[164:167], v226 offset:3072
	s_add_u32 s40, s40, 0x80000
	s_addc_u32 s41, s41, 0
	s_mov_b32 m0, s67
	ds_read_b128 v[168:171], v145 offset:32768
	ds_read_b128 v[172:175], v145 offset:33792
	ds_read_b128 v[176:179], v145 offset:34816
	ds_read_b128 v[180:183], v145 offset:35840
	ds_read_b128 v[184:187], v145 offset:36864
	ds_read_b128 v[188:191], v145 offset:37888
	ds_read_b128 v[192:195], v145 offset:38912
	global_load_lds_dwordx4 v0, s[40:41]
	s_mov_b32 m0, s68
	ds_read_b128 v[196:199], v145 offset:39936
	global_load_lds_dwordx4 v134, s[40:41]
	s_waitcnt lgkmcnt(8)
	s_barrier
	s_waitcnt lgkmcnt(7)
	v_mfma_f32_16x16x32_bf16 v[126:129], v[152:155], v[168:171], v[126:129]
	v_mfma_f32_16x16x32_bf16 v[122:125], v[160:163], v[168:171], v[122:125]
	s_waitcnt lgkmcnt(5)
	v_mfma_f32_16x16x32_bf16 v[110:113], v[152:155], v[176:179], v[110:113]
	v_mfma_f32_16x16x32_bf16 v[106:109], v[160:163], v[176:179], v[106:109]
	s_waitcnt lgkmcnt(3)
	v_mfma_f32_16x16x32_bf16 v[94:97], v[152:155], v[184:187], v[94:97]
	v_mfma_f32_16x16x32_bf16 v[90:93], v[160:163], v[184:187], v[90:93]
	s_waitcnt lgkmcnt(1)
	v_mfma_f32_16x16x32_bf16 v[78:81], v[152:155], v[192:195], v[78:81]
	v_mfma_f32_16x16x32_bf16 v[74:77], v[160:163], v[192:195], v[74:77]
	v_mfma_f32_16x16x32_bf16 v[126:129], v[156:159], v[172:175], v[126:129]
	v_mfma_f32_16x16x32_bf16 v[122:125], v[164:167], v[172:175], v[122:125]
	v_mfma_f32_16x16x32_bf16 v[110:113], v[156:159], v[180:183], v[110:113]
	v_mfma_f32_16x16x32_bf16 v[106:109], v[164:167], v[180:183], v[106:109]
	v_mfma_f32_16x16x32_bf16 v[94:97], v[156:159], v[188:191], v[94:97]
	v_mfma_f32_16x16x32_bf16 v[90:93], v[164:167], v[188:191], v[90:93]
	s_waitcnt lgkmcnt(0)
	v_mfma_f32_16x16x32_bf16 v[78:81], v[156:159], v[196:199], v[78:81]
	v_mfma_f32_16x16x32_bf16 v[74:77], v[164:167], v[196:199], v[74:77]
	s_barrier
	s_add_i32 s40, 0, 0x1c000
	s_add_i32 s41, s81, s60
	s_add_u32 s100, s30, 0x80
	s_addc_u32 s101, s31, 0
	s_mov_b32 m0, s41
	ds_read_b128 v[200:203], v227
	ds_read_b128 v[204:207], v227 offset:1024
	ds_read_b128 v[216:219], v227 offset:2048
	global_load_lds_dwordx4 v0, s[100:101]
	s_add_i32 m0, s41, 0x2000
	ds_read_b128 v[220:223], v227 offset:3072
	global_load_lds_dwordx4 v134, s[100:101]
	s_barrier
	s_waitcnt lgkmcnt(3)
	v_mfma_f32_16x16x32_bf16 v[118:121], v[200:203], v[168:171], v[118:121]
	s_waitcnt lgkmcnt(1)
	v_mfma_f32_16x16x32_bf16 v[114:117], v[216:219], v[168:171], v[114:117]
	v_mfma_f32_16x16x32_bf16 v[102:105], v[200:203], v[176:179], v[102:105]
	v_mfma_f32_16x16x32_bf16 v[98:101], v[216:219], v[176:179], v[98:101]
	v_mfma_f32_16x16x32_bf16 v[86:89], v[200:203], v[184:187], v[86:89]
	v_mfma_f32_16x16x32_bf16 v[82:85], v[216:219], v[184:187], v[82:85]
	v_mfma_f32_16x16x32_bf16 v[70:73], v[200:203], v[192:195], v[70:73]
	v_mfma_f32_16x16x32_bf16 v[66:69], v[216:219], v[192:195], v[66:69]
	v_mfma_f32_16x16x32_bf16 v[118:121], v[204:207], v[172:175], v[118:121]
	s_waitcnt lgkmcnt(0)
	v_mfma_f32_16x16x32_bf16 v[114:117], v[220:223], v[172:175], v[114:117]
	v_mfma_f32_16x16x32_bf16 v[102:105], v[204:207], v[180:183], v[102:105]
	v_mfma_f32_16x16x32_bf16 v[98:101], v[220:223], v[180:183], v[98:101]
	v_mfma_f32_16x16x32_bf16 v[86:89], v[204:207], v[188:191], v[86:89]
	v_mfma_f32_16x16x32_bf16 v[82:85], v[220:223], v[188:191], v[82:85]
	v_mfma_f32_16x16x32_bf16 v[70:73], v[204:207], v[196:199], v[70:73]
	v_mfma_f32_16x16x32_bf16 v[66:69], v[220:223], v[196:199], v[66:69]
	s_mov_b32 m0, s69
	s_barrier
	ds_read_b128 v[168:171], v145 offset:49152
	ds_read_b128 v[172:175], v145 offset:50176
	ds_read_b128 v[176:179], v145 offset:51200
	ds_read_b128 v[180:183], v145 offset:52224
	ds_read_b128 v[184:187], v145 offset:53248
	ds_read_b128 v[188:191], v145 offset:54272
	ds_read_b128 v[192:195], v145 offset:55296
	global_load_lds_dwordx4 v0, s[98:99]
	s_mov_b32 m0, s75
	ds_read_b128 v[196:199], v145 offset:56320
	global_load_lds_dwordx4 v134, s[98:99]
	s_barrier
	s_waitcnt lgkmcnt(7)
	v_mfma_f32_16x16x32_bf16 v[62:65], v[152:155], v[168:171], v[62:65]
	v_mfma_f32_16x16x32_bf16 v[58:61], v[160:163], v[168:171], v[58:61]
	s_waitcnt lgkmcnt(5)
	v_mfma_f32_16x16x32_bf16 v[46:49], v[152:155], v[176:179], v[46:49]
	v_mfma_f32_16x16x32_bf16 v[42:45], v[160:163], v[176:179], v[42:45]
	s_waitcnt lgkmcnt(3)
	v_mfma_f32_16x16x32_bf16 v[30:33], v[152:155], v[184:187], v[30:33]
	v_mfma_f32_16x16x32_bf16 v[26:29], v[160:163], v[184:187], v[26:29]
	s_waitcnt lgkmcnt(1)
	v_mfma_f32_16x16x32_bf16 v[14:17], v[152:155], v[192:195], v[14:17]
	v_mfma_f32_16x16x32_bf16 v[10:13], v[160:163], v[192:195], v[10:13]
	v_mfma_f32_16x16x32_bf16 v[62:65], v[156:159], v[172:175], v[62:65]
	v_mfma_f32_16x16x32_bf16 v[58:61], v[164:167], v[172:175], v[58:61]
	v_mfma_f32_16x16x32_bf16 v[46:49], v[156:159], v[180:183], v[46:49]
	v_mfma_f32_16x16x32_bf16 v[42:45], v[164:167], v[180:183], v[42:45]
	v_mfma_f32_16x16x32_bf16 v[30:33], v[156:159], v[188:191], v[30:33]
	v_mfma_f32_16x16x32_bf16 v[26:29], v[164:167], v[188:191], v[26:29]
	s_waitcnt lgkmcnt(0)
	v_mfma_f32_16x16x32_bf16 v[14:17], v[156:159], v[196:199], v[14:17]
	v_mfma_f32_16x16x32_bf16 v[10:13], v[164:167], v[196:199], v[10:13]
	s_barrier
	s_add_i32 s40, s40, s60
	s_mov_b32 m0, s40
	s_add_u32 s30, s30, 0x80080
	s_addc_u32 s31, s31, 0
	global_load_lds_dwordx4 v0, s[30:31]
	s_add_i32 m0, s40, 0x2000
	s_nop 0
	global_load_lds_dwordx4 v134, s[30:31]
	s_waitcnt vmcnt(6)
	s_barrier
	v_mfma_f32_16x16x32_bf16 v[54:57], v[200:203], v[168:171], v[54:57]
	v_mfma_f32_16x16x32_bf16 v[50:53], v[216:219], v[168:171], v[50:53]
	v_mfma_f32_16x16x32_bf16 v[38:41], v[200:203], v[176:179], v[38:41]
	v_mfma_f32_16x16x32_bf16 v[34:37], v[216:219], v[176:179], v[34:37]
	v_mfma_f32_16x16x32_bf16 v[22:25], v[200:203], v[184:187], v[22:25]
	v_mfma_f32_16x16x32_bf16 v[18:21], v[216:219], v[184:187], v[18:21]
	v_mfma_f32_16x16x32_bf16 v[6:9], v[200:203], v[192:195], v[6:9]
	v_mfma_f32_16x16x32_bf16 v[2:5], v[216:219], v[192:195], v[2:5]
	v_mfma_f32_16x16x32_bf16 v[54:57], v[204:207], v[172:175], v[54:57]
	v_mfma_f32_16x16x32_bf16 v[50:53], v[220:223], v[172:175], v[50:53]
	v_mfma_f32_16x16x32_bf16 v[38:41], v[204:207], v[180:183], v[38:41]
	v_mfma_f32_16x16x32_bf16 v[34:37], v[220:223], v[180:183], v[34:37]
	v_mfma_f32_16x16x32_bf16 v[22:25], v[204:207], v[188:191], v[22:25]
	v_mfma_f32_16x16x32_bf16 v[18:21], v[220:223], v[188:191], v[18:21]
	v_mfma_f32_16x16x32_bf16 v[6:9], v[204:207], v[196:199], v[6:9]
	v_mfma_f32_16x16x32_bf16 v[2:5], v[220:223], v[196:199], v[2:5]
	s_add_i32 s45, s45, 2
	s_add_u32 s26, s26, 0x100
	s_addc_u32 s27, s27, 0
	s_cmp_gt_u32 s45, 29
	s_barrier
	s_cbranch_scc0 .LBB0_807
	s_setprio 0
	s_add_u32 s26, s79, 0xffffff00
	s_addc_u32 s27, s80, -1
	s_and_b64 vcc, exec, s[42:43]
	s_cbranch_vccnz .LBB0_796
	v_mov_b32_e32 v2, 0
	s_mov_b32 s14, s8
	s_mov_b32 s50, s77
	s_mov_b64 s[6:7], s[22:23]
	s_mov_b32 s76, s78
	v_mov_b32_e32 v3, v2
	v_mov_b32_e32 v4, v2
	v_mov_b32_e32 v5, v2
	v_mov_b32_e32 v6, v2
	v_mov_b32_e32 v7, v2
	v_mov_b32_e32 v8, v2
	v_mov_b32_e32 v9, v2
	v_mov_b32_e32 v18, v2
	v_mov_b32_e32 v19, v2
	v_mov_b32_e32 v20, v2
	v_mov_b32_e32 v21, v2
	v_mov_b32_e32 v22, v2
	v_mov_b32_e32 v23, v2
	v_mov_b32_e32 v24, v2
	v_mov_b32_e32 v25, v2
	v_mov_b32_e32 v34, v2
	v_mov_b32_e32 v35, v2
	v_mov_b32_e32 v36, v2
	v_mov_b32_e32 v37, v2
	v_mov_b32_e32 v38, v2
	v_mov_b32_e32 v39, v2
	v_mov_b32_e32 v40, v2
	v_mov_b32_e32 v41, v2
	v_mov_b32_e32 v50, v2
	v_mov_b32_e32 v51, v2
	v_mov_b32_e32 v52, v2
	v_mov_b32_e32 v53, v2
	v_mov_b32_e32 v54, v2
	v_mov_b32_e32 v55, v2
	v_mov_b32_e32 v56, v2
	v_mov_b32_e32 v57, v2
	v_mov_b32_e32 v10, v2
	v_mov_b32_e32 v11, v2
	v_mov_b32_e32 v12, v2
	v_mov_b32_e32 v13, v2
	v_mov_b32_e32 v14, v2
	v_mov_b32_e32 v15, v2
	v_mov_b32_e32 v16, v2
	v_mov_b32_e32 v17, v2
	v_mov_b32_e32 v26, v2
	v_mov_b32_e32 v27, v2
	v_mov_b32_e32 v28, v2
	v_mov_b32_e32 v29, v2
	v_mov_b32_e32 v30, v2
	v_mov_b32_e32 v31, v2
	v_mov_b32_e32 v32, v2
	v_mov_b32_e32 v33, v2
	v_mov_b32_e32 v42, v2
	v_mov_b32_e32 v43, v2
	v_mov_b32_e32 v44, v2
	v_mov_b32_e32 v45, v2
	v_mov_b32_e32 v46, v2
	v_mov_b32_e32 v47, v2
	v_mov_b32_e32 v48, v2
	v_mov_b32_e32 v49, v2
	v_mov_b32_e32 v58, v2
	v_mov_b32_e32 v59, v2
	v_mov_b32_e32 v60, v2
	v_mov_b32_e32 v61, v2
	v_mov_b32_e32 v62, v2
	v_mov_b32_e32 v63, v2
	v_mov_b32_e32 v64, v2
	v_mov_b32_e32 v65, v2
	v_mov_b32_e32 v66, v2
	v_mov_b32_e32 v67, v2
	v_mov_b32_e32 v68, v2
	v_mov_b32_e32 v69, v2
	v_mov_b32_e32 v70, v2
	v_mov_b32_e32 v71, v2
	v_mov_b32_e32 v72, v2
	v_mov_b32_e32 v73, v2
	v_mov_b32_e32 v82, v2
	v_mov_b32_e32 v83, v2
	v_mov_b32_e32 v84, v2
	v_mov_b32_e32 v85, v2
	v_mov_b32_e32 v86, v2
	v_mov_b32_e32 v87, v2
	v_mov_b32_e32 v88, v2
	v_mov_b32_e32 v89, v2
	v_mov_b32_e32 v98, v2
	v_mov_b32_e32 v99, v2
	v_mov_b32_e32 v100, v2
	v_mov_b32_e32 v101, v2
	v_mov_b32_e32 v102, v2
	v_mov_b32_e32 v103, v2
	v_mov_b32_e32 v104, v2
	v_mov_b32_e32 v105, v2
	v_mov_b32_e32 v114, v2
	v_mov_b32_e32 v115, v2
	v_mov_b32_e32 v116, v2
	v_mov_b32_e32 v117, v2
	v_mov_b32_e32 v118, v2
	v_mov_b32_e32 v119, v2
	v_mov_b32_e32 v120, v2
	v_mov_b32_e32 v121, v2
	v_mov_b32_e32 v74, v2
	v_mov_b32_e32 v75, v2
	v_mov_b32_e32 v76, v2
	v_mov_b32_e32 v77, v2
	v_mov_b32_e32 v78, v2
	v_mov_b32_e32 v79, v2
	v_mov_b32_e32 v80, v2
	v_mov_b32_e32 v81, v2
	v_mov_b32_e32 v90, v2
	v_mov_b32_e32 v91, v2
	v_mov_b32_e32 v92, v2
	v_mov_b32_e32 v93, v2
	v_mov_b32_e32 v94, v2
	v_mov_b32_e32 v95, v2
	v_mov_b32_e32 v96, v2
	v_mov_b32_e32 v97, v2
	v_mov_b32_e32 v106, v2
	v_mov_b32_e32 v107, v2
	v_mov_b32_e32 v108, v2
	v_mov_b32_e32 v109, v2
	v_mov_b32_e32 v110, v2
	v_mov_b32_e32 v111, v2
	v_mov_b32_e32 v112, v2
	v_mov_b32_e32 v113, v2
	v_mov_b32_e32 v122, v2
	v_mov_b32_e32 v123, v2
	v_mov_b32_e32 v124, v2
	v_mov_b32_e32 v125, v2
	v_mov_b32_e32 v126, v2
	v_mov_b32_e32 v127, v2
	v_mov_b32_e32 v128, v2
	v_mov_b32_e32 v129, v2
	s_andn2_b64 vcc, exec, s[0:1]
	s_cbranch_vccnz .LBB0_797

.LBB0_938:
	s_ashr_i32 s23, s22, 31
	s_lshl_b64 s[28:29], s[22:23], 20
	s_add_u32 s28, s8, s28
	s_addc_u32 s29, s9, s29
	s_and_b64 s[38:39], s[42:43], exec
	s_cselect_b32 s23, s29, s37
	s_cselect_b32 s42, s28, s36
	s_add_u32 s30, s30, 0x80080
	s_addc_u32 s31, s31, 0
	s_add_u32 s43, s36, 0x100
	v_mov_b32_e32 v2, 0
	s_addc_u32 s67, s37, 0
	s_mov_b32 s68, -2
	v_mov_b32_e32 v3, v2
	v_mov_b32_e32 v4, v2
	v_mov_b32_e32 v5, v2
	v_mov_b32_e32 v6, v2
	v_mov_b32_e32 v7, v2
	v_mov_b32_e32 v8, v2
	v_mov_b32_e32 v9, v2
	v_mov_b32_e32 v10, v2
	v_mov_b32_e32 v11, v2
	v_mov_b32_e32 v12, v2
	v_mov_b32_e32 v13, v2
	v_mov_b32_e32 v14, v2
	v_mov_b32_e32 v15, v2
	v_mov_b32_e32 v16, v2
	v_mov_b32_e32 v17, v2
	v_mov_b32_e32 v26, v2
	v_mov_b32_e32 v27, v2
	v_mov_b32_e32 v28, v2
	v_mov_b32_e32 v29, v2
	v_mov_b32_e32 v30, v2
	v_mov_b32_e32 v31, v2
	v_mov_b32_e32 v32, v2
	v_mov_b32_e32 v33, v2
	v_mov_b32_e32 v42, v2
	v_mov_b32_e32 v43, v2
	v_mov_b32_e32 v44, v2
	v_mov_b32_e32 v45, v2
	v_mov_b32_e32 v46, v2
	v_mov_b32_e32 v47, v2
	v_mov_b32_e32 v48, v2
	v_mov_b32_e32 v49, v2
	v_mov_b32_e32 v18, v2
	v_mov_b32_e32 v19, v2
	v_mov_b32_e32 v20, v2
	v_mov_b32_e32 v21, v2
	v_mov_b32_e32 v22, v2
	v_mov_b32_e32 v23, v2
	v_mov_b32_e32 v24, v2
	v_mov_b32_e32 v25, v2
	v_mov_b32_e32 v34, v2
	v_mov_b32_e32 v35, v2
	v_mov_b32_e32 v36, v2
	v_mov_b32_e32 v37, v2
	v_mov_b32_e32 v38, v2
	v_mov_b32_e32 v39, v2
	v_mov_b32_e32 v40, v2
	v_mov_b32_e32 v41, v2
	v_mov_b32_e32 v50, v2
	v_mov_b32_e32 v51, v2
	v_mov_b32_e32 v52, v2
	v_mov_b32_e32 v53, v2
	v_mov_b32_e32 v54, v2
	v_mov_b32_e32 v55, v2
	v_mov_b32_e32 v56, v2
	v_mov_b32_e32 v57, v2
	v_mov_b32_e32 v58, v2
	v_mov_b32_e32 v59, v2
	v_mov_b32_e32 v60, v2
	v_mov_b32_e32 v61, v2
	v_mov_b32_e32 v62, v2
	v_mov_b32_e32 v63, v2
	v_mov_b32_e32 v64, v2
	v_mov_b32_e32 v65, v2
	v_mov_b32_e32 v66, v2
	v_mov_b32_e32 v67, v2
	v_mov_b32_e32 v68, v2
	v_mov_b32_e32 v69, v2
	v_mov_b32_e32 v70, v2
	v_mov_b32_e32 v71, v2
	v_mov_b32_e32 v72, v2
	v_mov_b32_e32 v73, v2
	v_mov_b32_e32 v74, v2
	v_mov_b32_e32 v75, v2
	v_mov_b32_e32 v76, v2
	v_mov_b32_e32 v77, v2
	v_mov_b32_e32 v78, v2
	v_mov_b32_e32 v79, v2
	v_mov_b32_e32 v80, v2
	v_mov_b32_e32 v81, v2
	v_mov_b32_e32 v90, v2
	v_mov_b32_e32 v91, v2
	v_mov_b32_e32 v92, v2
	v_mov_b32_e32 v93, v2
	v_mov_b32_e32 v94, v2
	v_mov_b32_e32 v95, v2
	v_mov_b32_e32 v96, v2
	v_mov_b32_e32 v97, v2
	v_mov_b32_e32 v106, v2
	v_mov_b32_e32 v107, v2
	v_mov_b32_e32 v108, v2
	v_mov_b32_e32 v109, v2
	v_mov_b32_e32 v110, v2
	v_mov_b32_e32 v111, v2
	v_mov_b32_e32 v112, v2
	v_mov_b32_e32 v113, v2
	v_mov_b32_e32 v82, v2
	v_mov_b32_e32 v83, v2
	v_mov_b32_e32 v84, v2
	v_mov_b32_e32 v85, v2
	v_mov_b32_e32 v86, v2
	v_mov_b32_e32 v87, v2
	v_mov_b32_e32 v88, v2
	v_mov_b32_e32 v89, v2
	v_mov_b32_e32 v98, v2
	v_mov_b32_e32 v99, v2
	v_mov_b32_e32 v100, v2
	v_mov_b32_e32 v101, v2
	v_mov_b32_e32 v102, v2
	v_mov_b32_e32 v103, v2
	v_mov_b32_e32 v104, v2
	v_mov_b32_e32 v105, v2
	v_mov_b32_e32 v114, v2
	v_mov_b32_e32 v115, v2
	v_mov_b32_e32 v116, v2
	v_mov_b32_e32 v117, v2
	v_mov_b32_e32 v118, v2
	v_mov_b32_e32 v119, v2
	v_mov_b32_e32 v120, v2
	v_mov_b32_e32 v121, v2
	v_mov_b32_e32 v122, v2
	v_mov_b32_e32 v123, v2
	v_mov_b32_e32 v124, v2
	v_mov_b32_e32 v125, v2
	v_mov_b32_e32 v126, v2
	v_mov_b32_e32 v127, v2
	v_mov_b32_e32 v128, v2
	v_mov_b32_e32 v129, v2
	v_add_u32_e32 v224, 0x10000, v140
	v_add_u32_e32 v225, 0x14000, v140
	v_add_u32_e32 v226, 0x18000, v140
	v_add_u32_e32 v227, 0x1c000, v140
	v_readfirstlane_b32 s32, v148
	s_nop 3
	s_cmp_ge_u32 s32, 0x100
	s_cbranch_scc0 .Lprio_skip_3
	s_setprio 1
.Lprio_skip_3:
.LBB0_939:
	s_add_u32 s36, s30, 0xfff80080
	s_addc_u32 s37, s31, -1
	s_add_i32 s69, 0, 0x10000
	ds_read_b128 v[142:145], v224
	ds_read_b128 v[152:155], v224 offset:1024
	ds_read_b128 v[156:159], v224 offset:2048
	ds_read_b128 v[160:163], v224 offset:3072
	s_cmp_eq_u32 s68, 28
	s_cselect_b32 s39, s27, s37
	s_cselect_b32 s38, s26, s36
	s_cselect_b32 s37, s23, s67
	s_cselect_b32 s36, s42, s43
	s_add_i32 m0, s41, 0xc000
	ds_read_b128 v[164:167], v141
	ds_read_b128 v[168:171], v141 offset:1024
	ds_read_b128 v[172:175], v141 offset:2048
	ds_read_b128 v[176:179], v141 offset:3072
	ds_read_b128 v[180:183], v141 offset:4096
	ds_read_b128 v[184:187], v141 offset:5120
	ds_read_b128 v[188:191], v141 offset:6144
	global_load_lds_dwordx4 v136, s[30:31]
	s_add_i32 m0, s41, 0xe000
	ds_read_b128 v[192:195], v141 offset:7168
	global_load_lds_dwordx4 v138, s[30:31]
	s_waitcnt lgkmcnt(8)
	s_barrier
	s_waitcnt lgkmcnt(7)
	v_mfma_f32_16x16x32_bf16 v[126:129], v[142:145], v[164:167], v[126:129]
	v_mfma_f32_16x16x32_bf16 v[122:125], v[156:159], v[164:167], v[122:125]
	s_waitcnt lgkmcnt(5)
	v_mfma_f32_16x16x32_bf16 v[118:121], v[142:145], v[172:175], v[118:121]
	v_mfma_f32_16x16x32_bf16 v[114:117], v[156:159], v[172:175], v[114:117]
	s_waitcnt lgkmcnt(3)
	v_mfma_f32_16x16x32_bf16 v[102:105], v[142:145], v[180:183], v[102:105]
	v_mfma_f32_16x16x32_bf16 v[98:101], v[156:159], v[180:183], v[98:101]
	s_waitcnt lgkmcnt(1)
	v_mfma_f32_16x16x32_bf16 v[86:89], v[142:145], v[188:191], v[86:89]
	v_mfma_f32_16x16x32_bf16 v[82:85], v[156:159], v[188:191], v[82:85]
	v_mfma_f32_16x16x32_bf16 v[126:129], v[152:155], v[168:171], v[126:129]
	v_mfma_f32_16x16x32_bf16 v[122:125], v[160:163], v[168:171], v[122:125]
	v_mfma_f32_16x16x32_bf16 v[118:121], v[152:155], v[176:179], v[118:121]
	v_mfma_f32_16x16x32_bf16 v[114:117], v[160:163], v[176:179], v[114:117]
	v_mfma_f32_16x16x32_bf16 v[102:105], v[152:155], v[184:187], v[102:105]
	v_mfma_f32_16x16x32_bf16 v[98:101], v[160:163], v[184:187], v[98:101]
	s_waitcnt lgkmcnt(0)
	v_mfma_f32_16x16x32_bf16 v[86:89], v[152:155], v[192:195], v[86:89]
	v_mfma_f32_16x16x32_bf16 v[82:85], v[160:163], v[192:195], v[82:85]
	s_barrier
	s_add_i32 s75, 0, 0x14000
	s_add_i32 s69, s69, s40
	ds_read_b128 v[196:199], v225
	ds_read_b128 v[200:203], v225 offset:1024
	ds_read_b128 v[204:207], v225 offset:2048
	ds_read_b128 v[216:219], v225 offset:3072
	s_mov_b32 m0, s69
	s_nop 0
	global_load_lds_dwordx4 v0, s[36:37]
	s_add_i32 m0, s69, 0x2000
	s_nop 0
	global_load_lds_dwordx4 v130, s[36:37]
	s_barrier
	s_waitcnt lgkmcnt(3)
	v_mfma_f32_16x16x32_bf16 v[110:113], v[196:199], v[164:167], v[110:113]
	s_waitcnt lgkmcnt(1)
	v_mfma_f32_16x16x32_bf16 v[106:109], v[204:207], v[164:167], v[106:109]
	v_mfma_f32_16x16x32_bf16 v[94:97], v[196:199], v[172:175], v[94:97]
	v_mfma_f32_16x16x32_bf16 v[90:93], v[204:207], v[172:175], v[90:93]
	v_mfma_f32_16x16x32_bf16 v[78:81], v[196:199], v[180:183], v[78:81]
	v_mfma_f32_16x16x32_bf16 v[74:77], v[204:207], v[180:183], v[74:77]
	v_mfma_f32_16x16x32_bf16 v[70:73], v[196:199], v[188:191], v[70:73]
	v_mfma_f32_16x16x32_bf16 v[66:69], v[204:207], v[188:191], v[66:69]
	v_mfma_f32_16x16x32_bf16 v[110:113], v[200:203], v[168:171], v[110:113]
	s_waitcnt lgkmcnt(0)
	v_mfma_f32_16x16x32_bf16 v[106:109], v[216:219], v[168:171], v[106:109]
	v_mfma_f32_16x16x32_bf16 v[94:97], v[200:203], v[176:179], v[94:97]
	v_mfma_f32_16x16x32_bf16 v[90:93], v[216:219], v[176:179], v[90:93]
	v_mfma_f32_16x16x32_bf16 v[78:81], v[200:203], v[184:187], v[78:81]
	v_mfma_f32_16x16x32_bf16 v[74:77], v[216:219], v[184:187], v[74:77]
	v_mfma_f32_16x16x32_bf16 v[70:73], v[200:203], v[192:195], v[70:73]
	v_mfma_f32_16x16x32_bf16 v[66:69], v[216:219], v[192:195], v[66:69]
	s_mov_b32 m0, s41
	s_add_u32 s98, s38, 0x80
	s_addc_u32 s99, s39, 0
	s_barrier
	ds_read_b128 v[164:167], v141 offset:16384
	ds_read_b128 v[168:171], v141 offset:17408
	ds_read_b128 v[172:175], v141 offset:18432
	ds_read_b128 v[176:179], v141 offset:19456
	ds_read_b128 v[180:183], v141 offset:20480
	ds_read_b128 v[184:187], v141 offset:21504
	ds_read_b128 v[188:191], v141 offset:22528
	global_load_lds_dwordx4 v134, s[38:39]
	s_mov_b32 m0, s44
	ds_read_b128 v[192:195], v141 offset:23552
	global_load_lds_dwordx4 v132, s[38:39]
	s_barrier
	s_waitcnt lgkmcnt(7)
	v_mfma_f32_16x16x32_bf16 v[62:65], v[142:145], v[164:167], v[62:65]
	v_mfma_f32_16x16x32_bf16 v[58:61], v[156:159], v[164:167], v[58:61]
	s_waitcnt lgkmcnt(5)
	v_mfma_f32_16x16x32_bf16 v[54:57], v[142:145], v[172:175], v[54:57]
	v_mfma_f32_16x16x32_bf16 v[50:53], v[156:159], v[172:175], v[50:53]
	s_waitcnt lgkmcnt(3)
	v_mfma_f32_16x16x32_bf16 v[38:41], v[142:145], v[180:183], v[38:41]
	v_mfma_f32_16x16x32_bf16 v[34:37], v[156:159], v[180:183], v[34:37]
	s_waitcnt lgkmcnt(1)
	v_mfma_f32_16x16x32_bf16 v[22:25], v[142:145], v[188:191], v[22:25]
	v_mfma_f32_16x16x32_bf16 v[18:21], v[156:159], v[188:191], v[18:21]
	v_mfma_f32_16x16x32_bf16 v[62:65], v[152:155], v[168:171], v[62:65]
	v_mfma_f32_16x16x32_bf16 v[58:61], v[160:163], v[168:171], v[58:61]
	v_mfma_f32_16x16x32_bf16 v[54:57], v[152:155], v[176:179], v[54:57]
	v_mfma_f32_16x16x32_bf16 v[50:53], v[160:163], v[176:179], v[50:53]
	v_mfma_f32_16x16x32_bf16 v[38:41], v[152:155], v[184:187], v[38:41]
	v_mfma_f32_16x16x32_bf16 v[34:37], v[160:163], v[184:187], v[34:37]
	s_waitcnt lgkmcnt(0)
	v_mfma_f32_16x16x32_bf16 v[22:25], v[152:155], v[192:195], v[22:25]
	v_mfma_f32_16x16x32_bf16 v[18:21], v[160:163], v[192:195], v[18:21]
	s_barrier
	s_add_i32 s69, s75, s40
	s_mov_b32 m0, s69
	s_add_u32 s76, s36, 0x80000
	s_addc_u32 s77, s37, 0
	global_load_lds_dwordx4 v0, s[76:77]
	s_add_i32 m0, s69, 0x2000
	s_nop 0
	global_load_lds_dwordx4 v130, s[76:77]
	s_waitcnt vmcnt(6)
	s_barrier
	v_mfma_f32_16x16x32_bf16 v[46:49], v[196:199], v[164:167], v[46:49]
	v_mfma_f32_16x16x32_bf16 v[42:45], v[204:207], v[164:167], v[42:45]
	v_mfma_f32_16x16x32_bf16 v[30:33], v[196:199], v[172:175], v[30:33]
	v_mfma_f32_16x16x32_bf16 v[26:29], v[204:207], v[172:175], v[26:29]
	v_mfma_f32_16x16x32_bf16 v[14:17], v[196:199], v[180:183], v[14:17]
	v_mfma_f32_16x16x32_bf16 v[10:13], v[204:207], v[180:183], v[10:13]
	v_mfma_f32_16x16x32_bf16 v[6:9], v[196:199], v[188:191], v[6:9]
	v_mfma_f32_16x16x32_bf16 v[2:5], v[204:207], v[188:191], v[2:5]
	v_mfma_f32_16x16x32_bf16 v[46:49], v[200:203], v[168:171], v[46:49]
	v_mfma_f32_16x16x32_bf16 v[42:45], v[216:219], v[168:171], v[42:45]
	v_mfma_f32_16x16x32_bf16 v[30:33], v[200:203], v[176:179], v[30:33]
	v_mfma_f32_16x16x32_bf16 v[26:29], v[216:219], v[176:179], v[26:29]
	v_mfma_f32_16x16x32_bf16 v[14:17], v[200:203], v[184:187], v[14:17]
	v_mfma_f32_16x16x32_bf16 v[10:13], v[216:219], v[184:187], v[10:13]
	v_mfma_f32_16x16x32_bf16 v[6:9], v[200:203], v[192:195], v[6:9]
	v_mfma_f32_16x16x32_bf16 v[2:5], v[216:219], v[192:195], v[2:5]
	s_add_i32 s69, 0, 0x18000
	s_barrier
	ds_read_b128 v[142:145], v226
	ds_read_b128 v[152:155], v226 offset:1024
	ds_read_b128 v[156:159], v226 offset:2048
	ds_read_b128 v[160:163], v226 offset:3072
	s_add_u32 s38, s38, 0x80000
	s_addc_u32 s39, s39, 0
	s_mov_b32 m0, s45
	ds_read_b128 v[164:167], v141 offset:32768
	ds_read_b128 v[168:171], v141 offset:33792
	ds_read_b128 v[172:175], v141 offset:34816
	ds_read_b128 v[176:179], v141 offset:35840
	ds_read_b128 v[180:183], v141 offset:36864
	ds_read_b128 v[184:187], v141 offset:37888
	ds_read_b128 v[188:191], v141 offset:38912
	global_load_lds_dwordx4 v134, s[38:39]
	s_mov_b32 m0, s50
	ds_read_b128 v[192:195], v141 offset:39936
	global_load_lds_dwordx4 v132, s[38:39]
	s_waitcnt lgkmcnt(8)
	s_barrier
	s_waitcnt lgkmcnt(7)
	v_mfma_f32_16x16x32_bf16 v[126:129], v[142:145], v[164:167], v[126:129]
	v_mfma_f32_16x16x32_bf16 v[122:125], v[156:159], v[164:167], v[122:125]
	s_waitcnt lgkmcnt(5)
	v_mfma_f32_16x16x32_bf16 v[118:121], v[142:145], v[172:175], v[118:121]
	v_mfma_f32_16x16x32_bf16 v[114:117], v[156:159], v[172:175], v[114:117]
	s_waitcnt lgkmcnt(3)
	v_mfma_f32_16x16x32_bf16 v[102:105], v[142:145], v[180:183], v[102:105]
	v_mfma_f32_16x16x32_bf16 v[98:101], v[156:159], v[180:183], v[98:101]
	s_waitcnt lgkmcnt(1)
	v_mfma_f32_16x16x32_bf16 v[86:89], v[142:145], v[188:191], v[86:89]
	v_mfma_f32_16x16x32_bf16 v[82:85], v[156:159], v[188:191], v[82:85]
	v_mfma_f32_16x16x32_bf16 v[126:129], v[152:155], v[168:171], v[126:129]
	v_mfma_f32_16x16x32_bf16 v[122:125], v[160:163], v[168:171], v[122:125]
	v_mfma_f32_16x16x32_bf16 v[118:121], v[152:155], v[176:179], v[118:121]
	v_mfma_f32_16x16x32_bf16 v[114:117], v[160:163], v[176:179], v[114:117]
	v_mfma_f32_16x16x32_bf16 v[102:105], v[152:155], v[184:187], v[102:105]
	v_mfma_f32_16x16x32_bf16 v[98:101], v[160:163], v[184:187], v[98:101]
	s_waitcnt lgkmcnt(0)
	v_mfma_f32_16x16x32_bf16 v[86:89], v[152:155], v[192:195], v[86:89]
	v_mfma_f32_16x16x32_bf16 v[82:85], v[160:163], v[192:195], v[82:85]
	s_barrier
	s_add_i32 s38, 0, 0x1c000
	s_add_i32 s39, s69, s40
	s_add_u32 s100, s36, 0x80
	s_addc_u32 s101, s37, 0
	s_mov_b32 m0, s39
	ds_read_b128 v[196:199], v227
	ds_read_b128 v[200:203], v227 offset:1024
	ds_read_b128 v[204:207], v227 offset:2048
	global_load_lds_dwordx4 v0, s[100:101]
	s_add_i32 m0, s39, 0x2000
	ds_read_b128 v[216:219], v227 offset:3072
	global_load_lds_dwordx4 v130, s[100:101]
	s_barrier
	s_waitcnt lgkmcnt(3)
	v_mfma_f32_16x16x32_bf16 v[110:113], v[196:199], v[164:167], v[110:113]
	s_waitcnt lgkmcnt(1)
	v_mfma_f32_16x16x32_bf16 v[106:109], v[204:207], v[164:167], v[106:109]
	v_mfma_f32_16x16x32_bf16 v[94:97], v[196:199], v[172:175], v[94:97]
	v_mfma_f32_16x16x32_bf16 v[90:93], v[204:207], v[172:175], v[90:93]
	v_mfma_f32_16x16x32_bf16 v[78:81], v[196:199], v[180:183], v[78:81]
	v_mfma_f32_16x16x32_bf16 v[74:77], v[204:207], v[180:183], v[74:77]
	v_mfma_f32_16x16x32_bf16 v[70:73], v[196:199], v[188:191], v[70:73]
	v_mfma_f32_16x16x32_bf16 v[66:69], v[204:207], v[188:191], v[66:69]
	v_mfma_f32_16x16x32_bf16 v[110:113], v[200:203], v[168:171], v[110:113]
	s_waitcnt lgkmcnt(0)
	v_mfma_f32_16x16x32_bf16 v[106:109], v[216:219], v[168:171], v[106:109]
	v_mfma_f32_16x16x32_bf16 v[94:97], v[200:203], v[176:179], v[94:97]
	v_mfma_f32_16x16x32_bf16 v[90:93], v[216:219], v[176:179], v[90:93]
	v_mfma_f32_16x16x32_bf16 v[78:81], v[200:203], v[184:187], v[78:81]
	v_mfma_f32_16x16x32_bf16 v[74:77], v[216:219], v[184:187], v[74:77]
	v_mfma_f32_16x16x32_bf16 v[70:73], v[200:203], v[192:195], v[70:73]
	v_mfma_f32_16x16x32_bf16 v[66:69], v[216:219], v[192:195], v[66:69]
	s_mov_b32 m0, s52
	s_barrier
	ds_read_b128 v[164:167], v141 offset:49152
	ds_read_b128 v[168:171], v141 offset:50176
	ds_read_b128 v[172:175], v141 offset:51200
	ds_read_b128 v[176:179], v141 offset:52224
	ds_read_b128 v[180:183], v141 offset:53248
	ds_read_b128 v[184:187], v141 offset:54272
	ds_read_b128 v[188:191], v141 offset:55296
	global_load_lds_dwordx4 v134, s[98:99]
	s_mov_b32 m0, s53
	ds_read_b128 v[192:195], v141 offset:56320
	global_load_lds_dwordx4 v132, s[98:99]
	s_barrier
	s_waitcnt lgkmcnt(7)
	v_mfma_f32_16x16x32_bf16 v[62:65], v[142:145], v[164:167], v[62:65]
	v_mfma_f32_16x16x32_bf16 v[58:61], v[156:159], v[164:167], v[58:61]
	s_waitcnt lgkmcnt(5)
	v_mfma_f32_16x16x32_bf16 v[54:57], v[142:145], v[172:175], v[54:57]
	v_mfma_f32_16x16x32_bf16 v[50:53], v[156:159], v[172:175], v[50:53]
	s_waitcnt lgkmcnt(3)
	v_mfma_f32_16x16x32_bf16 v[38:41], v[142:145], v[180:183], v[38:41]
	v_mfma_f32_16x16x32_bf16 v[34:37], v[156:159], v[180:183], v[34:37]
	s_waitcnt lgkmcnt(1)
	v_mfma_f32_16x16x32_bf16 v[22:25], v[142:145], v[188:191], v[22:25]
	v_mfma_f32_16x16x32_bf16 v[18:21], v[156:159], v[188:191], v[18:21]
	v_mfma_f32_16x16x32_bf16 v[62:65], v[152:155], v[168:171], v[62:65]
	v_mfma_f32_16x16x32_bf16 v[58:61], v[160:163], v[168:171], v[58:61]
	v_mfma_f32_16x16x32_bf16 v[54:57], v[152:155], v[176:179], v[54:57]
	v_mfma_f32_16x16x32_bf16 v[50:53], v[160:163], v[176:179], v[50:53]
	v_mfma_f32_16x16x32_bf16 v[38:41], v[152:155], v[184:187], v[38:41]
	v_mfma_f32_16x16x32_bf16 v[34:37], v[160:163], v[184:187], v[34:37]
	s_waitcnt lgkmcnt(0)
	v_mfma_f32_16x16x32_bf16 v[22:25], v[152:155], v[192:195], v[22:25]
	v_mfma_f32_16x16x32_bf16 v[18:21], v[160:163], v[192:195], v[18:21]
	s_barrier
	s_add_i32 s38, s38, s40
	s_mov_b32 m0, s38
	s_add_u32 s36, s36, 0x80080
	s_addc_u32 s37, s37, 0
	global_load_lds_dwordx4 v0, s[36:37]
	s_add_i32 m0, s38, 0x2000
	s_nop 0
	global_load_lds_dwordx4 v130, s[36:37]
	s_waitcnt vmcnt(6)
	s_barrier
	v_mfma_f32_16x16x32_bf16 v[46:49], v[196:199], v[164:167], v[46:49]
	v_mfma_f32_16x16x32_bf16 v[42:45], v[204:207], v[164:167], v[42:45]
	v_mfma_f32_16x16x32_bf16 v[30:33], v[196:199], v[172:175], v[30:33]
	v_mfma_f32_16x16x32_bf16 v[26:29], v[204:207], v[172:175], v[26:29]
	v_mfma_f32_16x16x32_bf16 v[14:17], v[196:199], v[180:183], v[14:17]
	v_mfma_f32_16x16x32_bf16 v[10:13], v[204:207], v[180:183], v[10:13]
	v_mfma_f32_16x16x32_bf16 v[6:9], v[196:199], v[188:191], v[6:9]
	v_mfma_f32_16x16x32_bf16 v[2:5], v[204:207], v[188:191], v[2:5]
	v_mfma_f32_16x16x32_bf16 v[46:49], v[200:203], v[168:171], v[46:49]
	v_mfma_f32_16x16x32_bf16 v[42:45], v[216:219], v[168:171], v[42:45]
	v_mfma_f32_16x16x32_bf16 v[30:33], v[200:203], v[176:179], v[30:33]
	v_mfma_f32_16x16x32_bf16 v[26:29], v[216:219], v[176:179], v[26:29]
	v_mfma_f32_16x16x32_bf16 v[14:17], v[200:203], v[184:187], v[14:17]
	v_mfma_f32_16x16x32_bf16 v[10:13], v[216:219], v[184:187], v[10:13]
	v_mfma_f32_16x16x32_bf16 v[6:9], v[200:203], v[192:195], v[6:9]
	v_mfma_f32_16x16x32_bf16 v[2:5], v[216:219], v[192:195], v[2:5]
	s_add_i32 s68, s68, 2
	s_add_u32 s30, s30, 0x100
	s_addc_u32 s31, s31, 0
	s_add_u32 s43, s43, 0x100
	s_addc_u32 s67, s67, 0
	s_cmp_gt_u32 s68, 29
	s_barrier
	s_cbranch_scc0 .LBB0_939
	s_setprio 0
	s_lshr_b32 s23, s66, 3
	s_mulk_i32 s23, 0x880
	s_lshl_b32 s30, s66, 8
	v_mov_b32_e32 v142, v148
	s_and_b32 s30, s30, 0x700
	s_add_i32 s23, s60, s23
	s_add_i32 s23, s23, s30
	v_and_or_b32 v144, v142, 15, s23
	s_lshl_b32 s23, s65, 8
	v_lshrrev_b32_e32 v142, 1, v142
	v_and_or_b32 v142, v142, 24, s23
	v_or_b32_e32 v142, s51, v142
	v_cvt_pk_bf16_f32 v126, v126, v127
	v_cvt_pk_bf16_f32 v127, v128, v129
	v_cvt_pk_bf16_f32 v128, v122, v123
	v_mov_b64_e32 v[122:123], s[6:7]
	v_ashrrev_i32_e32 v143, 31, v142
	v_cvt_pk_bf16_f32 v70, v70, v71
	v_cvt_pk_bf16_f32 v71, v72, v73
	v_cvt_pk_bf16_f32 v72, v66, v67
	v_add_u32_e32 v66, 0x80, v144
	v_cvt_pk_bf16_f32 v129, v124, v125
	v_mad_i64_i32 v[124:125], s[30:31], v144, s74, v[122:123]
	v_lshlrev_b64 v[142:143], 1, v[142:143]
	v_cvt_pk_bf16_f32 v62, v62, v63
	v_cvt_pk_bf16_f32 v63, v64, v65
	v_cvt_pk_bf16_f32 v64, v58, v59
	v_mad_i64_i32 v[58:59], s[30:31], v66, s74, v[122:123]
	v_lshl_add_u64 v[124:125], v[124:125], 0, v[142:143]
	v_cvt_pk_bf16_f32 v110, v110, v111
	v_cvt_pk_bf16_f32 v111, v112, v113
	v_cvt_pk_bf16_f32 v112, v106, v107
	v_cvt_pk_bf16_f32 v113, v108, v109
	v_lshl_add_u64 v[58:59], v[58:59], 0, v[142:143]
	v_cvt_pk_bf16_f32 v46, v46, v47
	v_cvt_pk_bf16_f32 v47, v48, v49
	v_cvt_pk_bf16_f32 v48, v42, v43
	v_cvt_pk_bf16_f32 v49, v44, v45
	global_store_dwordx4 v[124:125], v[110:113], off offset:256
	global_store_dwordx4 v[58:59], v[46:49], off offset:256
	v_cvt_pk_bf16_f32 v94, v94, v95
	v_add_u32_e32 v110, 16, v144
	v_add_u32_e32 v46, 0x90, v144
	v_mad_i64_i32 v[110:111], s[30:31], v110, s74, v[122:123]
	v_mad_i64_i32 v[46:47], s[30:31], v46, s74, v[122:123]
	v_lshl_add_u64 v[110:111], v[110:111], 0, v[142:143]
	v_cvt_pk_bf16_f32 v95, v96, v97
	v_cvt_pk_bf16_f32 v96, v90, v91
	v_cvt_pk_bf16_f32 v97, v92, v93
	v_lshl_add_u64 v[46:47], v[46:47], 0, v[142:143]
	v_cvt_pk_bf16_f32 v30, v30, v31
	v_cvt_pk_bf16_f32 v31, v32, v33
	v_cvt_pk_bf16_f32 v32, v26, v27
	v_cvt_pk_bf16_f32 v33, v28, v29
	global_store_dwordx4 v[110:111], v[94:97], off offset:256
	global_store_dwordx4 v[46:47], v[30:33], off offset:256
	v_cvt_pk_bf16_f32 v78, v78, v79
	v_add_u32_e32 v94, 32, v144
	v_add_u32_e32 v30, 0xa0, v144
	v_mad_i64_i32 v[94:95], s[30:31], v94, s74, v[122:123]
	v_mad_i64_i32 v[30:31], s[30:31], v30, s74, v[122:123]
	v_lshl_add_u64 v[94:95], v[94:95], 0, v[142:143]
	v_cvt_pk_bf16_f32 v79, v80, v81
	v_cvt_pk_bf16_f32 v80, v74, v75
	v_cvt_pk_bf16_f32 v81, v76, v77
	v_lshl_add_u64 v[30:31], v[30:31], 0, v[142:143]
	v_cvt_pk_bf16_f32 v14, v14, v15
	v_cvt_pk_bf16_f32 v15, v16, v17
	v_cvt_pk_bf16_f32 v16, v10, v11
	v_cvt_pk_bf16_f32 v17, v12, v13
	global_store_dwordx4 v[94:95], v[78:81], off offset:256
	global_store_dwordx4 v[30:31], v[14:17], off offset:256
	v_cvt_pk_bf16_f32 v106, v118, v119
	v_add_u32_e32 v78, 48, v144
	v_add_u32_e32 v14, 0xb0, v144
	v_mad_i64_i32 v[78:79], s[30:31], v78, s74, v[122:123]
	v_mad_i64_i32 v[14:15], s[30:31], v14, s74, v[122:123]
	v_cvt_pk_bf16_f32 v107, v120, v121
	v_cvt_pk_bf16_f32 v108, v114, v115
	v_cvt_pk_bf16_f32 v109, v116, v117
	v_cvt_pk_bf16_f32 v90, v102, v103
	v_cvt_pk_bf16_f32 v91, v104, v105
	v_cvt_pk_bf16_f32 v92, v98, v99
	v_cvt_pk_bf16_f32 v93, v100, v101
	v_cvt_pk_bf16_f32 v74, v86, v87
	v_cvt_pk_bf16_f32 v75, v88, v89
	v_cvt_pk_bf16_f32 v76, v82, v83
	v_cvt_pk_bf16_f32 v77, v84, v85
	v_lshl_add_u64 v[78:79], v[78:79], 0, v[142:143]
	v_cvt_pk_bf16_f32 v73, v68, v69
	v_cvt_pk_bf16_f32 v65, v60, v61
	v_cvt_pk_bf16_f32 v42, v54, v55
	v_cvt_pk_bf16_f32 v43, v56, v57
	v_cvt_pk_bf16_f32 v44, v50, v51
	v_cvt_pk_bf16_f32 v45, v52, v53
	v_cvt_pk_bf16_f32 v26, v38, v39
	v_cvt_pk_bf16_f32 v27, v40, v41
	v_cvt_pk_bf16_f32 v28, v34, v35
	v_cvt_pk_bf16_f32 v29, v36, v37
	v_cvt_pk_bf16_f32 v10, v22, v23
	v_cvt_pk_bf16_f32 v11, v24, v25
	v_cvt_pk_bf16_f32 v12, v18, v19
	v_cvt_pk_bf16_f32 v13, v20, v21
	v_lshl_add_u64 v[14:15], v[14:15], 0, v[142:143]
	v_cvt_pk_bf16_f32 v6, v6, v7
	v_cvt_pk_bf16_f32 v7, v8, v9
	v_cvt_pk_bf16_f32 v8, v2, v3
	v_cvt_pk_bf16_f32 v9, v4, v5
	s_and_b64 vcc, exec, s[0:1]
	s_mov_b32 s65, s22
	s_mov_b32 s66, s64
	s_mov_b64 s[36:37], s[28:29]
	s_mov_b64 s[30:31], s[26:27]
	global_store_dwordx4 v[124:125], v[126:129], off
	global_store_dwordx4 v[110:111], v[106:109], off
	global_store_dwordx4 v[94:95], v[90:93], off
	global_store_dwordx4 v[78:79], v[74:77], off
	global_store_dwordx4 v[78:79], v[70:73], off offset:256
	global_store_dwordx4 v[58:59], v[62:65], off
	global_store_dwordx4 v[46:47], v[42:45], off
	global_store_dwordx4 v[30:31], v[26:29], off
	global_store_dwordx4 v[14:15], v[10:13], off
	global_store_dwordx4 v[14:15], v[6:9], off offset:256
	s_cbranch_vccz .LBB0_934
	s_waitcnt vmcnt(0)
	s_cmpk_gt_u32 s14, 0xff
	s_cbranch_scc1 .LBB0_943
	s_barrier

.LBB0_1083:
	s_add_u32 s42, s22, 0x100
	s_addc_u32 s43, s23, 0
	s_add_u32 s22, s6, 0x158080
	s_addc_u32 s23, s7, 0
	v_lshl_add_u64 v[142:143], s[22:23], 0, v[138:139]
	v_lshl_add_u64 v[144:145], s[22:23], 0, v[140:141]
	s_mov_b32 s78, -2
	s_mov_b64 s[22:23], 0
	v_add_u32_e32 v224, 0x10000, v146
	v_add_u32_e32 v225, 0x14000, v146
	v_add_u32_e32 v226, 0x18000, v146
	v_add_u32_e32 v227, 0x1c000, v146
	v_readfirstlane_b32 s32, v148
	s_nop 3
	s_cmp_ge_u32 s32, 0x100
	s_cbranch_scc0 .Lprio_skip_4
	s_setprio 1
.Lprio_skip_4:
.LBB0_1084:
	s_add_u32 s30, s6, s22
	s_addc_u32 s31, s7, s23
	s_add_u32 s30, s30, 0x100
	s_addc_u32 s31, s31, 0
	s_add_u32 s79, s42, s22
	s_addc_u32 s80, s43, s23
	s_add_i32 s81, 0, 0x10000
	ds_read_b128 v[152:155], v224
	ds_read_b128 v[156:159], v224 offset:1024
	ds_read_b128 v[160:163], v224 offset:2048
	ds_read_b128 v[164:167], v224 offset:3072
	s_cmpk_eq_i32 s22, 0x2a00
	s_cselect_b32 s41, s13, s31
	s_cselect_b32 s40, s12, s30
	s_cselect_b32 s31, s9, s80
	s_cselect_b32 s30, s8, s79
	v_lshl_add_u64 v[200:201], v[142:143], 0, s[22:23]
	s_add_i32 m0, s53, 0xc000
	ds_read_b128 v[168:171], v147
	ds_read_b128 v[172:175], v147 offset:1024
	ds_read_b128 v[176:179], v147 offset:2048
	ds_read_b128 v[180:183], v147 offset:3072
	ds_read_b128 v[184:187], v147 offset:4096
	ds_read_b128 v[188:191], v147 offset:5120
	ds_read_b128 v[192:195], v147 offset:6144
	ds_read_b128 v[196:199], v147 offset:7168
	global_load_lds_dwordx4 v[200:201], off
	v_lshl_add_u64 v[200:201], v[144:145], 0, s[22:23]
	s_add_i32 m0, s53, 0xe000
	s_nop 0
	global_load_lds_dwordx4 v[200:201], off
	s_waitcnt lgkmcnt(8)
	s_barrier
	s_waitcnt lgkmcnt(7)
	v_mfma_f32_16x16x32_bf16 v[126:129], v[152:155], v[168:171], v[126:129]
	v_mfma_f32_16x16x32_bf16 v[122:125], v[160:163], v[168:171], v[122:125]
	s_waitcnt lgkmcnt(5)
	v_mfma_f32_16x16x32_bf16 v[110:113], v[152:155], v[176:179], v[110:113]
	v_mfma_f32_16x16x32_bf16 v[106:109], v[160:163], v[176:179], v[106:109]
	s_waitcnt lgkmcnt(3)
	v_mfma_f32_16x16x32_bf16 v[94:97], v[152:155], v[184:187], v[94:97]
	v_mfma_f32_16x16x32_bf16 v[90:93], v[160:163], v[184:187], v[90:93]
	s_waitcnt lgkmcnt(1)
	v_mfma_f32_16x16x32_bf16 v[78:81], v[152:155], v[192:195], v[78:81]
	v_mfma_f32_16x16x32_bf16 v[74:77], v[160:163], v[192:195], v[74:77]
	v_mfma_f32_16x16x32_bf16 v[126:129], v[156:159], v[172:175], v[126:129]
	v_mfma_f32_16x16x32_bf16 v[122:125], v[164:167], v[172:175], v[122:125]
	v_mfma_f32_16x16x32_bf16 v[110:113], v[156:159], v[180:183], v[110:113]
	v_mfma_f32_16x16x32_bf16 v[106:109], v[164:167], v[180:183], v[106:109]
	v_mfma_f32_16x16x32_bf16 v[94:97], v[156:159], v[188:191], v[94:97]
	v_mfma_f32_16x16x32_bf16 v[90:93], v[164:167], v[188:191], v[90:93]
	s_waitcnt lgkmcnt(0)
	v_mfma_f32_16x16x32_bf16 v[78:81], v[156:159], v[196:199], v[78:81]
	v_mfma_f32_16x16x32_bf16 v[74:77], v[164:167], v[196:199], v[74:77]
	s_barrier
	s_add_i32 s79, 0, 0x14000
	s_add_i32 s80, s81, s52
	s_mov_b32 m0, s80
	ds_read_b128 v[200:203], v225
	ds_read_b128 v[204:207], v225 offset:1024
	ds_read_b128 v[216:219], v225 offset:2048
	global_load_lds_dwordx4 v0, s[30:31]
	s_add_i32 m0, s80, 0x2000
	ds_read_b128 v[220:223], v225 offset:3072
	global_load_lds_dwordx4 v136, s[30:31]
	s_barrier
	s_waitcnt lgkmcnt(3)
	v_mfma_f32_16x16x32_bf16 v[118:121], v[200:203], v[168:171], v[118:121]
	s_waitcnt lgkmcnt(1)
	v_mfma_f32_16x16x32_bf16 v[114:117], v[216:219], v[168:171], v[114:117]
	v_mfma_f32_16x16x32_bf16 v[102:105], v[200:203], v[176:179], v[102:105]
	v_mfma_f32_16x16x32_bf16 v[98:101], v[216:219], v[176:179], v[98:101]
	v_mfma_f32_16x16x32_bf16 v[86:89], v[200:203], v[184:187], v[86:89]
	v_mfma_f32_16x16x32_bf16 v[82:85], v[216:219], v[184:187], v[82:85]
	v_mfma_f32_16x16x32_bf16 v[70:73], v[200:203], v[192:195], v[70:73]
	v_mfma_f32_16x16x32_bf16 v[66:69], v[216:219], v[192:195], v[66:69]
	v_mfma_f32_16x16x32_bf16 v[118:121], v[204:207], v[172:175], v[118:121]
	s_waitcnt lgkmcnt(0)
	v_mfma_f32_16x16x32_bf16 v[114:117], v[220:223], v[172:175], v[114:117]
	v_mfma_f32_16x16x32_bf16 v[102:105], v[204:207], v[180:183], v[102:105]
	v_mfma_f32_16x16x32_bf16 v[98:101], v[220:223], v[180:183], v[98:101]
	v_mfma_f32_16x16x32_bf16 v[86:89], v[204:207], v[188:191], v[86:89]
	v_mfma_f32_16x16x32_bf16 v[82:85], v[220:223], v[188:191], v[82:85]
	v_mfma_f32_16x16x32_bf16 v[70:73], v[204:207], v[196:199], v[70:73]
	v_mfma_f32_16x16x32_bf16 v[66:69], v[220:223], v[196:199], v[66:69]
	s_mov_b32 m0, s53
	s_add_u32 s98, s40, 0x80
	s_addc_u32 s99, s41, 0
	s_barrier
	ds_read_b128 v[168:171], v147 offset:16384
	ds_read_b128 v[172:175], v147 offset:17408
	ds_read_b128 v[176:179], v147 offset:18432
	ds_read_b128 v[180:183], v147 offset:19456
	ds_read_b128 v[184:187], v147 offset:20480
	ds_read_b128 v[188:191], v147 offset:21504
	ds_read_b128 v[192:195], v147 offset:22528
	global_load_lds_dwordx4 v0, s[40:41]
	s_mov_b32 m0, s60
	ds_read_b128 v[196:199], v147 offset:23552
	global_load_lds_dwordx4 v136, s[40:41]
	s_barrier
	s_waitcnt lgkmcnt(7)
	v_mfma_f32_16x16x32_bf16 v[62:65], v[152:155], v[168:171], v[62:65]
	v_mfma_f32_16x16x32_bf16 v[58:61], v[160:163], v[168:171], v[58:61]
	s_waitcnt lgkmcnt(5)
	v_mfma_f32_16x16x32_bf16 v[46:49], v[152:155], v[176:179], v[46:49]
	v_mfma_f32_16x16x32_bf16 v[42:45], v[160:163], v[176:179], v[42:45]
	s_waitcnt lgkmcnt(3)
	v_mfma_f32_16x16x32_bf16 v[30:33], v[152:155], v[184:187], v[30:33]
	v_mfma_f32_16x16x32_bf16 v[26:29], v[160:163], v[184:187], v[26:29]
	s_waitcnt lgkmcnt(1)
	v_mfma_f32_16x16x32_bf16 v[14:17], v[152:155], v[192:195], v[14:17]
	v_mfma_f32_16x16x32_bf16 v[10:13], v[160:163], v[192:195], v[10:13]
	v_mfma_f32_16x16x32_bf16 v[62:65], v[156:159], v[172:175], v[62:65]
	v_mfma_f32_16x16x32_bf16 v[58:61], v[164:167], v[172:175], v[58:61]
	v_mfma_f32_16x16x32_bf16 v[46:49], v[156:159], v[180:183], v[46:49]
	v_mfma_f32_16x16x32_bf16 v[42:45], v[164:167], v[180:183], v[42:45]
	v_mfma_f32_16x16x32_bf16 v[30:33], v[156:159], v[188:191], v[30:33]
	v_mfma_f32_16x16x32_bf16 v[26:29], v[164:167], v[188:191], v[26:29]
	s_waitcnt lgkmcnt(0)
	v_mfma_f32_16x16x32_bf16 v[14:17], v[156:159], v[196:199], v[14:17]
	v_mfma_f32_16x16x32_bf16 v[10:13], v[164:167], v[196:199], v[10:13]
	s_barrier
	s_add_i32 s79, s79, s52
	s_mov_b32 m0, s79
	s_add_u32 s80, s30, 0x158000
	s_addc_u32 s81, s31, 0
	global_load_lds_dwordx4 v0, s[80:81]
	s_add_i32 m0, s79, 0x2000
	s_nop 0
	global_load_lds_dwordx4 v136, s[80:81]
	s_waitcnt vmcnt(6)
	s_barrier
	v_mfma_f32_16x16x32_bf16 v[54:57], v[200:203], v[168:171], v[54:57]
	v_mfma_f32_16x16x32_bf16 v[50:53], v[216:219], v[168:171], v[50:53]
	v_mfma_f32_16x16x32_bf16 v[38:41], v[200:203], v[176:179], v[38:41]
	v_mfma_f32_16x16x32_bf16 v[34:37], v[216:219], v[176:179], v[34:37]
	v_mfma_f32_16x16x32_bf16 v[22:25], v[200:203], v[184:187], v[22:25]
	v_mfma_f32_16x16x32_bf16 v[18:21], v[216:219], v[184:187], v[18:21]
	v_mfma_f32_16x16x32_bf16 v[6:9], v[200:203], v[192:195], v[6:9]
	v_mfma_f32_16x16x32_bf16 v[2:5], v[216:219], v[192:195], v[2:5]
	v_mfma_f32_16x16x32_bf16 v[54:57], v[204:207], v[172:175], v[54:57]
	v_mfma_f32_16x16x32_bf16 v[50:53], v[220:223], v[172:175], v[50:53]
	v_mfma_f32_16x16x32_bf16 v[38:41], v[204:207], v[180:183], v[38:41]
	v_mfma_f32_16x16x32_bf16 v[34:37], v[220:223], v[180:183], v[34:37]
	v_mfma_f32_16x16x32_bf16 v[22:25], v[204:207], v[188:191], v[22:25]
	v_mfma_f32_16x16x32_bf16 v[18:21], v[220:223], v[188:191], v[18:21]
	v_mfma_f32_16x16x32_bf16 v[6:9], v[204:207], v[196:199], v[6:9]
	v_mfma_f32_16x16x32_bf16 v[2:5], v[220:223], v[196:199], v[2:5]
	s_add_i32 s79, 0, 0x18000
	s_barrier
	ds_read_b128 v[152:155], v226
	ds_read_b128 v[156:159], v226 offset:1024
	ds_read_b128 v[160:163], v226 offset:2048
	ds_read_b128 v[164:167], v226 offset:3072
	s_add_u32 s40, s40, 0x158000
	s_addc_u32 s41, s41, 0
	s_mov_b32 m0, s65
	ds_read_b128 v[168:171], v147 offset:32768
	ds_read_b128 v[172:175], v147 offset:33792
	ds_read_b128 v[176:179], v147 offset:34816
	ds_read_b128 v[180:183], v147 offset:35840
	ds_read_b128 v[184:187], v147 offset:36864
	ds_read_b128 v[188:191], v147 offset:37888
	ds_read_b128 v[192:195], v147 offset:38912
	global_load_lds_dwordx4 v0, s[40:41]
	s_mov_b32 m0, s66
	ds_read_b128 v[196:199], v147 offset:39936
	global_load_lds_dwordx4 v136, s[40:41]
	s_waitcnt lgkmcnt(8)
	s_barrier
	s_waitcnt lgkmcnt(7)
	v_mfma_f32_16x16x32_bf16 v[126:129], v[152:155], v[168:171], v[126:129]
	v_mfma_f32_16x16x32_bf16 v[122:125], v[160:163], v[168:171], v[122:125]
	s_waitcnt lgkmcnt(5)
	v_mfma_f32_16x16x32_bf16 v[110:113], v[152:155], v[176:179], v[110:113]
	v_mfma_f32_16x16x32_bf16 v[106:109], v[160:163], v[176:179], v[106:109]
	s_waitcnt lgkmcnt(3)
	v_mfma_f32_16x16x32_bf16 v[94:97], v[152:155], v[184:187], v[94:97]
	v_mfma_f32_16x16x32_bf16 v[90:93], v[160:163], v[184:187], v[90:93]
	s_waitcnt lgkmcnt(1)
	v_mfma_f32_16x16x32_bf16 v[78:81], v[152:155], v[192:195], v[78:81]
	v_mfma_f32_16x16x32_bf16 v[74:77], v[160:163], v[192:195], v[74:77]
	v_mfma_f32_16x16x32_bf16 v[126:129], v[156:159], v[172:175], v[126:129]
	v_mfma_f32_16x16x32_bf16 v[122:125], v[164:167], v[172:175], v[122:125]
	v_mfma_f32_16x16x32_bf16 v[110:113], v[156:159], v[180:183], v[110:113]
	v_mfma_f32_16x16x32_bf16 v[106:109], v[164:167], v[180:183], v[106:109]
	v_mfma_f32_16x16x32_bf16 v[94:97], v[156:159], v[188:191], v[94:97]
	v_mfma_f32_16x16x32_bf16 v[90:93], v[164:167], v[188:191], v[90:93]
	s_waitcnt lgkmcnt(0)
	v_mfma_f32_16x16x32_bf16 v[78:81], v[156:159], v[196:199], v[78:81]
	v_mfma_f32_16x16x32_bf16 v[74:77], v[164:167], v[196:199], v[74:77]
	s_barrier
	s_add_i32 s40, 0, 0x1c000
	s_add_i32 s41, s79, s52
	s_add_u32 s100, s30, 0x80
	s_addc_u32 s101, s31, 0
	s_mov_b32 m0, s41
	ds_read_b128 v[200:203], v227
	ds_read_b128 v[204:207], v227 offset:1024
	ds_read_b128 v[216:219], v227 offset:2048
	global_load_lds_dwordx4 v0, s[100:101]
	s_add_i32 m0, s41, 0x2000
	ds_read_b128 v[220:223], v227 offset:3072
	global_load_lds_dwordx4 v136, s[100:101]
	s_barrier
	s_waitcnt lgkmcnt(3)
	v_mfma_f32_16x16x32_bf16 v[118:121], v[200:203], v[168:171], v[118:121]
	s_waitcnt lgkmcnt(1)
	v_mfma_f32_16x16x32_bf16 v[114:117], v[216:219], v[168:171], v[114:117]
	v_mfma_f32_16x16x32_bf16 v[102:105], v[200:203], v[176:179], v[102:105]
	v_mfma_f32_16x16x32_bf16 v[98:101], v[216:219], v[176:179], v[98:101]
	v_mfma_f32_16x16x32_bf16 v[86:89], v[200:203], v[184:187], v[86:89]
	v_mfma_f32_16x16x32_bf16 v[82:85], v[216:219], v[184:187], v[82:85]
	v_mfma_f32_16x16x32_bf16 v[70:73], v[200:203], v[192:195], v[70:73]
	v_mfma_f32_16x16x32_bf16 v[66:69], v[216:219], v[192:195], v[66:69]
	v_mfma_f32_16x16x32_bf16 v[118:121], v[204:207], v[172:175], v[118:121]
	s_waitcnt lgkmcnt(0)
	v_mfma_f32_16x16x32_bf16 v[114:117], v[220:223], v[172:175], v[114:117]
	v_mfma_f32_16x16x32_bf16 v[102:105], v[204:207], v[180:183], v[102:105]
	v_mfma_f32_16x16x32_bf16 v[98:101], v[220:223], v[180:183], v[98:101]
	v_mfma_f32_16x16x32_bf16 v[86:89], v[204:207], v[188:191], v[86:89]
	v_mfma_f32_16x16x32_bf16 v[82:85], v[220:223], v[188:191], v[82:85]
	v_mfma_f32_16x16x32_bf16 v[70:73], v[204:207], v[196:199], v[70:73]
	v_mfma_f32_16x16x32_bf16 v[66:69], v[220:223], v[196:199], v[66:69]
	s_mov_b32 m0, s67
	s_barrier
	ds_read_b128 v[168:171], v147 offset:49152
	ds_read_b128 v[172:175], v147 offset:50176
	ds_read_b128 v[176:179], v147 offset:51200
	ds_read_b128 v[180:183], v147 offset:52224
	ds_read_b128 v[184:187], v147 offset:53248
	ds_read_b128 v[188:191], v147 offset:54272
	ds_read_b128 v[192:195], v147 offset:55296
	global_load_lds_dwordx4 v0, s[98:99]
	s_mov_b32 m0, s68
	ds_read_b128 v[196:199], v147 offset:56320
	global_load_lds_dwordx4 v136, s[98:99]
	s_barrier
	s_waitcnt lgkmcnt(7)
	v_mfma_f32_16x16x32_bf16 v[62:65], v[152:155], v[168:171], v[62:65]
	v_mfma_f32_16x16x32_bf16 v[58:61], v[160:163], v[168:171], v[58:61]
	s_waitcnt lgkmcnt(5)
	v_mfma_f32_16x16x32_bf16 v[46:49], v[152:155], v[176:179], v[46:49]
	v_mfma_f32_16x16x32_bf16 v[42:45], v[160:163], v[176:179], v[42:45]
	s_waitcnt lgkmcnt(3)
	v_mfma_f32_16x16x32_bf16 v[30:33], v[152:155], v[184:187], v[30:33]
	v_mfma_f32_16x16x32_bf16 v[26:29], v[160:163], v[184:187], v[26:29]
	s_waitcnt lgkmcnt(1)
	v_mfma_f32_16x16x32_bf16 v[14:17], v[152:155], v[192:195], v[14:17]
	v_mfma_f32_16x16x32_bf16 v[10:13], v[160:163], v[192:195], v[10:13]
	v_mfma_f32_16x16x32_bf16 v[62:65], v[156:159], v[172:175], v[62:65]
	v_mfma_f32_16x16x32_bf16 v[58:61], v[164:167], v[172:175], v[58:61]
	v_mfma_f32_16x16x32_bf16 v[46:49], v[156:159], v[180:183], v[46:49]
	v_mfma_f32_16x16x32_bf16 v[42:45], v[164:167], v[180:183], v[42:45]
	v_mfma_f32_16x16x32_bf16 v[30:33], v[156:159], v[188:191], v[30:33]
	v_mfma_f32_16x16x32_bf16 v[26:29], v[164:167], v[188:191], v[26:29]
	s_waitcnt lgkmcnt(0)
	v_mfma_f32_16x16x32_bf16 v[14:17], v[156:159], v[196:199], v[14:17]
	v_mfma_f32_16x16x32_bf16 v[10:13], v[164:167], v[196:199], v[10:13]
	s_barrier
	s_add_i32 s40, s40, s52
	s_mov_b32 m0, s40
	s_add_u32 s30, s30, 0x158080
	s_addc_u32 s31, s31, 0
	global_load_lds_dwordx4 v0, s[30:31]
	s_add_i32 m0, s40, 0x2000
	s_nop 0
	global_load_lds_dwordx4 v136, s[30:31]
	s_waitcnt vmcnt(6)
	s_barrier
	v_mfma_f32_16x16x32_bf16 v[54:57], v[200:203], v[168:171], v[54:57]
	v_mfma_f32_16x16x32_bf16 v[50:53], v[216:219], v[168:171], v[50:53]
	v_mfma_f32_16x16x32_bf16 v[38:41], v[200:203], v[176:179], v[38:41]
	v_mfma_f32_16x16x32_bf16 v[34:37], v[216:219], v[176:179], v[34:37]
	v_mfma_f32_16x16x32_bf16 v[22:25], v[200:203], v[184:187], v[22:25]
	v_mfma_f32_16x16x32_bf16 v[18:21], v[216:219], v[184:187], v[18:21]
	v_mfma_f32_16x16x32_bf16 v[6:9], v[200:203], v[192:195], v[6:9]
	v_mfma_f32_16x16x32_bf16 v[2:5], v[216:219], v[192:195], v[2:5]
	v_mfma_f32_16x16x32_bf16 v[54:57], v[204:207], v[172:175], v[54:57]
	v_mfma_f32_16x16x32_bf16 v[50:53], v[220:223], v[172:175], v[50:53]
	v_mfma_f32_16x16x32_bf16 v[38:41], v[204:207], v[180:183], v[38:41]
	v_mfma_f32_16x16x32_bf16 v[34:37], v[220:223], v[180:183], v[34:37]
	v_mfma_f32_16x16x32_bf16 v[22:25], v[204:207], v[188:191], v[22:25]
	v_mfma_f32_16x16x32_bf16 v[18:21], v[220:223], v[188:191], v[18:21]
	v_mfma_f32_16x16x32_bf16 v[6:9], v[204:207], v[196:199], v[6:9]
	v_mfma_f32_16x16x32_bf16 v[2:5], v[220:223], v[196:199], v[2:5]
	s_add_i32 s78, s78, 2
	s_add_u32 s22, s22, 0x100
	s_addc_u32 s23, s23, 0
	s_cmpk_gt_u32 s78, 0x53
	s_barrier
	s_cbranch_scc0 .LBB0_1084
	s_setprio 0
	s_add_u32 s22, s42, 0xffffff00
	s_addc_u32 s23, s43, -1
	s_and_b64 vcc, exec, s[38:39]
	s_cbranch_vccnz .LBB0_1071
	v_mov_b32_e32 v2, 0
	s_mov_b32 s14, s75
	s_mov_b32 s50, s76
	s_mov_b64 s[6:7], s[12:13]
	s_mov_b32 s69, s77
	v_mov_b32_e32 v3, v2
	v_mov_b32_e32 v4, v2
	v_mov_b32_e32 v5, v2
	v_mov_b32_e32 v6, v2
	v_mov_b32_e32 v7, v2
	v_mov_b32_e32 v8, v2
	v_mov_b32_e32 v9, v2
	v_mov_b32_e32 v18, v2
	v_mov_b32_e32 v19, v2
	v_mov_b32_e32 v20, v2
	v_mov_b32_e32 v21, v2
	v_mov_b32_e32 v22, v2
	v_mov_b32_e32 v23, v2
	v_mov_b32_e32 v24, v2
	v_mov_b32_e32 v25, v2
	v_mov_b32_e32 v34, v2
	v_mov_b32_e32 v35, v2
	v_mov_b32_e32 v36, v2
	v_mov_b32_e32 v37, v2
	v_mov_b32_e32 v38, v2
	v_mov_b32_e32 v39, v2
	v_mov_b32_e32 v40, v2
	v_mov_b32_e32 v41, v2
	v_mov_b32_e32 v50, v2
	v_mov_b32_e32 v51, v2
	v_mov_b32_e32 v52, v2
	v_mov_b32_e32 v53, v2
	v_mov_b32_e32 v54, v2
	v_mov_b32_e32 v55, v2
	v_mov_b32_e32 v56, v2
	v_mov_b32_e32 v57, v2
	v_mov_b32_e32 v10, v2
	v_mov_b32_e32 v11, v2
	v_mov_b32_e32 v12, v2
	v_mov_b32_e32 v13, v2
	v_mov_b32_e32 v14, v2
	v_mov_b32_e32 v15, v2
	v_mov_b32_e32 v16, v2
	v_mov_b32_e32 v17, v2
	v_mov_b32_e32 v26, v2
	v_mov_b32_e32 v27, v2
	v_mov_b32_e32 v28, v2
	v_mov_b32_e32 v29, v2
	v_mov_b32_e32 v30, v2
	v_mov_b32_e32 v31, v2
	v_mov_b32_e32 v32, v2
	v_mov_b32_e32 v33, v2
	v_mov_b32_e32 v42, v2
	v_mov_b32_e32 v43, v2
	v_mov_b32_e32 v44, v2
	v_mov_b32_e32 v45, v2
	v_mov_b32_e32 v46, v2
	v_mov_b32_e32 v47, v2
	v_mov_b32_e32 v48, v2
	v_mov_b32_e32 v49, v2
	v_mov_b32_e32 v58, v2
	v_mov_b32_e32 v59, v2
	v_mov_b32_e32 v60, v2
	v_mov_b32_e32 v61, v2
	v_mov_b32_e32 v62, v2
	v_mov_b32_e32 v63, v2
	v_mov_b32_e32 v64, v2
	v_mov_b32_e32 v65, v2
	v_mov_b32_e32 v66, v2
	v_mov_b32_e32 v67, v2
	v_mov_b32_e32 v68, v2
	v_mov_b32_e32 v69, v2
	v_mov_b32_e32 v70, v2
	v_mov_b32_e32 v71, v2
	v_mov_b32_e32 v72, v2
	v_mov_b32_e32 v73, v2
	v_mov_b32_e32 v82, v2
	v_mov_b32_e32 v83, v2
	v_mov_b32_e32 v84, v2
	v_mov_b32_e32 v85, v2
	v_mov_b32_e32 v86, v2
	v_mov_b32_e32 v87, v2
	v_mov_b32_e32 v88, v2
	v_mov_b32_e32 v89, v2
	v_mov_b32_e32 v98, v2
	v_mov_b32_e32 v99, v2
	v_mov_b32_e32 v100, v2
	v_mov_b32_e32 v101, v2
	v_mov_b32_e32 v102, v2
	v_mov_b32_e32 v103, v2
	v_mov_b32_e32 v104, v2
	v_mov_b32_e32 v105, v2
	v_mov_b32_e32 v114, v2
	v_mov_b32_e32 v115, v2
	v_mov_b32_e32 v116, v2
	v_mov_b32_e32 v117, v2
	v_mov_b32_e32 v118, v2
	v_mov_b32_e32 v119, v2
	v_mov_b32_e32 v120, v2
	v_mov_b32_e32 v121, v2
	v_mov_b32_e32 v74, v2
	v_mov_b32_e32 v75, v2
	v_mov_b32_e32 v76, v2
	v_mov_b32_e32 v77, v2
	v_mov_b32_e32 v78, v2
	v_mov_b32_e32 v79, v2
	v_mov_b32_e32 v80, v2
	v_mov_b32_e32 v81, v2
	v_mov_b32_e32 v90, v2
	v_mov_b32_e32 v91, v2
	v_mov_b32_e32 v92, v2
	v_mov_b32_e32 v93, v2
	v_mov_b32_e32 v94, v2
	v_mov_b32_e32 v95, v2
	v_mov_b32_e32 v96, v2
	v_mov_b32_e32 v97, v2
	v_mov_b32_e32 v106, v2
	v_mov_b32_e32 v107, v2
	v_mov_b32_e32 v108, v2
	v_mov_b32_e32 v109, v2
	v_mov_b32_e32 v110, v2
	v_mov_b32_e32 v111, v2
	v_mov_b32_e32 v112, v2
	v_mov_b32_e32 v113, v2
	v_mov_b32_e32 v122, v2
	v_mov_b32_e32 v123, v2
	v_mov_b32_e32 v124, v2
	v_mov_b32_e32 v125, v2
	v_mov_b32_e32 v126, v2
	v_mov_b32_e32 v127, v2
	v_mov_b32_e32 v128, v2
	v_mov_b32_e32 v129, v2
	s_andn2_b64 vcc, exec, s[0:1]
	s_cbranch_vccnz .LBB0_1072
